# row_scale_loads_hoisted_to_tile_top_no_vmcnt0_in_epilogue
# speedup vs baseline: 1.0097x; 1.0024x over previous
.LBB0_711:
	s_ashr_i32 s21, s20, 31
	v_cmp_lt_i64_e32 vcc, s[22:23], v[140:141]
	s_lshl_b64 s[22:23], s[20:21], 19
	s_add_u32 s22, s10, s22
	s_addc_u32 s23, s11, s23
	s_and_b64 s[24:25], vcc, exec
	s_cselect_b32 s21, s23, s3
	s_cselect_b32 s52, s22, s2
	s_ashr_i32 s19, s18, 31
	s_lshl_b64 s[24:25], s[18:19], 19
	v_readlane_b32 s19, v253, 49
	s_add_u32 s24, s19, s24
	v_readlane_b32 s19, v253, 50
	s_addc_u32 s25, s19, s25
	s_and_b64 s[28:29], vcc, exec
	s_cselect_b32 s19, s25, s27
	s_cselect_b32 s53, s24, s26
	s_add_u32 s2, s2, 0x40080
	s_addc_u32 s3, s3, 0
	s_add_u32 s54, s26, 0x100
	v_lshl_add_u32 v240, s0, 8, v148
	v_ashrrev_i32_e32 v241, 31, v240
	v_lshl_add_u64 v[240:241], v[240:241], 2, s[66:67]
	global_load_dword v242, v[240:241], off
	global_load_dword v243, v[240:241], off offset:64
	global_load_dword v244, v[240:241], off offset:128
	global_load_dword v245, v[240:241], off offset:192
	global_load_dword v246, v[240:241], off offset:512
	global_load_dword v247, v[240:241], off offset:576
	global_load_dword v248, v[240:241], off offset:640
	global_load_dword v249, v[240:241], off offset:704
	v_mov_b32_e32 v0, 0
	s_addc_u32 s55, s27, 0
	s_mov_b32 s56, -2
	v_mov_b32_e32 v1, v0
	v_mov_b64_e32 v[2:3], v[0:1]
	v_mov_b64_e32 v[4:5], v[0:1]
	v_mov_b64_e32 v[6:7], v[0:1]
	v_mov_b64_e32 v[8:9], v[0:1]
	v_mov_b64_e32 v[10:11], v[0:1]
	v_mov_b64_e32 v[12:13], v[0:1]
	v_mov_b64_e32 v[14:15], v[0:1]
	v_mov_b64_e32 v[16:17], v[0:1]
	v_mov_b64_e32 v[18:19], v[0:1]
	v_mov_b64_e32 v[20:21], v[0:1]
	v_mov_b64_e32 v[22:23], v[0:1]
	v_mov_b64_e32 v[24:25], v[0:1]
	v_mov_b64_e32 v[26:27], v[0:1]
	v_mov_b64_e32 v[28:29], v[0:1]
	v_mov_b64_e32 v[30:31], v[0:1]
	v_mov_b64_e32 v[32:33], v[0:1]
	v_mov_b64_e32 v[34:35], v[0:1]
	v_mov_b64_e32 v[36:37], v[0:1]
	v_mov_b64_e32 v[38:39], v[0:1]
	v_mov_b64_e32 v[40:41], v[0:1]
	v_mov_b64_e32 v[42:43], v[0:1]
	v_mov_b64_e32 v[44:45], v[0:1]
	v_mov_b64_e32 v[46:47], v[0:1]
	v_mov_b64_e32 v[48:49], v[0:1]
	v_mov_b64_e32 v[50:51], v[0:1]
	v_mov_b64_e32 v[52:53], v[0:1]
	v_mov_b64_e32 v[54:55], v[0:1]
	v_mov_b64_e32 v[56:57], v[0:1]
	v_mov_b64_e32 v[58:59], v[0:1]
	v_mov_b64_e32 v[60:61], v[0:1]
	v_mov_b64_e32 v[62:63], v[0:1]
	v_mov_b64_e32 v[64:65], v[0:1]
	v_mov_b64_e32 v[66:67], v[0:1]
	v_mov_b64_e32 v[68:69], v[0:1]
	v_mov_b64_e32 v[70:71], v[0:1]
	v_mov_b64_e32 v[72:73], v[0:1]
	v_mov_b64_e32 v[74:75], v[0:1]
	v_mov_b64_e32 v[76:77], v[0:1]
	v_mov_b64_e32 v[78:79], v[0:1]
	v_mov_b64_e32 v[80:81], v[0:1]
	v_mov_b64_e32 v[82:83], v[0:1]
	v_mov_b64_e32 v[84:85], v[0:1]
	v_mov_b64_e32 v[86:87], v[0:1]
	v_mov_b64_e32 v[88:89], v[0:1]
	v_mov_b64_e32 v[90:91], v[0:1]
	v_mov_b64_e32 v[92:93], v[0:1]
	v_mov_b64_e32 v[94:95], v[0:1]
	v_mov_b64_e32 v[96:97], v[0:1]
	v_mov_b64_e32 v[98:99], v[0:1]
	v_mov_b64_e32 v[100:101], v[0:1]
	v_mov_b64_e32 v[102:103], v[0:1]
	v_mov_b64_e32 v[104:105], v[0:1]
	v_mov_b64_e32 v[106:107], v[0:1]
	v_mov_b64_e32 v[108:109], v[0:1]
	v_mov_b64_e32 v[110:111], v[0:1]
	v_mov_b64_e32 v[112:113], v[0:1]
	v_mov_b64_e32 v[114:115], v[0:1]
	v_mov_b64_e32 v[116:117], v[0:1]
	v_mov_b64_e32 v[118:119], v[0:1]
	v_mov_b64_e32 v[120:121], v[0:1]
	v_mov_b64_e32 v[122:123], v[0:1]
	v_mov_b64_e32 v[124:125], v[0:1]
	v_mov_b64_e32 v[126:127], v[0:1]
.LBB0_712:
	ds_read_b128 v[144:147], v151
	ds_read_b128 v[156:159], v151 offset:1024
	ds_read_b128 v[160:163], v151 offset:2048
	ds_read_b128 v[164:167], v151 offset:3072
	s_add_u32 s26, s2, 0xfffc0080
	s_addc_u32 s27, s3, -1
	s_cmp_eq_u32 s56, 12
	s_cselect_b32 s29, s21, s27
	s_cselect_b32 s28, s52, s26
	s_cselect_b32 s27, s19, s55
	s_cselect_b32 s26, s53, s54
	v_lshl_add_u64 v[172:173], s[2:3], 0, v[136:137]
	s_add_i32 m0, s34, 0xc000
	ds_read_b128 v[168:171], v152
	ds_read_b128 v[176:179], v152 offset:1024
	ds_read_b128 v[180:183], v152 offset:2048
	ds_read_b128 v[184:187], v152 offset:3072
	ds_read_b128 v[188:191], v152 offset:4096
	ds_read_b128 v[192:195], v152 offset:5120
	ds_read_b128 v[196:199], v152 offset:6144
	ds_read_b128 v[200:203], v152 offset:7168
	global_load_lds_dwordx4 v[172:173], off
	s_add_i32 m0, s34, 0xe000
	v_lshl_add_u64 v[172:173], s[2:3], 0, v[138:139]
	global_load_lds_dwordx4 v[172:173], off
	s_waitcnt lgkmcnt(8)
	s_setprio 1
	s_barrier
	s_waitcnt lgkmcnt(0)
	v_mfma_f32_16x16x32_bf16 v[124:127], v[144:147], v[168:171], v[124:127]
	v_mfma_f32_16x16x32_bf16 v[120:123], v[160:163], v[168:171], v[120:123]
	v_mfma_f32_16x16x32_bf16 v[116:119], v[144:147], v[180:183], v[116:119]
	v_mfma_f32_16x16x32_bf16 v[112:115], v[160:163], v[180:183], v[112:115]
	v_mfma_f32_16x16x32_bf16 v[104:107], v[144:147], v[188:191], v[104:107]
	v_mfma_f32_16x16x32_bf16 v[96:99], v[160:163], v[188:191], v[96:99]
	v_mfma_f32_16x16x32_bf16 v[76:79], v[144:147], v[196:199], v[76:79]
	v_mfma_f32_16x16x32_bf16 v[72:75], v[160:163], v[196:199], v[72:75]
	v_mfma_f32_16x16x32_bf16 v[124:127], v[156:159], v[176:179], v[124:127]
	v_mfma_f32_16x16x32_bf16 v[120:123], v[164:167], v[176:179], v[120:123]
	v_mfma_f32_16x16x32_bf16 v[116:119], v[156:159], v[184:187], v[116:119]
	v_mfma_f32_16x16x32_bf16 v[112:115], v[164:167], v[184:187], v[112:115]
	v_mfma_f32_16x16x32_bf16 v[104:107], v[156:159], v[192:195], v[104:107]
	v_mfma_f32_16x16x32_bf16 v[96:99], v[164:167], v[192:195], v[96:99]
	v_mfma_f32_16x16x32_bf16 v[76:79], v[156:159], v[200:203], v[76:79]
	v_mfma_f32_16x16x32_bf16 v[72:75], v[164:167], v[200:203], v[72:75]
	s_barrier
	s_setprio 0
	s_add_i32 s57, s43, s33
	v_lshl_add_u64 v[172:173], s[26:27], 0, v[130:131]
	s_mov_b32 m0, s57
	ds_read_b128 v[204:207], v153
	ds_read_b128 v[212:215], v153 offset:1024
	ds_read_b128 v[216:219], v153 offset:2048
	ds_read_b128 v[220:223], v153 offset:3072
	global_load_lds_dwordx4 v[172:173], off
	s_add_i32 m0, s57, 0x2000
	v_lshl_add_u64 v[208:209], s[26:27], 0, v[134:135]
	global_load_lds_dwordx4 v[208:209], off
	s_setprio 1
	s_barrier
	s_waitcnt lgkmcnt(0)
	v_mfma_f32_16x16x32_bf16 v[108:111], v[204:207], v[168:171], v[108:111]
	v_mfma_f32_16x16x32_bf16 v[100:103], v[216:219], v[168:171], v[100:103]
	v_mfma_f32_16x16x32_bf16 v[92:95], v[204:207], v[180:183], v[92:95]
	v_mfma_f32_16x16x32_bf16 v[88:91], v[216:219], v[180:183], v[88:91]
	v_mfma_f32_16x16x32_bf16 v[84:87], v[204:207], v[188:191], v[84:87]
	v_mfma_f32_16x16x32_bf16 v[80:83], v[216:219], v[188:191], v[80:83]
	v_mfma_f32_16x16x32_bf16 v[68:71], v[204:207], v[196:199], v[68:71]
	v_mfma_f32_16x16x32_bf16 v[64:67], v[216:219], v[196:199], v[64:67]
	v_mfma_f32_16x16x32_bf16 v[108:111], v[212:215], v[176:179], v[108:111]
	v_mfma_f32_16x16x32_bf16 v[100:103], v[220:223], v[176:179], v[100:103]
	v_mfma_f32_16x16x32_bf16 v[92:95], v[212:215], v[184:187], v[92:95]
	v_mfma_f32_16x16x32_bf16 v[88:91], v[220:223], v[184:187], v[88:91]
	v_mfma_f32_16x16x32_bf16 v[84:87], v[212:215], v[192:195], v[84:87]
	v_mfma_f32_16x16x32_bf16 v[80:83], v[220:223], v[192:195], v[80:83]
	v_mfma_f32_16x16x32_bf16 v[68:71], v[212:215], v[200:203], v[68:71]
	v_mfma_f32_16x16x32_bf16 v[64:67], v[220:223], v[200:203], v[64:67]
	s_barrier
	s_setprio 0
	s_mov_b32 m0, s34
	v_lshl_add_u64 v[224:225], s[28:29], 0, v[128:129]
	ds_read_b128 v[168:171], v152 offset:16384
	ds_read_b128 v[176:179], v152 offset:17408
	ds_read_b128 v[180:183], v152 offset:18432
	ds_read_b128 v[184:187], v152 offset:19456
	ds_read_b128 v[188:191], v152 offset:20480
	ds_read_b128 v[192:195], v152 offset:21504
	ds_read_b128 v[196:199], v152 offset:22528
	ds_read_b128 v[200:203], v152 offset:23552
	global_load_lds_dwordx4 v[224:225], off
	s_mov_b32 m0, s35
	v_lshl_add_u64 v[226:227], s[28:29], 0, v[132:133]
	global_load_lds_dwordx4 v[226:227], off
	s_setprio 1
	s_barrier
	s_waitcnt lgkmcnt(0)
	v_mfma_f32_16x16x32_bf16 v[60:63], v[144:147], v[168:171], v[60:63]
	v_mfma_f32_16x16x32_bf16 v[56:59], v[160:163], v[168:171], v[56:59]
	v_mfma_f32_16x16x32_bf16 v[44:47], v[144:147], v[180:183], v[44:47]
	v_mfma_f32_16x16x32_bf16 v[40:43], v[160:163], v[180:183], v[40:43]
	v_mfma_f32_16x16x32_bf16 v[28:31], v[144:147], v[188:191], v[28:31]
	v_mfma_f32_16x16x32_bf16 v[24:27], v[160:163], v[188:191], v[24:27]
	v_mfma_f32_16x16x32_bf16 v[12:15], v[144:147], v[196:199], v[12:15]
	v_mfma_f32_16x16x32_bf16 v[8:11], v[160:163], v[196:199], v[8:11]
	v_mfma_f32_16x16x32_bf16 v[60:63], v[156:159], v[176:179], v[60:63]
	v_mfma_f32_16x16x32_bf16 v[56:59], v[164:167], v[176:179], v[56:59]
	v_mfma_f32_16x16x32_bf16 v[44:47], v[156:159], v[184:187], v[44:47]
	v_mfma_f32_16x16x32_bf16 v[40:43], v[164:167], v[184:187], v[40:43]
	v_mfma_f32_16x16x32_bf16 v[28:31], v[156:159], v[192:195], v[28:31]
	v_mfma_f32_16x16x32_bf16 v[24:27], v[164:167], v[192:195], v[24:27]
	v_mfma_f32_16x16x32_bf16 v[12:15], v[156:159], v[200:203], v[12:15]
	v_mfma_f32_16x16x32_bf16 v[8:11], v[164:167], v[200:203], v[8:11]
	s_barrier
	s_setprio 0
	s_add_u32 s58, s26, 0x40000
	s_addc_u32 s59, s27, 0
	s_add_i32 s57, s48, s33
	s_mov_b32 m0, s57
	v_lshl_add_u64 v[144:145], s[58:59], 0, v[130:131]
	global_load_lds_dwordx4 v[144:145], off
	s_add_i32 m0, s57, 0x2000
	v_lshl_add_u64 v[144:145], s[58:59], 0, v[134:135]
	global_load_lds_dwordx4 v[144:145], off
	s_waitcnt vmcnt(6)
	s_setprio 1
	s_barrier
	v_mfma_f32_16x16x32_bf16 v[52:55], v[204:207], v[168:171], v[52:55]
	v_mfma_f32_16x16x32_bf16 v[48:51], v[216:219], v[168:171], v[48:51]
	v_mfma_f32_16x16x32_bf16 v[36:39], v[204:207], v[180:183], v[36:39]
	v_mfma_f32_16x16x32_bf16 v[32:35], v[216:219], v[180:183], v[32:35]
	v_mfma_f32_16x16x32_bf16 v[20:23], v[204:207], v[188:191], v[20:23]
	v_mfma_f32_16x16x32_bf16 v[16:19], v[216:219], v[188:191], v[16:19]
	v_mfma_f32_16x16x32_bf16 v[4:7], v[204:207], v[196:199], v[4:7]
	v_mfma_f32_16x16x32_bf16 v[0:3], v[216:219], v[196:199], v[0:3]
	v_mfma_f32_16x16x32_bf16 v[52:55], v[212:215], v[176:179], v[52:55]
	v_mfma_f32_16x16x32_bf16 v[48:51], v[220:223], v[176:179], v[48:51]
	v_mfma_f32_16x16x32_bf16 v[36:39], v[212:215], v[184:187], v[36:39]
	v_mfma_f32_16x16x32_bf16 v[32:35], v[220:223], v[184:187], v[32:35]
	v_mfma_f32_16x16x32_bf16 v[20:23], v[212:215], v[192:195], v[20:23]
	v_mfma_f32_16x16x32_bf16 v[16:19], v[220:223], v[192:195], v[16:19]
	v_mfma_f32_16x16x32_bf16 v[4:7], v[212:215], v[200:203], v[4:7]
	v_mfma_f32_16x16x32_bf16 v[0:3], v[220:223], v[200:203], v[0:3]
	s_barrier
	s_setprio 0
	s_add_i32 s57, 0, 0x18000
	v_add_u32_e32 v155, s57, v149
	ds_read_b128 v[144:147], v155
	ds_read_b128 v[156:159], v155 offset:1024
	ds_read_b128 v[160:163], v155 offset:2048
	ds_read_b128 v[164:167], v155 offset:3072
	s_add_u32 s28, s28, 0x40000
	s_addc_u32 s29, s29, 0
	s_mov_b32 m0, s36
	v_lshl_add_u64 v[204:205], s[28:29], 0, v[128:129]
	ds_read_b128 v[168:171], v152 offset:32768
	ds_read_b128 v[176:179], v152 offset:33792
	ds_read_b128 v[180:183], v152 offset:34816
	ds_read_b128 v[184:187], v152 offset:35840
	ds_read_b128 v[188:191], v152 offset:36864
	ds_read_b128 v[192:195], v152 offset:37888
	ds_read_b128 v[196:199], v152 offset:38912
	ds_read_b128 v[200:203], v152 offset:39936
	global_load_lds_dwordx4 v[204:205], off
	s_mov_b32 m0, s37
	v_lshl_add_u64 v[204:205], s[28:29], 0, v[132:133]
	global_load_lds_dwordx4 v[204:205], off
	s_waitcnt lgkmcnt(8)
	s_setprio 1
	s_barrier
	s_waitcnt lgkmcnt(0)
	v_mfma_f32_16x16x32_bf16 v[124:127], v[144:147], v[168:171], v[124:127]
	v_mfma_f32_16x16x32_bf16 v[120:123], v[160:163], v[168:171], v[120:123]
	v_mfma_f32_16x16x32_bf16 v[116:119], v[144:147], v[180:183], v[116:119]
	v_mfma_f32_16x16x32_bf16 v[112:115], v[160:163], v[180:183], v[112:115]
	v_mfma_f32_16x16x32_bf16 v[104:107], v[144:147], v[188:191], v[104:107]
	v_mfma_f32_16x16x32_bf16 v[96:99], v[160:163], v[188:191], v[96:99]
	v_mfma_f32_16x16x32_bf16 v[76:79], v[144:147], v[196:199], v[76:79]
	v_mfma_f32_16x16x32_bf16 v[72:75], v[160:163], v[196:199], v[72:75]
	v_mfma_f32_16x16x32_bf16 v[124:127], v[156:159], v[176:179], v[124:127]
	v_mfma_f32_16x16x32_bf16 v[120:123], v[164:167], v[176:179], v[120:123]
	v_mfma_f32_16x16x32_bf16 v[116:119], v[156:159], v[184:187], v[116:119]
	v_mfma_f32_16x16x32_bf16 v[112:115], v[164:167], v[184:187], v[112:115]
	v_mfma_f32_16x16x32_bf16 v[104:107], v[156:159], v[192:195], v[104:107]
	v_mfma_f32_16x16x32_bf16 v[96:99], v[164:167], v[192:195], v[96:99]
	v_mfma_f32_16x16x32_bf16 v[76:79], v[156:159], v[200:203], v[76:79]
	v_mfma_f32_16x16x32_bf16 v[72:75], v[164:167], v[200:203], v[72:75]
	s_barrier
	s_setprio 0
	s_add_i32 s28, 0, 0x1c000
	s_add_i32 s29, s57, s33
	v_add_u32_e32 v155, s28, v149
	v_lshl_add_u64 v[172:173], v[172:173], 0, s[8:9]
	s_mov_b32 m0, s29
	ds_read_b128 v[204:207], v155
	ds_read_b128 v[212:215], v155 offset:1024
	ds_read_b128 v[216:219], v155 offset:2048
	ds_read_b128 v[220:223], v155 offset:3072
	global_load_lds_dwordx4 v[172:173], off
	s_add_i32 m0, s29, 0x2000
	v_lshl_add_u64 v[172:173], v[208:209], 0, s[8:9]
	global_load_lds_dwordx4 v[172:173], off
	s_setprio 1
	s_barrier
	s_waitcnt lgkmcnt(0)
	v_mfma_f32_16x16x32_bf16 v[108:111], v[204:207], v[168:171], v[108:111]
	v_mfma_f32_16x16x32_bf16 v[100:103], v[216:219], v[168:171], v[100:103]
	v_mfma_f32_16x16x32_bf16 v[92:95], v[204:207], v[180:183], v[92:95]
	v_mfma_f32_16x16x32_bf16 v[88:91], v[216:219], v[180:183], v[88:91]
	v_mfma_f32_16x16x32_bf16 v[84:87], v[204:207], v[188:191], v[84:87]
	v_mfma_f32_16x16x32_bf16 v[80:83], v[216:219], v[188:191], v[80:83]
	v_mfma_f32_16x16x32_bf16 v[68:71], v[204:207], v[196:199], v[68:71]
	v_mfma_f32_16x16x32_bf16 v[64:67], v[216:219], v[196:199], v[64:67]
	v_mfma_f32_16x16x32_bf16 v[108:111], v[212:215], v[176:179], v[108:111]
	v_mfma_f32_16x16x32_bf16 v[100:103], v[220:223], v[176:179], v[100:103]
	v_mfma_f32_16x16x32_bf16 v[92:95], v[212:215], v[184:187], v[92:95]
	v_mfma_f32_16x16x32_bf16 v[88:91], v[220:223], v[184:187], v[88:91]
	v_mfma_f32_16x16x32_bf16 v[84:87], v[212:215], v[192:195], v[84:87]
	v_mfma_f32_16x16x32_bf16 v[80:83], v[220:223], v[192:195], v[80:83]
	v_mfma_f32_16x16x32_bf16 v[68:71], v[212:215], v[200:203], v[68:71]
	v_mfma_f32_16x16x32_bf16 v[64:67], v[220:223], v[200:203], v[64:67]
	s_barrier
	s_setprio 0
	s_mov_b32 m0, s39
	v_lshl_add_u64 v[172:173], v[224:225], 0, s[8:9]
	ds_read_b128 v[168:171], v152 offset:49152
	ds_read_b128 v[176:179], v152 offset:50176
	ds_read_b128 v[180:183], v152 offset:51200
	ds_read_b128 v[184:187], v152 offset:52224
	ds_read_b128 v[188:191], v152 offset:53248
	ds_read_b128 v[192:195], v152 offset:54272
	ds_read_b128 v[196:199], v152 offset:55296
	ds_read_b128 v[200:203], v152 offset:56320
	global_load_lds_dwordx4 v[172:173], off
	s_mov_b32 m0, s40
	v_lshl_add_u64 v[172:173], v[226:227], 0, s[8:9]
	global_load_lds_dwordx4 v[172:173], off
	s_setprio 1
	s_barrier
	s_waitcnt lgkmcnt(0)
	v_mfma_f32_16x16x32_bf16 v[60:63], v[144:147], v[168:171], v[60:63]
	v_mfma_f32_16x16x32_bf16 v[56:59], v[160:163], v[168:171], v[56:59]
	v_mfma_f32_16x16x32_bf16 v[44:47], v[144:147], v[180:183], v[44:47]
	v_mfma_f32_16x16x32_bf16 v[40:43], v[160:163], v[180:183], v[40:43]
	v_mfma_f32_16x16x32_bf16 v[28:31], v[144:147], v[188:191], v[28:31]
	v_mfma_f32_16x16x32_bf16 v[24:27], v[160:163], v[188:191], v[24:27]
	v_mfma_f32_16x16x32_bf16 v[12:15], v[144:147], v[196:199], v[12:15]
	v_mfma_f32_16x16x32_bf16 v[8:11], v[160:163], v[196:199], v[8:11]
	v_mfma_f32_16x16x32_bf16 v[60:63], v[156:159], v[176:179], v[60:63]
	v_mfma_f32_16x16x32_bf16 v[56:59], v[164:167], v[176:179], v[56:59]
	v_mfma_f32_16x16x32_bf16 v[44:47], v[156:159], v[184:187], v[44:47]
	v_mfma_f32_16x16x32_bf16 v[40:43], v[164:167], v[184:187], v[40:43]
	v_mfma_f32_16x16x32_bf16 v[28:31], v[156:159], v[192:195], v[28:31]
	v_mfma_f32_16x16x32_bf16 v[24:27], v[164:167], v[192:195], v[24:27]
	v_mfma_f32_16x16x32_bf16 v[12:15], v[156:159], v[200:203], v[12:15]
	v_mfma_f32_16x16x32_bf16 v[8:11], v[164:167], v[200:203], v[8:11]
	s_barrier
	s_setprio 0
	s_add_u32 s26, s26, 0x40080
	s_addc_u32 s27, s27, 0
	s_add_i32 s28, s28, s33
	s_mov_b32 m0, s28
	v_lshl_add_u64 v[144:145], s[26:27], 0, v[130:131]
	global_load_lds_dwordx4 v[144:145], off
	s_add_i32 m0, s28, 0x2000
	v_lshl_add_u64 v[144:145], s[26:27], 0, v[134:135]
	global_load_lds_dwordx4 v[144:145], off
	s_waitcnt vmcnt(6)
	s_setprio 1
	s_barrier
	v_mfma_f32_16x16x32_bf16 v[52:55], v[204:207], v[168:171], v[52:55]
	v_mfma_f32_16x16x32_bf16 v[48:51], v[216:219], v[168:171], v[48:51]
	v_mfma_f32_16x16x32_bf16 v[36:39], v[204:207], v[180:183], v[36:39]
	v_mfma_f32_16x16x32_bf16 v[32:35], v[216:219], v[180:183], v[32:35]
	v_mfma_f32_16x16x32_bf16 v[20:23], v[204:207], v[188:191], v[20:23]
	v_mfma_f32_16x16x32_bf16 v[16:19], v[216:219], v[188:191], v[16:19]
	v_mfma_f32_16x16x32_bf16 v[4:7], v[204:207], v[196:199], v[4:7]
	v_mfma_f32_16x16x32_bf16 v[0:3], v[216:219], v[196:199], v[0:3]
	v_mfma_f32_16x16x32_bf16 v[52:55], v[212:215], v[176:179], v[52:55]
	v_mfma_f32_16x16x32_bf16 v[48:51], v[220:223], v[176:179], v[48:51]
	v_mfma_f32_16x16x32_bf16 v[36:39], v[212:215], v[184:187], v[36:39]
	v_mfma_f32_16x16x32_bf16 v[32:35], v[220:223], v[184:187], v[32:35]
	v_mfma_f32_16x16x32_bf16 v[20:23], v[212:215], v[192:195], v[20:23]
	v_mfma_f32_16x16x32_bf16 v[16:19], v[220:223], v[192:195], v[16:19]
	v_mfma_f32_16x16x32_bf16 v[4:7], v[212:215], v[200:203], v[4:7]
	v_mfma_f32_16x16x32_bf16 v[0:3], v[220:223], v[200:203], v[0:3]
	s_barrier
	s_setprio 0
	s_add_i32 s56, s56, 2
	s_add_u32 s2, s2, 0x100
	s_addc_u32 s3, s3, 0
	s_add_u32 s54, s54, 0x100
	s_addc_u32 s55, s55, 0
	s_cmp_gt_u32 s56, 13
	s_cbranch_scc0 .LBB0_712
	v_lshl_add_u32 v146, s0, 8, v148
	v_ashrrev_i32_e32 v147, 31, v146
	v_mov_b32_e32 v155, v242
	v_mov_b32_e32 v164, v243
	v_mov_b32_e32 v165, v244
	v_mov_b32_e32 v166, v245
	v_mov_b32_e32 v167, v246
	v_mov_b32_e32 v168, v247
	v_mov_b32_e32 v169, v248
	v_mov_b32_e32 v170, v249
	v_lshl_or_b32 v144, s1, 8, v150
	v_ashrrev_i32_e32 v145, 31, v144
	v_lshlrev_b64 v[160:161], 10, v[146:147]
	v_lshlrev_b64 v[162:163], 1, v[144:145]
	v_lshl_add_u64 v[144:145], s[92:93], 0, v[160:161]
	v_or_b32_e32 v156, 16, v146
	v_ashrrev_i32_e32 v157, 31, v156
	v_or_b32_e32 v158, 32, v146
	v_lshlrev_b64 v[156:157], 10, v[156:157]
	v_lshl_add_u64 v[144:145], v[144:145], 0, v[162:163]
	v_ashrrev_i32_e32 v159, 31, v158
	v_lshl_add_u64 v[156:157], s[92:93], 0, v[156:157]
	v_lshlrev_b64 v[158:159], 10, v[158:159]
	v_lshl_add_u64 v[156:157], v[156:157], 0, v[162:163]
	v_lshl_add_u64 v[158:159], s[92:93], 0, v[158:159]
	v_lshl_add_u64 v[158:159], v[158:159], 0, v[162:163]
	s_mov_b64 s[26:27], s[24:25]
	v_fmamk_f32 v147, v155, 0x3a800000, v154
	v_fmamk_f32 v155, v164, 0x3a800000, v154
	v_fmamk_f32 v160, v165, 0x3a800000, v154
	v_mul_f32_e32 v161, 0x4b800000, v147
	v_mul_f32_e32 v164, 0x4b800000, v155
	v_cmp_gt_f32_e32 vcc, s49, v147
	v_cmp_gt_f32_e64 s[0:1], s49, v155
	v_mul_f32_e32 v165, 0x4b800000, v160
	v_cndmask_b32_e32 v147, v147, v161, vcc
	v_cndmask_b32_e64 v155, v155, v164, s[0:1]
	v_cmp_gt_f32_e64 s[2:3], s49, v160
	v_rsq_f32_e32 v147, v147
	v_rsq_f32_e32 v155, v155
	v_cndmask_b32_e64 v160, v160, v165, s[2:3]
	v_rsq_f32_e32 v160, v160
	v_mul_f32_e32 v161, 0x45800000, v147
	v_mul_f32_e32 v164, 0x45800000, v155
	v_cndmask_b32_e32 v147, v147, v161, vcc
	v_mul_f32_e32 v165, 0x45800000, v160
	v_cndmask_b32_e64 v155, v155, v164, s[0:1]
	v_cndmask_b32_e64 v161, v160, v165, s[2:3]
	v_mul_f32_e32 v160, 0x3e0293ee, v147
	v_mul_f32_e32 v164, 0x3e0293ee, v155
	v_fmamk_f32 v171, v166, 0x3a800000, v154
	v_mul_f32_e32 v166, 0x3e0293ee, v161
	v_pk_mul_f32 v[126:127], v[126:127], v[160:161] op_sel_hi:[1,0]
	v_pk_mul_f32 v[124:125], v[124:125], v[160:161] op_sel_hi:[1,0]
	v_pk_mul_f32 v[122:123], v[122:123], v[160:161] op_sel_hi:[1,0]
	v_pk_mul_f32 v[120:121], v[120:121], v[160:161] op_sel_hi:[1,0]
	v_pk_mul_f32 v[110:111], v[110:111], v[160:161] op_sel_hi:[1,0]
	v_pk_mul_f32 v[108:109], v[108:109], v[160:161] op_sel_hi:[1,0]
	v_pk_mul_f32 v[102:103], v[102:103], v[160:161] op_sel_hi:[1,0]
	v_pk_mul_f32 v[100:101], v[100:101], v[160:161] op_sel_hi:[1,0]
	v_pk_mul_f32 v[118:119], v[118:119], v[164:165] op_sel_hi:[1,0]
	v_pk_mul_f32 v[116:117], v[116:117], v[164:165] op_sel_hi:[1,0]
	v_pk_mul_f32 v[114:115], v[114:115], v[164:165] op_sel_hi:[1,0]
	v_pk_mul_f32 v[112:113], v[112:113], v[164:165] op_sel_hi:[1,0]
	v_pk_mul_f32 v[94:95], v[94:95], v[164:165] op_sel_hi:[1,0]
	v_pk_mul_f32 v[92:93], v[92:93], v[164:165] op_sel_hi:[1,0]
	v_pk_mul_f32 v[160:161], v[90:91], v[164:165] op_sel_hi:[1,0]
	v_pk_mul_f32 v[164:165], v[88:89], v[164:165] op_sel_hi:[1,0]
	v_cvt_pk_bf16_f32 v88, v124, v125
	v_cvt_pk_bf16_f32 v89, v126, v127
	v_cvt_pk_bf16_f32 v90, v120, v121
	v_cvt_pk_bf16_f32 v91, v122, v123
	global_store_dwordx4 v[144:145], v[88:91], off
	v_fmamk_f32 v167, v167, 0x3a800000, v154
	v_pk_mul_f32 v[106:107], v[106:107], v[166:167] op_sel_hi:[1,0]
	v_cvt_pk_bf16_f32 v88, v108, v109
	v_cvt_pk_bf16_f32 v89, v110, v111
	v_cvt_pk_bf16_f32 v90, v100, v101
	v_cvt_pk_bf16_f32 v91, v102, v103
	global_store_dwordx4 v[144:145], v[88:91], off offset:256
	v_pk_mul_f32 v[104:105], v[104:105], v[166:167] op_sel_hi:[1,0]
	v_pk_mul_f32 v[98:99], v[98:99], v[166:167] op_sel_hi:[1,0]
	v_cvt_pk_bf16_f32 v88, v116, v117
	v_cvt_pk_bf16_f32 v89, v118, v119
	v_cvt_pk_bf16_f32 v90, v112, v113
	v_cvt_pk_bf16_f32 v91, v114, v115
	global_store_dwordx4 v[156:157], v[88:91], off
	v_pk_mul_f32 v[96:97], v[96:97], v[166:167] op_sel_hi:[1,0]
	v_pk_mul_f32 v[86:87], v[86:87], v[166:167] op_sel_hi:[1,0]
	v_cvt_pk_bf16_f32 v88, v92, v93
	v_cvt_pk_bf16_f32 v89, v94, v95
	v_cvt_pk_bf16_f32 v90, v164, v165
	v_cvt_pk_bf16_f32 v91, v160, v161
	global_store_dwordx4 v[156:157], v[88:91], off offset:256
	v_pk_mul_f32 v[84:85], v[84:85], v[166:167] op_sel_hi:[1,0]
	v_cmp_gt_f32_e32 vcc, s49, v171
	v_cvt_pk_bf16_f32 v88, v104, v105
	v_cvt_pk_bf16_f32 v89, v106, v107
	v_cvt_pk_bf16_f32 v90, v96, v97
	v_cvt_pk_bf16_f32 v91, v98, v99
	global_store_dwordx4 v[158:159], v[88:91], off
	s_mov_b64 s[0:1], 0x20000
	v_fmamk_f32 v168, v168, 0x3a800000, v154
	v_pk_mul_f32 v[88:89], v[82:83], v[166:167] op_sel_hi:[1,0]
	v_pk_mul_f32 v[82:83], v[80:81], v[166:167] op_sel_hi:[1,0]
	v_cvt_pk_bf16_f32 v80, v84, v85
	v_cvt_pk_bf16_f32 v81, v86, v87
	v_fmamk_f32 v169, v169, 0x3a800000, v154
	v_cvt_pk_bf16_f32 v82, v82, v83
	v_cvt_pk_bf16_f32 v83, v88, v89
	global_store_dwordx4 v[158:159], v[80:83], off offset:256
	v_fmamk_f32 v170, v170, 0x3a800000, v154
	s_mov_b64 s[2:3], s[22:23]
	v_mul_f32_e32 v82, 0x4b800000, v171
	v_cndmask_b32_e32 v82, v171, v82, vcc
	v_rsq_f32_e32 v82, v82
	v_or_b32_e32 v80, 48, v146
	v_ashrrev_i32_e32 v81, 31, v80
	v_lshlrev_b64 v[80:81], 10, v[80:81]
	v_mul_f32_e32 v83, 0x45800000, v82
	v_cndmask_b32_e32 v82, v82, v83, vcc
	v_lshl_add_u64 v[80:81], s[92:93], 0, v[80:81]
	v_mul_f32_e32 v82, 0x3e0293ee, v82
	v_lshl_add_u64 v[80:81], v[80:81], 0, v[162:163]
	v_pk_mul_f32 v[78:79], v[78:79], v[82:83] op_sel_hi:[1,0]
	v_pk_mul_f32 v[76:77], v[76:77], v[82:83] op_sel_hi:[1,0]
	v_pk_mul_f32 v[84:85], v[74:75], v[82:83] op_sel_hi:[1,0]
	v_pk_mul_f32 v[74:75], v[72:73], v[82:83] op_sel_hi:[1,0]
	v_cvt_pk_bf16_f32 v72, v76, v77
	v_cvt_pk_bf16_f32 v73, v78, v79
	v_pk_mul_f32 v[70:71], v[70:71], v[82:83] op_sel_hi:[1,0]
	v_cvt_pk_bf16_f32 v74, v74, v75
	v_cvt_pk_bf16_f32 v75, v84, v85
	global_store_dwordx4 v[80:81], v[72:75], off
	v_pk_mul_f32 v[68:69], v[68:69], v[82:83] op_sel_hi:[1,0]
	v_cmp_gt_f32_e32 vcc, s49, v167
	v_pk_mul_f32 v[72:73], v[66:67], v[82:83] op_sel_hi:[1,0]
	v_pk_mul_f32 v[66:67], v[64:65], v[82:83] op_sel_hi:[1,0]
	v_cvt_pk_bf16_f32 v64, v68, v69
	v_cvt_pk_bf16_f32 v65, v70, v71
	s_nop 0
	v_cvt_pk_bf16_f32 v66, v66, v67
	v_mul_f32_e32 v67, 0x4b800000, v167
	v_cndmask_b32_e32 v67, v167, v67, vcc
	v_rsq_f32_e32 v68, v67
	v_cvt_pk_bf16_f32 v67, v72, v73
	global_store_dwordx4 v[80:81], v[64:67], off offset:256
	s_nop 1
	v_mul_f32_e32 v66, 0x45800000, v68
	v_cndmask_b32_e32 v66, v68, v66, vcc
	v_mul_f32_e32 v66, 0x3e0293ee, v66
	v_lshl_add_u64 v[64:65], v[144:145], 0, s[0:1]
	v_pk_mul_f32 v[60:61], v[60:61], v[66:67] op_sel_hi:[1,0]
	s_mov_b32 s0, 0x20000
	v_pk_mul_f32 v[68:69], v[58:59], v[66:67] op_sel_hi:[1,0]
	v_pk_mul_f32 v[58:59], v[56:57], v[66:67] op_sel_hi:[1,0]
	v_cvt_pk_bf16_f32 v56, v60, v61
	v_add_co_u32_e32 v60, vcc, s0, v144
	v_pk_mul_f32 v[62:63], v[62:63], v[66:67] op_sel_hi:[1,0]
	s_nop 0
	v_addc_co_u32_e32 v61, vcc, 0, v145, vcc
	v_cvt_pk_bf16_f32 v57, v62, v63
	v_cvt_pk_bf16_f32 v58, v58, v59
	v_cvt_pk_bf16_f32 v59, v68, v69
	global_store_dwordx4 v[60:61], v[56:59], off
	v_pk_mul_f32 v[54:55], v[54:55], v[66:67] op_sel_hi:[1,0]
	v_pk_mul_f32 v[52:53], v[52:53], v[66:67] op_sel_hi:[1,0]
	v_pk_mul_f32 v[56:57], v[50:51], v[66:67] op_sel_hi:[1,0]
	v_pk_mul_f32 v[50:51], v[48:49], v[66:67] op_sel_hi:[1,0]
	v_cvt_pk_bf16_f32 v48, v52, v53
	v_cvt_pk_bf16_f32 v49, v54, v55
	v_cmp_gt_f32_e32 vcc, s49, v168
	v_cvt_pk_bf16_f32 v50, v50, v51
	v_mul_f32_e32 v51, 0x4b800000, v168
	s_mov_b64 s[0:1], 0x24000
	v_cndmask_b32_e32 v51, v168, v51, vcc
	v_rsq_f32_e32 v52, v51
	v_cvt_pk_bf16_f32 v51, v56, v57
	global_store_dwordx4 v[64:65], v[48:51], off offset:256
	s_nop 1
	v_mul_f32_e32 v50, 0x45800000, v52
	v_cndmask_b32_e32 v50, v52, v50, vcc
	v_mul_f32_e32 v50, 0x3e0293ee, v50
	v_lshl_add_u64 v[48:49], v[144:145], 0, s[0:1]
	v_pk_mul_f32 v[44:45], v[44:45], v[50:51] op_sel_hi:[1,0]
	s_mov_b32 s0, 0x24000
	v_pk_mul_f32 v[52:53], v[42:43], v[50:51] op_sel_hi:[1,0]
	v_pk_mul_f32 v[42:43], v[40:41], v[50:51] op_sel_hi:[1,0]
	v_cvt_pk_bf16_f32 v40, v44, v45
	v_add_co_u32_e32 v44, vcc, s0, v144
	v_pk_mul_f32 v[46:47], v[46:47], v[50:51] op_sel_hi:[1,0]
	s_nop 0
	v_addc_co_u32_e32 v45, vcc, 0, v145, vcc
	v_cvt_pk_bf16_f32 v41, v46, v47
	v_cvt_pk_bf16_f32 v42, v42, v43
	v_cvt_pk_bf16_f32 v43, v52, v53
	global_store_dwordx4 v[44:45], v[40:43], off
	v_pk_mul_f32 v[38:39], v[38:39], v[50:51] op_sel_hi:[1,0]
	v_pk_mul_f32 v[36:37], v[36:37], v[50:51] op_sel_hi:[1,0]
	v_pk_mul_f32 v[40:41], v[34:35], v[50:51] op_sel_hi:[1,0]
	v_pk_mul_f32 v[34:35], v[32:33], v[50:51] op_sel_hi:[1,0]
	v_cvt_pk_bf16_f32 v32, v36, v37
	v_cvt_pk_bf16_f32 v33, v38, v39
	v_cmp_gt_f32_e32 vcc, s49, v169
	v_cvt_pk_bf16_f32 v34, v34, v35
	v_mul_f32_e32 v35, 0x4b800000, v169
	s_mov_b32 s1, s18
	v_cndmask_b32_e32 v35, v169, v35, vcc
	v_rsq_f32_e32 v36, v35
	v_cvt_pk_bf16_f32 v35, v40, v41
	global_store_dwordx4 v[48:49], v[32:35], off offset:256
	s_mov_b32 s0, s20
	s_nop 0
	v_mul_f32_e32 v34, 0x45800000, v36
	v_cndmask_b32_e32 v34, v36, v34, vcc
	v_mul_f32_e32 v34, 0x3e0293ee, v34
	v_pk_mul_f32 v[28:29], v[28:29], v[34:35] op_sel_hi:[1,0]
	v_pk_mul_f32 v[36:37], v[26:27], v[34:35] op_sel_hi:[1,0]
	v_pk_mul_f32 v[26:27], v[24:25], v[34:35] op_sel_hi:[1,0]
	v_cvt_pk_bf16_f32 v24, v28, v29
	v_add_co_u32_e32 v28, vcc, s50, v144
	v_pk_mul_f32 v[30:31], v[30:31], v[34:35] op_sel_hi:[1,0]
	s_nop 0
	v_addc_co_u32_e32 v29, vcc, 0, v145, vcc
	v_cvt_pk_bf16_f32 v25, v30, v31
	v_cvt_pk_bf16_f32 v26, v26, v27
	v_cvt_pk_bf16_f32 v27, v36, v37
	global_store_dwordx4 v[28:29], v[24:27], off
	v_pk_mul_f32 v[22:23], v[22:23], v[34:35] op_sel_hi:[1,0]
	v_pk_mul_f32 v[20:21], v[20:21], v[34:35] op_sel_hi:[1,0]
	v_pk_mul_f32 v[24:25], v[18:19], v[34:35] op_sel_hi:[1,0]
	v_pk_mul_f32 v[18:19], v[16:17], v[34:35] op_sel_hi:[1,0]
	v_cvt_pk_bf16_f32 v16, v20, v21
	v_cvt_pk_bf16_f32 v17, v22, v23
	v_cmp_gt_f32_e32 vcc, s49, v170
	v_cvt_pk_bf16_f32 v18, v18, v19
	v_mul_f32_e32 v19, 0x4b800000, v170
	v_lshl_add_u64 v[32:33], v[144:145], 0, s[12:13]
	v_cndmask_b32_e32 v19, v170, v19, vcc
	v_rsq_f32_e32 v20, v19
	v_cvt_pk_bf16_f32 v19, v24, v25
	global_store_dwordx4 v[32:33], v[16:19], off offset:256
	s_nop 1
	v_mul_f32_e32 v18, 0x45800000, v20
	v_cndmask_b32_e32 v18, v20, v18, vcc
	v_mul_f32_e32 v18, 0x3e0293ee, v18
	v_pk_mul_f32 v[12:13], v[12:13], v[18:19] op_sel_hi:[1,0]
	v_pk_mul_f32 v[20:21], v[10:11], v[18:19] op_sel_hi:[1,0]
	v_pk_mul_f32 v[10:11], v[8:9], v[18:19] op_sel_hi:[1,0]
	v_cvt_pk_bf16_f32 v8, v12, v13
	v_add_co_u32_e32 v12, vcc, s51, v144
	v_pk_mul_f32 v[14:15], v[14:15], v[18:19] op_sel_hi:[1,0]
	s_nop 0
	v_addc_co_u32_e32 v13, vcc, 0, v145, vcc
	v_cvt_pk_bf16_f32 v9, v14, v15
	v_lshl_add_u64 v[16:17], v[144:145], 0, s[16:17]
	v_cvt_pk_bf16_f32 v10, v10, v11
	v_cvt_pk_bf16_f32 v11, v20, v21
	global_store_dwordx4 v[12:13], v[8:11], off
	s_and_b64 vcc, exec, s[6:7]
	v_pk_mul_f32 v[6:7], v[6:7], v[18:19] op_sel_hi:[1,0]
	v_pk_mul_f32 v[8:9], v[2:3], v[18:19] op_sel_hi:[1,0]
	v_pk_mul_f32 v[2:3], v[0:1], v[18:19] op_sel_hi:[1,0]
	v_pk_mul_f32 v[4:5], v[4:5], v[18:19] op_sel_hi:[1,0]
	s_nop 0
	v_cvt_pk_bf16_f32 v0, v4, v5
	v_cvt_pk_bf16_f32 v1, v6, v7
	v_cvt_pk_bf16_f32 v2, v2, v3
	v_cvt_pk_bf16_f32 v3, v8, v9
	global_store_dwordx4 v[16:17], v[0:3], off offset:256
	s_cbranch_vccz .LBB0_705
	s_waitcnt vmcnt(0)
	s_cmpk_gt_u32 s30, 0xff
	s_cbranch_scc1 .LBB0_716
	s_barrier

.LBB0_849:
	s_ashr_i32 s27, s26, 31
	v_cmp_lt_i64_e32 vcc, s[28:29], v[140:141]
	s_lshl_b64 s[28:29], s[26:27], 19
	s_add_u32 s28, s90, s28
	s_addc_u32 s29, s91, s29
	s_and_b64 s[30:31], vcc, exec
	s_cselect_b32 s27, s29, s35
	s_cselect_b32 s62, s28, s34
	s_ashr_i32 s25, s24, 31
	s_lshl_b64 s[30:31], s[24:25], 19
	v_readlane_b32 s25, v253, 45
	s_add_u32 s30, s25, s30
	v_readlane_b32 s25, v253, 46
	s_addc_u32 s31, s25, s31
	s_and_b64 s[38:39], vcc, exec
	s_cselect_b32 s25, s31, s37
	s_cselect_b32 s63, s30, s36
	s_add_u32 s34, s34, 0x40080
	s_addc_u32 s35, s35, 0
	s_add_u32 s64, s36, 0x100
	v_lshl_add_u32 v240, s0, 8, v148
	v_ashrrev_i32_e32 v241, 31, v240
	v_lshl_add_u64 v[240:241], v[240:241], 2, s[2:3]
	global_load_dword v242, v[240:241], off
	global_load_dword v243, v[240:241], off offset:64
	global_load_dword v244, v[240:241], off offset:128
	global_load_dword v245, v[240:241], off offset:192
	global_load_dword v246, v[240:241], off offset:512
	global_load_dword v247, v[240:241], off offset:576
	global_load_dword v248, v[240:241], off offset:640
	global_load_dword v249, v[240:241], off offset:704
	v_mov_b32_e32 v0, 0
	s_addc_u32 s65, s37, 0
	s_mov_b32 s66, -2
	v_mov_b32_e32 v1, v0
	v_mov_b64_e32 v[2:3], v[0:1]
	v_mov_b64_e32 v[4:5], v[0:1]
	v_mov_b64_e32 v[6:7], v[0:1]
	v_mov_b64_e32 v[8:9], v[0:1]
	v_mov_b64_e32 v[10:11], v[0:1]
	v_mov_b64_e32 v[12:13], v[0:1]
	v_mov_b64_e32 v[14:15], v[0:1]
	v_mov_b64_e32 v[16:17], v[0:1]
	v_mov_b64_e32 v[18:19], v[0:1]
	v_mov_b64_e32 v[20:21], v[0:1]
	v_mov_b64_e32 v[22:23], v[0:1]
	v_mov_b64_e32 v[24:25], v[0:1]
	v_mov_b64_e32 v[26:27], v[0:1]
	v_mov_b64_e32 v[28:29], v[0:1]
	v_mov_b64_e32 v[30:31], v[0:1]
	v_mov_b64_e32 v[32:33], v[0:1]
	v_mov_b64_e32 v[34:35], v[0:1]
	v_mov_b64_e32 v[36:37], v[0:1]
	v_mov_b64_e32 v[38:39], v[0:1]
	v_mov_b64_e32 v[40:41], v[0:1]
	v_mov_b64_e32 v[42:43], v[0:1]
	v_mov_b64_e32 v[44:45], v[0:1]
	v_mov_b64_e32 v[46:47], v[0:1]
	v_mov_b64_e32 v[48:49], v[0:1]
	v_mov_b64_e32 v[50:51], v[0:1]
	v_mov_b64_e32 v[52:53], v[0:1]
	v_mov_b64_e32 v[54:55], v[0:1]
	v_mov_b64_e32 v[56:57], v[0:1]
	v_mov_b64_e32 v[58:59], v[0:1]
	v_mov_b64_e32 v[60:61], v[0:1]
	v_mov_b64_e32 v[62:63], v[0:1]
	v_mov_b64_e32 v[64:65], v[0:1]
	v_mov_b64_e32 v[66:67], v[0:1]
	v_mov_b64_e32 v[68:69], v[0:1]
	v_mov_b64_e32 v[70:71], v[0:1]
	v_mov_b64_e32 v[72:73], v[0:1]
	v_mov_b64_e32 v[74:75], v[0:1]
	v_mov_b64_e32 v[76:77], v[0:1]
	v_mov_b64_e32 v[78:79], v[0:1]
	v_mov_b64_e32 v[80:81], v[0:1]
	v_mov_b64_e32 v[82:83], v[0:1]
	v_mov_b64_e32 v[84:85], v[0:1]
	v_mov_b64_e32 v[86:87], v[0:1]
	v_mov_b64_e32 v[88:89], v[0:1]
	v_mov_b64_e32 v[90:91], v[0:1]
	v_mov_b64_e32 v[92:93], v[0:1]
	v_mov_b64_e32 v[94:95], v[0:1]
	v_mov_b64_e32 v[96:97], v[0:1]
	v_mov_b64_e32 v[98:99], v[0:1]
	v_mov_b64_e32 v[100:101], v[0:1]
	v_mov_b64_e32 v[102:103], v[0:1]
	v_mov_b64_e32 v[104:105], v[0:1]
	v_mov_b64_e32 v[106:107], v[0:1]
	v_mov_b64_e32 v[108:109], v[0:1]
	v_mov_b64_e32 v[110:111], v[0:1]
	v_mov_b64_e32 v[112:113], v[0:1]
	v_mov_b64_e32 v[114:115], v[0:1]
	v_mov_b64_e32 v[116:117], v[0:1]
	v_mov_b64_e32 v[118:119], v[0:1]
	v_mov_b64_e32 v[120:121], v[0:1]
	v_mov_b64_e32 v[122:123], v[0:1]
	v_mov_b64_e32 v[124:125], v[0:1]
	v_mov_b64_e32 v[126:127], v[0:1]
.LBB0_850:
	ds_read_b128 v[144:147], v151
	ds_read_b128 v[156:159], v151 offset:1024
	ds_read_b128 v[160:163], v151 offset:2048
	ds_read_b128 v[164:167], v151 offset:3072
	s_add_u32 s36, s34, 0xfffc0080
	s_addc_u32 s37, s35, -1
	s_cmp_eq_u32 s66, 12
	s_cselect_b32 s39, s27, s37
	s_cselect_b32 s38, s62, s36
	s_cselect_b32 s37, s25, s65
	s_cselect_b32 s36, s63, s64
	v_lshl_add_u64 v[172:173], s[34:35], 0, v[136:137]
	s_add_i32 m0, s42, 0xc000
	ds_read_b128 v[168:171], v152
	ds_read_b128 v[176:179], v152 offset:1024
	ds_read_b128 v[180:183], v152 offset:2048
	ds_read_b128 v[184:187], v152 offset:3072
	ds_read_b128 v[188:191], v152 offset:4096
	ds_read_b128 v[192:195], v152 offset:5120
	ds_read_b128 v[196:199], v152 offset:6144
	ds_read_b128 v[200:203], v152 offset:7168
	global_load_lds_dwordx4 v[172:173], off
	s_add_i32 m0, s42, 0xe000
	v_lshl_add_u64 v[172:173], s[34:35], 0, v[138:139]
	global_load_lds_dwordx4 v[172:173], off
	s_waitcnt lgkmcnt(8)
	s_setprio 1
	s_barrier
	s_waitcnt lgkmcnt(0)
	v_mfma_f32_16x16x32_bf16 v[124:127], v[144:147], v[168:171], v[124:127]
	v_mfma_f32_16x16x32_bf16 v[120:123], v[160:163], v[168:171], v[120:123]
	v_mfma_f32_16x16x32_bf16 v[116:119], v[144:147], v[180:183], v[116:119]
	v_mfma_f32_16x16x32_bf16 v[112:115], v[160:163], v[180:183], v[112:115]
	v_mfma_f32_16x16x32_bf16 v[92:95], v[144:147], v[188:191], v[92:95]
	v_mfma_f32_16x16x32_bf16 v[88:91], v[160:163], v[188:191], v[88:91]
	v_mfma_f32_16x16x32_bf16 v[76:79], v[144:147], v[196:199], v[76:79]
	v_mfma_f32_16x16x32_bf16 v[72:75], v[160:163], v[196:199], v[72:75]
	v_mfma_f32_16x16x32_bf16 v[124:127], v[156:159], v[176:179], v[124:127]
	v_mfma_f32_16x16x32_bf16 v[120:123], v[164:167], v[176:179], v[120:123]
	v_mfma_f32_16x16x32_bf16 v[116:119], v[156:159], v[184:187], v[116:119]
	v_mfma_f32_16x16x32_bf16 v[112:115], v[164:167], v[184:187], v[112:115]
	v_mfma_f32_16x16x32_bf16 v[92:95], v[156:159], v[192:195], v[92:95]
	v_mfma_f32_16x16x32_bf16 v[88:91], v[164:167], v[192:195], v[88:91]
	v_mfma_f32_16x16x32_bf16 v[76:79], v[156:159], v[200:203], v[76:79]
	v_mfma_f32_16x16x32_bf16 v[72:75], v[164:167], v[200:203], v[72:75]
	s_barrier
	s_setprio 0
	s_add_i32 s67, s55, s41
	v_lshl_add_u64 v[172:173], s[36:37], 0, v[130:131]
	s_mov_b32 m0, s67
	ds_read_b128 v[204:207], v153
	ds_read_b128 v[212:215], v153 offset:1024
	ds_read_b128 v[216:219], v153 offset:2048
	ds_read_b128 v[220:223], v153 offset:3072
	global_load_lds_dwordx4 v[172:173], off
	s_add_i32 m0, s67, 0x2000
	v_lshl_add_u64 v[208:209], s[36:37], 0, v[134:135]
	global_load_lds_dwordx4 v[208:209], off
	s_setprio 1
	s_barrier
	s_waitcnt lgkmcnt(0)
	v_mfma_f32_16x16x32_bf16 v[108:111], v[204:207], v[168:171], v[108:111]
	v_mfma_f32_16x16x32_bf16 v[104:107], v[216:219], v[168:171], v[104:107]
	v_mfma_f32_16x16x32_bf16 v[100:103], v[204:207], v[180:183], v[100:103]
	v_mfma_f32_16x16x32_bf16 v[96:99], v[216:219], v[180:183], v[96:99]
	v_mfma_f32_16x16x32_bf16 v[84:87], v[204:207], v[188:191], v[84:87]
	v_mfma_f32_16x16x32_bf16 v[80:83], v[216:219], v[188:191], v[80:83]
	v_mfma_f32_16x16x32_bf16 v[68:71], v[204:207], v[196:199], v[68:71]
	v_mfma_f32_16x16x32_bf16 v[64:67], v[216:219], v[196:199], v[64:67]
	v_mfma_f32_16x16x32_bf16 v[108:111], v[212:215], v[176:179], v[108:111]
	v_mfma_f32_16x16x32_bf16 v[104:107], v[220:223], v[176:179], v[104:107]
	v_mfma_f32_16x16x32_bf16 v[100:103], v[212:215], v[184:187], v[100:103]
	v_mfma_f32_16x16x32_bf16 v[96:99], v[220:223], v[184:187], v[96:99]
	v_mfma_f32_16x16x32_bf16 v[84:87], v[212:215], v[192:195], v[84:87]
	v_mfma_f32_16x16x32_bf16 v[80:83], v[220:223], v[192:195], v[80:83]
	v_mfma_f32_16x16x32_bf16 v[68:71], v[212:215], v[200:203], v[68:71]
	v_mfma_f32_16x16x32_bf16 v[64:67], v[220:223], v[200:203], v[64:67]
	s_barrier
	s_setprio 0
	s_mov_b32 m0, s42
	v_lshl_add_u64 v[224:225], s[38:39], 0, v[128:129]
	ds_read_b128 v[168:171], v152 offset:16384
	ds_read_b128 v[176:179], v152 offset:17408
	ds_read_b128 v[180:183], v152 offset:18432
	ds_read_b128 v[184:187], v152 offset:19456
	ds_read_b128 v[188:191], v152 offset:20480
	ds_read_b128 v[192:195], v152 offset:21504
	ds_read_b128 v[196:199], v152 offset:22528
	ds_read_b128 v[200:203], v152 offset:23552
	global_load_lds_dwordx4 v[224:225], off
	s_mov_b32 m0, s43
	v_lshl_add_u64 v[226:227], s[38:39], 0, v[132:133]
	global_load_lds_dwordx4 v[226:227], off
	s_setprio 1
	s_barrier
	s_waitcnt lgkmcnt(0)
	v_mfma_f32_16x16x32_bf16 v[60:63], v[144:147], v[168:171], v[60:63]
	v_mfma_f32_16x16x32_bf16 v[56:59], v[160:163], v[168:171], v[56:59]
	v_mfma_f32_16x16x32_bf16 v[44:47], v[144:147], v[180:183], v[44:47]
	v_mfma_f32_16x16x32_bf16 v[40:43], v[160:163], v[180:183], v[40:43]
	v_mfma_f32_16x16x32_bf16 v[28:31], v[144:147], v[188:191], v[28:31]
	v_mfma_f32_16x16x32_bf16 v[24:27], v[160:163], v[188:191], v[24:27]
	v_mfma_f32_16x16x32_bf16 v[12:15], v[144:147], v[196:199], v[12:15]
	v_mfma_f32_16x16x32_bf16 v[8:11], v[160:163], v[196:199], v[8:11]
	v_mfma_f32_16x16x32_bf16 v[60:63], v[156:159], v[176:179], v[60:63]
	v_mfma_f32_16x16x32_bf16 v[56:59], v[164:167], v[176:179], v[56:59]
	v_mfma_f32_16x16x32_bf16 v[44:47], v[156:159], v[184:187], v[44:47]
	v_mfma_f32_16x16x32_bf16 v[40:43], v[164:167], v[184:187], v[40:43]
	v_mfma_f32_16x16x32_bf16 v[28:31], v[156:159], v[192:195], v[28:31]
	v_mfma_f32_16x16x32_bf16 v[24:27], v[164:167], v[192:195], v[24:27]
	v_mfma_f32_16x16x32_bf16 v[12:15], v[156:159], v[200:203], v[12:15]
	v_mfma_f32_16x16x32_bf16 v[8:11], v[164:167], v[200:203], v[8:11]
	s_barrier
	s_setprio 0
	s_add_u32 s68, s36, 0x40000
	s_addc_u32 s69, s37, 0
	s_add_i32 s67, s56, s41
	s_mov_b32 m0, s67
	v_lshl_add_u64 v[144:145], s[68:69], 0, v[130:131]
	global_load_lds_dwordx4 v[144:145], off
	s_add_i32 m0, s67, 0x2000
	v_lshl_add_u64 v[144:145], s[68:69], 0, v[134:135]
	global_load_lds_dwordx4 v[144:145], off
	s_waitcnt vmcnt(6)
	s_setprio 1
	s_barrier
	v_mfma_f32_16x16x32_bf16 v[52:55], v[204:207], v[168:171], v[52:55]
	v_mfma_f32_16x16x32_bf16 v[48:51], v[216:219], v[168:171], v[48:51]
	v_mfma_f32_16x16x32_bf16 v[36:39], v[204:207], v[180:183], v[36:39]
	v_mfma_f32_16x16x32_bf16 v[32:35], v[216:219], v[180:183], v[32:35]
	v_mfma_f32_16x16x32_bf16 v[20:23], v[204:207], v[188:191], v[20:23]
	v_mfma_f32_16x16x32_bf16 v[16:19], v[216:219], v[188:191], v[16:19]
	v_mfma_f32_16x16x32_bf16 v[4:7], v[204:207], v[196:199], v[4:7]
	v_mfma_f32_16x16x32_bf16 v[0:3], v[216:219], v[196:199], v[0:3]
	v_mfma_f32_16x16x32_bf16 v[52:55], v[212:215], v[176:179], v[52:55]
	v_mfma_f32_16x16x32_bf16 v[48:51], v[220:223], v[176:179], v[48:51]
	v_mfma_f32_16x16x32_bf16 v[36:39], v[212:215], v[184:187], v[36:39]
	v_mfma_f32_16x16x32_bf16 v[32:35], v[220:223], v[184:187], v[32:35]
	v_mfma_f32_16x16x32_bf16 v[20:23], v[212:215], v[192:195], v[20:23]
	v_mfma_f32_16x16x32_bf16 v[16:19], v[220:223], v[192:195], v[16:19]
	v_mfma_f32_16x16x32_bf16 v[4:7], v[212:215], v[200:203], v[4:7]
	v_mfma_f32_16x16x32_bf16 v[0:3], v[220:223], v[200:203], v[0:3]
	s_barrier
	s_setprio 0
	s_add_i32 s67, 0, 0x18000
	v_add_u32_e32 v155, s67, v149
	ds_read_b128 v[144:147], v155
	ds_read_b128 v[156:159], v155 offset:1024
	ds_read_b128 v[160:163], v155 offset:2048
	ds_read_b128 v[164:167], v155 offset:3072
	s_add_u32 s38, s38, 0x40000
	s_addc_u32 s39, s39, 0
	s_mov_b32 m0, s48
	v_lshl_add_u64 v[204:205], s[38:39], 0, v[128:129]
	ds_read_b128 v[168:171], v152 offset:32768
	ds_read_b128 v[176:179], v152 offset:33792
	ds_read_b128 v[180:183], v152 offset:34816
	ds_read_b128 v[184:187], v152 offset:35840
	ds_read_b128 v[188:191], v152 offset:36864
	ds_read_b128 v[192:195], v152 offset:37888
	ds_read_b128 v[196:199], v152 offset:38912
	ds_read_b128 v[200:203], v152 offset:39936
	global_load_lds_dwordx4 v[204:205], off
	s_mov_b32 m0, s49
	v_lshl_add_u64 v[204:205], s[38:39], 0, v[132:133]
	global_load_lds_dwordx4 v[204:205], off
	s_waitcnt lgkmcnt(8)
	s_setprio 1
	s_barrier
	s_waitcnt lgkmcnt(0)
	v_mfma_f32_16x16x32_bf16 v[124:127], v[144:147], v[168:171], v[124:127]
	v_mfma_f32_16x16x32_bf16 v[120:123], v[160:163], v[168:171], v[120:123]
	v_mfma_f32_16x16x32_bf16 v[116:119], v[144:147], v[180:183], v[116:119]
	v_mfma_f32_16x16x32_bf16 v[112:115], v[160:163], v[180:183], v[112:115]
	v_mfma_f32_16x16x32_bf16 v[92:95], v[144:147], v[188:191], v[92:95]
	v_mfma_f32_16x16x32_bf16 v[88:91], v[160:163], v[188:191], v[88:91]
	v_mfma_f32_16x16x32_bf16 v[76:79], v[144:147], v[196:199], v[76:79]
	v_mfma_f32_16x16x32_bf16 v[72:75], v[160:163], v[196:199], v[72:75]
	v_mfma_f32_16x16x32_bf16 v[124:127], v[156:159], v[176:179], v[124:127]
	v_mfma_f32_16x16x32_bf16 v[120:123], v[164:167], v[176:179], v[120:123]
	v_mfma_f32_16x16x32_bf16 v[116:119], v[156:159], v[184:187], v[116:119]
	v_mfma_f32_16x16x32_bf16 v[112:115], v[164:167], v[184:187], v[112:115]
	v_mfma_f32_16x16x32_bf16 v[92:95], v[156:159], v[192:195], v[92:95]
	v_mfma_f32_16x16x32_bf16 v[88:91], v[164:167], v[192:195], v[88:91]
	v_mfma_f32_16x16x32_bf16 v[76:79], v[156:159], v[200:203], v[76:79]
	v_mfma_f32_16x16x32_bf16 v[72:75], v[164:167], v[200:203], v[72:75]
	s_barrier
	s_setprio 0
	s_add_i32 s38, 0, 0x1c000
	s_add_i32 s39, s67, s41
	v_add_u32_e32 v155, s38, v149
	v_lshl_add_u64 v[172:173], v[172:173], 0, s[8:9]
	s_mov_b32 m0, s39
	ds_read_b128 v[204:207], v155
	ds_read_b128 v[212:215], v155 offset:1024
	ds_read_b128 v[216:219], v155 offset:2048
	ds_read_b128 v[220:223], v155 offset:3072
	global_load_lds_dwordx4 v[172:173], off
	s_add_i32 m0, s39, 0x2000
	v_lshl_add_u64 v[172:173], v[208:209], 0, s[8:9]
	global_load_lds_dwordx4 v[172:173], off
	s_setprio 1
	s_barrier
	s_waitcnt lgkmcnt(0)
	v_mfma_f32_16x16x32_bf16 v[108:111], v[204:207], v[168:171], v[108:111]
	v_mfma_f32_16x16x32_bf16 v[104:107], v[216:219], v[168:171], v[104:107]
	v_mfma_f32_16x16x32_bf16 v[100:103], v[204:207], v[180:183], v[100:103]
	v_mfma_f32_16x16x32_bf16 v[96:99], v[216:219], v[180:183], v[96:99]
	v_mfma_f32_16x16x32_bf16 v[84:87], v[204:207], v[188:191], v[84:87]
	v_mfma_f32_16x16x32_bf16 v[80:83], v[216:219], v[188:191], v[80:83]
	v_mfma_f32_16x16x32_bf16 v[68:71], v[204:207], v[196:199], v[68:71]
	v_mfma_f32_16x16x32_bf16 v[64:67], v[216:219], v[196:199], v[64:67]
	v_mfma_f32_16x16x32_bf16 v[108:111], v[212:215], v[176:179], v[108:111]
	v_mfma_f32_16x16x32_bf16 v[104:107], v[220:223], v[176:179], v[104:107]
	v_mfma_f32_16x16x32_bf16 v[100:103], v[212:215], v[184:187], v[100:103]
	v_mfma_f32_16x16x32_bf16 v[96:99], v[220:223], v[184:187], v[96:99]
	v_mfma_f32_16x16x32_bf16 v[84:87], v[212:215], v[192:195], v[84:87]
	v_mfma_f32_16x16x32_bf16 v[80:83], v[220:223], v[192:195], v[80:83]
	v_mfma_f32_16x16x32_bf16 v[68:71], v[212:215], v[200:203], v[68:71]
	v_mfma_f32_16x16x32_bf16 v[64:67], v[220:223], v[200:203], v[64:67]
	s_barrier
	s_setprio 0
	s_mov_b32 m0, s51
	v_lshl_add_u64 v[172:173], v[224:225], 0, s[8:9]
	ds_read_b128 v[168:171], v152 offset:49152
	ds_read_b128 v[176:179], v152 offset:50176
	ds_read_b128 v[180:183], v152 offset:51200
	ds_read_b128 v[184:187], v152 offset:52224
	ds_read_b128 v[188:191], v152 offset:53248
	ds_read_b128 v[192:195], v152 offset:54272
	ds_read_b128 v[196:199], v152 offset:55296
	ds_read_b128 v[200:203], v152 offset:56320
	global_load_lds_dwordx4 v[172:173], off
	s_mov_b32 m0, s52
	v_lshl_add_u64 v[172:173], v[226:227], 0, s[8:9]
	global_load_lds_dwordx4 v[172:173], off
	s_setprio 1
	s_barrier
	s_waitcnt lgkmcnt(0)
	v_mfma_f32_16x16x32_bf16 v[60:63], v[144:147], v[168:171], v[60:63]
	v_mfma_f32_16x16x32_bf16 v[56:59], v[160:163], v[168:171], v[56:59]
	v_mfma_f32_16x16x32_bf16 v[44:47], v[144:147], v[180:183], v[44:47]
	v_mfma_f32_16x16x32_bf16 v[40:43], v[160:163], v[180:183], v[40:43]
	v_mfma_f32_16x16x32_bf16 v[28:31], v[144:147], v[188:191], v[28:31]
	v_mfma_f32_16x16x32_bf16 v[24:27], v[160:163], v[188:191], v[24:27]
	v_mfma_f32_16x16x32_bf16 v[12:15], v[144:147], v[196:199], v[12:15]
	v_mfma_f32_16x16x32_bf16 v[8:11], v[160:163], v[196:199], v[8:11]
	v_mfma_f32_16x16x32_bf16 v[60:63], v[156:159], v[176:179], v[60:63]
	v_mfma_f32_16x16x32_bf16 v[56:59], v[164:167], v[176:179], v[56:59]
	v_mfma_f32_16x16x32_bf16 v[44:47], v[156:159], v[184:187], v[44:47]
	v_mfma_f32_16x16x32_bf16 v[40:43], v[164:167], v[184:187], v[40:43]
	v_mfma_f32_16x16x32_bf16 v[28:31], v[156:159], v[192:195], v[28:31]
	v_mfma_f32_16x16x32_bf16 v[24:27], v[164:167], v[192:195], v[24:27]
	v_mfma_f32_16x16x32_bf16 v[12:15], v[156:159], v[200:203], v[12:15]
	v_mfma_f32_16x16x32_bf16 v[8:11], v[164:167], v[200:203], v[8:11]
	s_barrier
	s_setprio 0
	s_add_u32 s36, s36, 0x40080
	s_addc_u32 s37, s37, 0
	s_add_i32 s38, s38, s41
	s_mov_b32 m0, s38
	v_lshl_add_u64 v[144:145], s[36:37], 0, v[130:131]
	global_load_lds_dwordx4 v[144:145], off
	s_add_i32 m0, s38, 0x2000
	v_lshl_add_u64 v[144:145], s[36:37], 0, v[134:135]
	global_load_lds_dwordx4 v[144:145], off
	s_waitcnt vmcnt(6)
	s_setprio 1
	s_barrier
	v_mfma_f32_16x16x32_bf16 v[52:55], v[204:207], v[168:171], v[52:55]
	v_mfma_f32_16x16x32_bf16 v[48:51], v[216:219], v[168:171], v[48:51]
	v_mfma_f32_16x16x32_bf16 v[36:39], v[204:207], v[180:183], v[36:39]
	v_mfma_f32_16x16x32_bf16 v[32:35], v[216:219], v[180:183], v[32:35]
	v_mfma_f32_16x16x32_bf16 v[20:23], v[204:207], v[188:191], v[20:23]
	v_mfma_f32_16x16x32_bf16 v[16:19], v[216:219], v[188:191], v[16:19]
	v_mfma_f32_16x16x32_bf16 v[4:7], v[204:207], v[196:199], v[4:7]
	v_mfma_f32_16x16x32_bf16 v[0:3], v[216:219], v[196:199], v[0:3]
	v_mfma_f32_16x16x32_bf16 v[52:55], v[212:215], v[176:179], v[52:55]
	v_mfma_f32_16x16x32_bf16 v[48:51], v[220:223], v[176:179], v[48:51]
	v_mfma_f32_16x16x32_bf16 v[36:39], v[212:215], v[184:187], v[36:39]
	v_mfma_f32_16x16x32_bf16 v[32:35], v[220:223], v[184:187], v[32:35]
	v_mfma_f32_16x16x32_bf16 v[20:23], v[212:215], v[192:195], v[20:23]
	v_mfma_f32_16x16x32_bf16 v[16:19], v[220:223], v[192:195], v[16:19]
	v_mfma_f32_16x16x32_bf16 v[4:7], v[212:215], v[200:203], v[4:7]
	v_mfma_f32_16x16x32_bf16 v[0:3], v[220:223], v[200:203], v[0:3]
	s_barrier
	s_setprio 0
	s_add_i32 s66, s66, 2
	s_add_u32 s34, s34, 0x100
	s_addc_u32 s35, s35, 0
	s_add_u32 s64, s64, 0x100
	s_addc_u32 s65, s65, 0
	s_cmp_gt_u32 s66, 13
	s_cbranch_scc0 .LBB0_850
	v_lshl_add_u32 v146, s0, 8, v148
	v_ashrrev_i32_e32 v147, 31, v146
	v_mov_b32_e32 v155, v242
	v_mov_b32_e32 v162, v243
	v_mov_b32_e32 v163, v244
	v_mov_b32_e32 v164, v245
	v_mov_b32_e32 v165, v246
	v_mov_b32_e32 v166, v247
	v_mov_b32_e32 v167, v248
	v_mov_b32_e32 v168, v249
	v_lshl_or_b32 v144, s1, 8, v150
	v_ashrrev_i32_e32 v145, 31, v144
	v_lshlrev_b64 v[158:159], 13, v[146:147]
	v_lshlrev_b64 v[160:161], 1, v[144:145]
	v_lshl_add_u64 v[144:145], s[92:93], 0, v[158:159]
	v_lshl_add_u64 v[144:145], v[144:145], 0, v[160:161]
	v_or_b32_e32 v156, 16, v146
	v_ashrrev_i32_e32 v157, 31, v156
	v_lshlrev_b64 v[156:157], 13, v[156:157]
	v_lshl_add_u64 v[156:157], s[92:93], 0, v[156:157]
	v_lshl_add_u64 v[156:157], v[156:157], 0, v[160:161]
	s_mov_b64 s[36:37], s[30:31]
	s_mov_b64 s[34:35], s[28:29]
	v_fmamk_f32 v147, v155, 0x3a800000, v154
	v_mul_f32_e32 v158, 0x4b800000, v147
	v_cmp_gt_f32_e32 vcc, s57, v147
	v_fmamk_f32 v155, v162, 0x3a800000, v154
	v_mul_f32_e32 v162, 0x4b800000, v155
	v_cndmask_b32_e32 v147, v147, v158, vcc
	v_rsq_f32_e32 v158, v147
	v_cmp_gt_f32_e64 s[0:1], s57, v155
	v_fmamk_f32 v159, v163, 0x3a800000, v154
	v_fmamk_f32 v163, v164, 0x3a800000, v154
	v_cndmask_b32_e64 v155, v155, v162, s[0:1]
	v_rsq_f32_e32 v155, v155
	v_mul_f32_e32 v162, 0x45800000, v158
	v_cndmask_b32_e32 v158, v158, v162, vcc
	v_pk_mul_f32 v[124:125], v[124:125], v[158:159] op_sel_hi:[1,0]
	v_pk_mul_f32 v[104:105], v[104:105], v[158:159] op_sel_hi:[1,0]
	v_fmamk_f32 v164, v165, 0x3a800000, v154
	v_fmamk_f32 v165, v166, 0x3a800000, v154
	v_fmamk_f32 v166, v167, 0x3a800000, v154
	v_mul_f32_e32 v167, 0x45800000, v155
	v_pk_mul_f32 v[126:127], v[126:127], v[158:159] op_sel_hi:[1,0]
	v_pk_mul_f32 v[122:123], v[122:123], v[158:159] op_sel_hi:[1,0]
	v_pk_mul_f32 v[120:121], v[120:121], v[158:159] op_sel_hi:[1,0]
	v_pk_mul_f32 v[108:109], v[108:109], v[158:159] op_sel_hi:[1,0]
	v_pk_mul_f32 v[106:107], v[106:107], v[158:159] op_sel_hi:[1,0]
	v_max_f32_e32 v124, 0, v124
	v_max_f32_e32 v125, 0, v125
	v_max_f32_e32 v104, 0, v104
	v_cndmask_b32_e64 v162, v155, v167, s[0:1]
	v_pk_mul_f32 v[110:111], v[110:111], v[158:159] op_sel_hi:[1,0]
	v_max_f32_e32 v120, 0, v120
	v_max_f32_e32 v121, 0, v121
	v_max_f32_e32 v126, 0, v126
	v_max_f32_e32 v122, 0, v122
	v_max_f32_e32 v127, 0, v127
	v_max_f32_e32 v123, 0, v123
	v_max_f32_e32 v108, 0, v108
	v_max_f32_e32 v109, 0, v109
	v_max_f32_e32 v105, 0, v105
	v_max_f32_e32 v106, 0, v106
	v_max_f32_e32 v107, 0, v107
	v_mul_f32_e32 v124, v124, v124
	v_mul_f32_e32 v125, v125, v125
	v_mul_f32_e32 v155, v104, v104
	v_cvt_pk_bf16_f32 v104, v124, v125
	v_fmamk_f32 v147, v168, 0x3a800000, v154
	v_pk_mul_f32 v[112:113], v[112:113], v[162:163] op_sel_hi:[1,0]
	v_max_f32_e32 v110, 0, v110
	v_max_f32_e32 v111, 0, v111
	v_mul_f32_e32 v120, v120, v120
	v_mul_f32_e32 v121, v121, v121
	v_mul_f32_e32 v126, v126, v126
	v_mul_f32_e32 v122, v122, v122
	v_mul_f32_e32 v127, v127, v127
	v_mul_f32_e32 v123, v123, v123
	v_mul_f32_e32 v108, v108, v108
	v_mul_f32_e32 v109, v109, v109
	v_mul_f32_e32 v158, v105, v105
	v_mul_f32_e32 v167, v106, v106
	v_mul_f32_e32 v168, v107, v107
	v_cvt_pk_bf16_f32 v105, v126, v127
	v_cvt_pk_bf16_f32 v106, v120, v121
	v_cvt_pk_bf16_f32 v107, v122, v123
	global_store_dwordx4 v[144:145], v[104:107], off nt
	v_pk_mul_f32 v[116:117], v[116:117], v[162:163] op_sel_hi:[1,0]
	v_mul_f32_e32 v110, v110, v110
	v_cvt_pk_bf16_f32 v104, v108, v109
	v_mul_f32_e32 v111, v111, v111
	v_cvt_pk_bf16_f32 v105, v110, v111
	v_cvt_pk_bf16_f32 v106, v155, v158
	v_cvt_pk_bf16_f32 v107, v167, v168
	global_store_dwordx4 v[144:145], v[104:107], off offset:256 nt
	v_pk_mul_f32 v[118:119], v[118:119], v[162:163] op_sel_hi:[1,0]
	v_pk_mul_f32 v[114:115], v[114:115], v[162:163] op_sel_hi:[1,0]
	v_max_f32_e32 v104, 0, v112
	v_mul_f32_e32 v106, v104, v104
	v_max_f32_e32 v104, 0, v117
	v_max_f32_e32 v116, 0, v116
	v_max_f32_e32 v107, 0, v113
	v_mul_f32_e32 v104, v104, v104
	v_pk_mul_f32 v[98:99], v[98:99], v[162:163] op_sel_hi:[1,0]
	v_pk_mul_f32 v[96:97], v[96:97], v[162:163] op_sel_hi:[1,0]
	v_mul_f32_e32 v105, v116, v116
	v_mul_f32_e32 v107, v107, v107
	v_max_f32_e32 v108, 0, v118
	v_max_f32_e32 v109, 0, v114
	v_max_f32_e32 v110, 0, v119
	v_max_f32_e32 v111, 0, v115
	v_cvt_pk_bf16_f32 v104, v105, v104
	v_pk_mul_f32 v[102:103], v[102:103], v[162:163] op_sel_hi:[1,0]
	v_pk_mul_f32 v[100:101], v[100:101], v[162:163] op_sel_hi:[1,0]
	v_max_f32_e32 v96, 0, v96
	v_max_f32_e32 v97, 0, v97
	v_max_f32_e32 v98, 0, v98
	v_mul_f32_e32 v108, v108, v108
	v_mul_f32_e32 v109, v109, v109
	v_mul_f32_e32 v110, v110, v110
	v_mul_f32_e32 v111, v111, v111
	v_cvt_pk_bf16_f32 v105, v108, v110
	v_cvt_pk_bf16_f32 v106, v106, v107
	v_cvt_pk_bf16_f32 v107, v109, v111
	global_store_dwordx4 v[156:157], v[104:107], off nt
	v_max_f32_e32 v100, 0, v100
	v_max_f32_e32 v99, 0, v99
	v_mul_f32_e32 v104, v96, v96
	v_max_f32_e32 v96, 0, v101
	v_mul_f32_e32 v101, v97, v97
	v_max_f32_e32 v97, 0, v102
	v_mul_f32_e32 v102, v98, v98
	v_max_f32_e32 v98, 0, v103
	v_mul_f32_e32 v96, v96, v96
	v_mul_f32_e32 v97, v97, v97
	v_mul_f32_e32 v98, v98, v98
	v_mul_f32_e32 v100, v100, v100
	v_mul_f32_e32 v99, v99, v99
	v_cvt_pk_bf16_f32 v96, v100, v96
	v_cvt_pk_bf16_f32 v97, v97, v98
	v_cvt_pk_bf16_f32 v98, v104, v101
	v_cvt_pk_bf16_f32 v99, v102, v99
	global_store_dwordx4 v[156:157], v[96:99], off offset:256 nt
	v_cmp_gt_f32_e32 vcc, s57, v159
	s_mov_b64 s[0:1], 0x100000
	v_mul_f32_e32 v98, 0x4b800000, v159
	v_cndmask_b32_e32 v98, v159, v98, vcc
	v_rsq_f32_e32 v98, v98
	v_or_b32_e32 v96, 32, v146
	v_ashrrev_i32_e32 v97, 31, v96
	v_lshlrev_b64 v[96:97], 13, v[96:97]
	v_mul_f32_e32 v99, 0x45800000, v98
	v_cndmask_b32_e32 v98, v98, v99, vcc
	v_pk_mul_f32 v[88:89], v[88:89], v[98:99] op_sel_hi:[1,0]
	v_pk_mul_f32 v[92:93], v[92:93], v[98:99] op_sel_hi:[1,0]
	v_pk_mul_f32 v[90:91], v[90:91], v[98:99] op_sel_hi:[1,0]
	v_max_f32_e32 v88, 0, v88
	v_pk_mul_f32 v[94:95], v[94:95], v[98:99] op_sel_hi:[1,0]
	v_mul_f32_e32 v99, v88, v88
	v_max_f32_e32 v88, 0, v93
	v_max_f32_e32 v89, 0, v89
	v_max_f32_e32 v90, 0, v90
	v_lshl_add_u64 v[96:97], s[92:93], 0, v[96:97]
	v_max_f32_e32 v92, 0, v92
	v_mul_f32_e32 v88, v88, v88
	v_mul_f32_e32 v93, v89, v89
	v_max_f32_e32 v89, 0, v94
	v_mul_f32_e32 v94, v90, v90
	v_max_f32_e32 v90, 0, v95
	v_max_f32_e32 v91, 0, v91
	v_pk_mul_f32 v[82:83], v[82:83], v[98:99] op_sel_hi:[1,0]
	v_pk_mul_f32 v[80:81], v[80:81], v[98:99] op_sel_hi:[1,0]
	v_lshl_add_u64 v[96:97], v[96:97], 0, v[160:161]
	v_mul_f32_e32 v92, v92, v92
	v_mul_f32_e32 v89, v89, v89
	v_mul_f32_e32 v90, v90, v90
	v_mul_f32_e32 v91, v91, v91
	v_cvt_pk_bf16_f32 v88, v92, v88
	v_pk_mul_f32 v[86:87], v[86:87], v[98:99] op_sel_hi:[1,0]
	v_pk_mul_f32 v[84:85], v[84:85], v[98:99] op_sel_hi:[1,0]
	v_max_f32_e32 v80, 0, v80
	v_max_f32_e32 v81, 0, v81
	v_max_f32_e32 v82, 0, v82
	v_cvt_pk_bf16_f32 v89, v89, v90
	v_cvt_pk_bf16_f32 v90, v99, v93
	v_cvt_pk_bf16_f32 v91, v94, v91
	global_store_dwordx4 v[96:97], v[88:91], off nt
	v_max_f32_e32 v84, 0, v84
	v_max_f32_e32 v83, 0, v83
	v_mul_f32_e32 v88, v80, v80
	v_max_f32_e32 v80, 0, v85
	v_mul_f32_e32 v85, v81, v81
	v_max_f32_e32 v81, 0, v86
	v_mul_f32_e32 v86, v82, v82
	v_max_f32_e32 v82, 0, v87
	v_mul_f32_e32 v80, v80, v80
	v_mul_f32_e32 v81, v81, v81
	v_mul_f32_e32 v82, v82, v82
	v_mul_f32_e32 v84, v84, v84
	v_mul_f32_e32 v83, v83, v83
	v_cvt_pk_bf16_f32 v80, v84, v80
	v_cvt_pk_bf16_f32 v81, v81, v82
	v_cvt_pk_bf16_f32 v82, v88, v85
	v_cvt_pk_bf16_f32 v83, v86, v83
	global_store_dwordx4 v[96:97], v[80:83], off offset:256 nt
	v_cmp_gt_f32_e32 vcc, s57, v163
	s_nop 0
	v_mul_f32_e32 v82, 0x4b800000, v163
	v_cndmask_b32_e32 v82, v163, v82, vcc
	v_rsq_f32_e32 v82, v82
	v_or_b32_e32 v80, 48, v146
	v_ashrrev_i32_e32 v81, 31, v80
	v_lshlrev_b64 v[80:81], 13, v[80:81]
	v_mul_f32_e32 v83, 0x45800000, v82
	v_cndmask_b32_e32 v82, v82, v83, vcc
	v_pk_mul_f32 v[72:73], v[72:73], v[82:83] op_sel_hi:[1,0]
	v_pk_mul_f32 v[76:77], v[76:77], v[82:83] op_sel_hi:[1,0]
	v_pk_mul_f32 v[74:75], v[74:75], v[82:83] op_sel_hi:[1,0]
	v_max_f32_e32 v72, 0, v72
	v_pk_mul_f32 v[78:79], v[78:79], v[82:83] op_sel_hi:[1,0]
	v_mul_f32_e32 v83, v72, v72
	v_max_f32_e32 v72, 0, v77
	v_max_f32_e32 v73, 0, v73
	v_max_f32_e32 v74, 0, v74
	v_lshl_add_u64 v[80:81], s[92:93], 0, v[80:81]
	v_max_f32_e32 v76, 0, v76
	v_mul_f32_e32 v72, v72, v72
	v_mul_f32_e32 v77, v73, v73
	v_max_f32_e32 v73, 0, v78
	v_mul_f32_e32 v78, v74, v74
	v_max_f32_e32 v74, 0, v79
	v_max_f32_e32 v75, 0, v75
	v_pk_mul_f32 v[64:65], v[64:65], v[82:83] op_sel_hi:[1,0]
	v_lshl_add_u64 v[80:81], v[80:81], 0, v[160:161]
	v_mul_f32_e32 v76, v76, v76
	v_mul_f32_e32 v73, v73, v73
	v_mul_f32_e32 v74, v74, v74
	v_mul_f32_e32 v75, v75, v75
	v_cvt_pk_bf16_f32 v72, v76, v72
	v_pk_mul_f32 v[68:69], v[68:69], v[82:83] op_sel_hi:[1,0]
	v_max_f32_e32 v64, 0, v64
	v_cvt_pk_bf16_f32 v73, v73, v74
	v_cvt_pk_bf16_f32 v74, v83, v77
	v_cvt_pk_bf16_f32 v75, v78, v75
	global_store_dwordx4 v[80:81], v[72:75], off nt
	v_max_f32_e32 v68, 0, v68
	v_mul_f32_e32 v68, v68, v68
	v_mul_f32_e32 v72, v64, v64
	v_max_f32_e32 v64, 0, v69
	v_mul_f32_e32 v64, v64, v64
	v_cvt_pk_bf16_f32 v64, v68, v64
	v_mul_f32_e32 v68, 0x4b800000, v164
	v_cmp_gt_f32_e32 vcc, s57, v164
	v_pk_mul_f32 v[66:67], v[66:67], v[82:83] op_sel_hi:[1,0]
	v_pk_mul_f32 v[70:71], v[70:71], v[82:83] op_sel_hi:[1,0]
	v_cndmask_b32_e32 v68, v164, v68, vcc
	v_max_f32_e32 v65, 0, v65
	v_max_f32_e32 v66, 0, v66
	v_rsq_f32_e32 v68, v68
	v_mul_f32_e32 v69, v65, v65
	v_max_f32_e32 v65, 0, v70
	v_mul_f32_e32 v70, v66, v66
	v_max_f32_e32 v66, 0, v71
	v_mul_f32_e32 v65, v65, v65
	v_max_f32_e32 v67, 0, v67
	v_mul_f32_e32 v66, v66, v66
	v_mul_f32_e32 v67, v67, v67
	v_cvt_pk_bf16_f32 v65, v65, v66
	v_cvt_pk_bf16_f32 v66, v72, v69
	v_cvt_pk_bf16_f32 v67, v70, v67
	global_store_dwordx4 v[80:81], v[64:67], off offset:256 nt
	s_nop 1
	v_mul_f32_e32 v66, 0x45800000, v68
	v_cndmask_b32_e32 v66, v68, v66, vcc
	v_pk_mul_f32 v[56:57], v[56:57], v[66:67] op_sel_hi:[1,0]
	v_pk_mul_f32 v[60:61], v[60:61], v[66:67] op_sel_hi:[1,0]
	v_pk_mul_f32 v[58:59], v[58:59], v[66:67] op_sel_hi:[1,0]
	v_max_f32_e32 v56, 0, v56
	v_pk_mul_f32 v[62:63], v[62:63], v[66:67] op_sel_hi:[1,0]
	v_max_f32_e32 v60, 0, v60
	v_mul_f32_e32 v67, v56, v56
	v_max_f32_e32 v56, 0, v61
	v_max_f32_e32 v57, 0, v57
	v_max_f32_e32 v58, 0, v58
	v_mul_f32_e32 v60, v60, v60
	v_mul_f32_e32 v56, v56, v56
	v_mul_f32_e32 v61, v57, v57
	v_max_f32_e32 v57, 0, v62
	v_mul_f32_e32 v62, v58, v58
	v_max_f32_e32 v58, 0, v63
	v_mul_f32_e32 v57, v57, v57
	v_max_f32_e32 v59, 0, v59
	v_mul_f32_e32 v58, v58, v58
	v_cvt_pk_bf16_f32 v56, v60, v56
	v_add_co_u32_e32 v60, vcc, s58, v144
	v_pk_mul_f32 v[48:49], v[48:49], v[66:67] op_sel_hi:[1,0]
	v_mul_f32_e32 v59, v59, v59
	v_cvt_pk_bf16_f32 v57, v57, v58
	v_cvt_pk_bf16_f32 v58, v67, v61
	v_addc_co_u32_e32 v61, vcc, 0, v145, vcc
	v_pk_mul_f32 v[52:53], v[52:53], v[66:67] op_sel_hi:[1,0]
	v_max_f32_e32 v48, 0, v48
	v_cvt_pk_bf16_f32 v59, v62, v59
	global_store_dwordx4 v[60:61], v[56:59], off nt
	v_max_f32_e32 v52, 0, v52
	v_mul_f32_e32 v52, v52, v52
	v_mul_f32_e32 v56, v48, v48
	v_max_f32_e32 v48, 0, v53
	v_mul_f32_e32 v48, v48, v48
	v_cvt_pk_bf16_f32 v48, v52, v48
	v_mul_f32_e32 v52, 0x4b800000, v165
	v_cmp_gt_f32_e32 vcc, s57, v165
	v_pk_mul_f32 v[50:51], v[50:51], v[66:67] op_sel_hi:[1,0]
	v_pk_mul_f32 v[54:55], v[54:55], v[66:67] op_sel_hi:[1,0]
	v_cndmask_b32_e32 v52, v165, v52, vcc
	v_max_f32_e32 v49, 0, v49
	v_max_f32_e32 v50, 0, v50
	v_rsq_f32_e32 v52, v52
	v_mul_f32_e32 v53, v49, v49
	v_max_f32_e32 v49, 0, v54
	v_mul_f32_e32 v54, v50, v50
	v_max_f32_e32 v50, 0, v55
	v_mul_f32_e32 v49, v49, v49
	v_max_f32_e32 v51, 0, v51
	v_mul_f32_e32 v50, v50, v50
	v_lshl_add_u64 v[64:65], v[144:145], 0, s[0:1]
	v_mul_f32_e32 v51, v51, v51
	v_cvt_pk_bf16_f32 v49, v49, v50
	v_cvt_pk_bf16_f32 v50, v56, v53
	v_cvt_pk_bf16_f32 v51, v54, v51
	global_store_dwordx4 v[64:65], v[48:51], off offset:256 nt
	s_mov_b32 s1, s24
	s_mov_b32 s0, s26
	v_mul_f32_e32 v50, 0x45800000, v52
	v_cndmask_b32_e32 v50, v52, v50, vcc
	v_pk_mul_f32 v[40:41], v[40:41], v[50:51] op_sel_hi:[1,0]
	v_pk_mul_f32 v[44:45], v[44:45], v[50:51] op_sel_hi:[1,0]
	v_pk_mul_f32 v[42:43], v[42:43], v[50:51] op_sel_hi:[1,0]
	v_max_f32_e32 v40, 0, v40
	v_pk_mul_f32 v[46:47], v[46:47], v[50:51] op_sel_hi:[1,0]
	v_max_f32_e32 v44, 0, v44
	v_mul_f32_e32 v51, v40, v40
	v_max_f32_e32 v40, 0, v45
	v_max_f32_e32 v41, 0, v41
	v_max_f32_e32 v42, 0, v42
	v_mul_f32_e32 v44, v44, v44
	v_mul_f32_e32 v40, v40, v40
	v_mul_f32_e32 v45, v41, v41
	v_max_f32_e32 v41, 0, v46
	v_mul_f32_e32 v46, v42, v42
	v_max_f32_e32 v42, 0, v47
	v_mul_f32_e32 v41, v41, v41
	v_max_f32_e32 v43, 0, v43
	v_mul_f32_e32 v42, v42, v42
	v_cvt_pk_bf16_f32 v40, v44, v40
	v_add_co_u32_e32 v44, vcc, s59, v144
	v_pk_mul_f32 v[32:33], v[32:33], v[50:51] op_sel_hi:[1,0]
	v_mul_f32_e32 v43, v43, v43
	v_cvt_pk_bf16_f32 v41, v41, v42
	v_cvt_pk_bf16_f32 v42, v51, v45
	v_addc_co_u32_e32 v45, vcc, 0, v145, vcc
	v_pk_mul_f32 v[36:37], v[36:37], v[50:51] op_sel_hi:[1,0]
	v_max_f32_e32 v32, 0, v32
	v_cvt_pk_bf16_f32 v43, v46, v43
	global_store_dwordx4 v[44:45], v[40:43], off nt
	v_max_f32_e32 v36, 0, v36
	v_mul_f32_e32 v36, v36, v36
	v_mul_f32_e32 v40, v32, v32
	v_max_f32_e32 v32, 0, v37
	v_mul_f32_e32 v32, v32, v32
	v_cvt_pk_bf16_f32 v32, v36, v32
	v_mul_f32_e32 v36, 0x4b800000, v166
	v_cmp_gt_f32_e32 vcc, s57, v166
	v_pk_mul_f32 v[34:35], v[34:35], v[50:51] op_sel_hi:[1,0]
	v_pk_mul_f32 v[38:39], v[38:39], v[50:51] op_sel_hi:[1,0]
	v_cndmask_b32_e32 v36, v166, v36, vcc
	v_max_f32_e32 v33, 0, v33
	v_max_f32_e32 v34, 0, v34
	v_rsq_f32_e32 v36, v36
	v_mul_f32_e32 v37, v33, v33
	v_max_f32_e32 v33, 0, v38
	v_mul_f32_e32 v38, v34, v34
	v_max_f32_e32 v34, 0, v39
	v_mul_f32_e32 v33, v33, v33
	v_max_f32_e32 v35, 0, v35
	v_mul_f32_e32 v34, v34, v34
	v_lshl_add_u64 v[48:49], v[144:145], 0, s[18:19]
	v_mul_f32_e32 v35, v35, v35
	v_cvt_pk_bf16_f32 v33, v33, v34
	v_cvt_pk_bf16_f32 v34, v40, v37
	v_cvt_pk_bf16_f32 v35, v38, v35
	global_store_dwordx4 v[48:49], v[32:35], off offset:256 nt
	s_nop 1
	v_mul_f32_e32 v34, 0x45800000, v36
	v_cndmask_b32_e32 v34, v36, v34, vcc
	v_pk_mul_f32 v[24:25], v[24:25], v[34:35] op_sel_hi:[1,0]
	v_pk_mul_f32 v[28:29], v[28:29], v[34:35] op_sel_hi:[1,0]
	v_pk_mul_f32 v[26:27], v[26:27], v[34:35] op_sel_hi:[1,0]
	v_max_f32_e32 v24, 0, v24
	v_pk_mul_f32 v[30:31], v[30:31], v[34:35] op_sel_hi:[1,0]
	v_max_f32_e32 v28, 0, v28
	v_mul_f32_e32 v35, v24, v24
	v_max_f32_e32 v24, 0, v29
	v_max_f32_e32 v25, 0, v25
	v_max_f32_e32 v26, 0, v26
	v_mul_f32_e32 v28, v28, v28
	v_mul_f32_e32 v24, v24, v24
	v_mul_f32_e32 v29, v25, v25
	v_max_f32_e32 v25, 0, v30
	v_mul_f32_e32 v30, v26, v26
	v_max_f32_e32 v26, 0, v31
	v_mul_f32_e32 v25, v25, v25
	v_max_f32_e32 v27, 0, v27
	v_mul_f32_e32 v26, v26, v26
	v_cvt_pk_bf16_f32 v24, v28, v24
	v_add_co_u32_e32 v28, vcc, s60, v144
	v_pk_mul_f32 v[16:17], v[16:17], v[34:35] op_sel_hi:[1,0]
	v_mul_f32_e32 v27, v27, v27
	v_cvt_pk_bf16_f32 v25, v25, v26
	v_cvt_pk_bf16_f32 v26, v35, v29
	v_addc_co_u32_e32 v29, vcc, 0, v145, vcc
	v_pk_mul_f32 v[20:21], v[20:21], v[34:35] op_sel_hi:[1,0]
	v_max_f32_e32 v16, 0, v16
	v_cvt_pk_bf16_f32 v27, v30, v27
	global_store_dwordx4 v[28:29], v[24:27], off nt
	v_max_f32_e32 v20, 0, v20
	v_mul_f32_e32 v20, v20, v20
	v_mul_f32_e32 v24, v16, v16
	v_max_f32_e32 v16, 0, v21
	v_mul_f32_e32 v16, v16, v16
	v_cvt_pk_bf16_f32 v16, v20, v16
	v_mul_f32_e32 v20, 0x4b800000, v147
	v_cmp_gt_f32_e32 vcc, s57, v147
	v_pk_mul_f32 v[18:19], v[18:19], v[34:35] op_sel_hi:[1,0]
	v_pk_mul_f32 v[22:23], v[22:23], v[34:35] op_sel_hi:[1,0]
	v_cndmask_b32_e32 v20, v147, v20, vcc
	v_max_f32_e32 v17, 0, v17
	v_max_f32_e32 v18, 0, v18
	v_rsq_f32_e32 v20, v20
	v_mul_f32_e32 v21, v17, v17
	v_max_f32_e32 v17, 0, v22
	v_mul_f32_e32 v22, v18, v18
	v_max_f32_e32 v18, 0, v23
	v_mul_f32_e32 v17, v17, v17
	v_max_f32_e32 v19, 0, v19
	v_mul_f32_e32 v18, v18, v18
	v_lshl_add_u64 v[32:33], v[144:145], 0, s[20:21]
	v_mul_f32_e32 v19, v19, v19
	v_cvt_pk_bf16_f32 v17, v17, v18
	v_cvt_pk_bf16_f32 v18, v24, v21
	v_cvt_pk_bf16_f32 v19, v22, v19
	global_store_dwordx4 v[32:33], v[16:19], off offset:256 nt
	s_nop 1
	v_mul_f32_e32 v18, 0x45800000, v20
	v_cndmask_b32_e32 v18, v20, v18, vcc
	v_pk_mul_f32 v[8:9], v[8:9], v[18:19] op_sel_hi:[1,0]
	v_pk_mul_f32 v[12:13], v[12:13], v[18:19] op_sel_hi:[1,0]
	v_pk_mul_f32 v[10:11], v[10:11], v[18:19] op_sel_hi:[1,0]
	v_max_f32_e32 v8, 0, v8
	v_pk_mul_f32 v[14:15], v[14:15], v[18:19] op_sel_hi:[1,0]
	v_max_f32_e32 v12, 0, v12
	v_mul_f32_e32 v19, v8, v8
	v_max_f32_e32 v8, 0, v13
	v_max_f32_e32 v9, 0, v9
	v_max_f32_e32 v10, 0, v10
	v_mul_f32_e32 v12, v12, v12
	v_mul_f32_e32 v8, v8, v8
	v_mul_f32_e32 v13, v9, v9
	v_max_f32_e32 v9, 0, v14
	v_mul_f32_e32 v14, v10, v10
	v_max_f32_e32 v10, 0, v15
	v_mul_f32_e32 v9, v9, v9
	v_max_f32_e32 v11, 0, v11
	v_mul_f32_e32 v10, v10, v10
	v_cvt_pk_bf16_f32 v8, v12, v8
	v_add_co_u32_e32 v12, vcc, s61, v144
	v_pk_mul_f32 v[2:3], v[2:3], v[18:19] op_sel_hi:[1,0]
	v_pk_mul_f32 v[0:1], v[0:1], v[18:19] op_sel_hi:[1,0]
	v_mul_f32_e32 v11, v11, v11
	v_cvt_pk_bf16_f32 v9, v9, v10
	v_cvt_pk_bf16_f32 v10, v19, v13
	v_addc_co_u32_e32 v13, vcc, 0, v145, vcc
	v_pk_mul_f32 v[6:7], v[6:7], v[18:19] op_sel_hi:[1,0]
	v_pk_mul_f32 v[4:5], v[4:5], v[18:19] op_sel_hi:[1,0]
	v_max_f32_e32 v0, 0, v0
	v_max_f32_e32 v1, 0, v1
	v_max_f32_e32 v2, 0, v2
	v_cvt_pk_bf16_f32 v11, v14, v11
	global_store_dwordx4 v[12:13], v[8:11], off nt
	v_max_f32_e32 v3, 0, v3
	v_lshl_add_u64 v[16:17], v[144:145], 0, s[22:23]
	v_mul_f32_e32 v8, v0, v0
	v_max_f32_e32 v0, 0, v5
	v_mul_f32_e32 v5, v1, v1
	v_max_f32_e32 v1, 0, v6
	v_mul_f32_e32 v6, v2, v2
	v_max_f32_e32 v2, 0, v7
	v_max_f32_e32 v4, 0, v4
	v_mul_f32_e32 v0, v0, v0
	v_mul_f32_e32 v1, v1, v1
	v_mul_f32_e32 v2, v2, v2
	v_mul_f32_e32 v3, v3, v3
	s_and_b64 vcc, exec, s[6:7]
	v_mul_f32_e32 v4, v4, v4
	v_cvt_pk_bf16_f32 v0, v4, v0
	v_cvt_pk_bf16_f32 v1, v1, v2
	v_cvt_pk_bf16_f32 v2, v8, v5
	v_cvt_pk_bf16_f32 v3, v6, v3
	global_store_dwordx4 v[16:17], v[0:3], off offset:256 nt
	s_cbranch_vccz .LBB0_843
	s_waitcnt vmcnt(0)
	s_cmpk_gt_u32 s33, 0xff
	s_cbranch_scc1 .LBB0_854
	s_barrier

.LBB0_945:
	s_ashr_i32 s23, s22, 31
	v_cmp_lt_i64_e32 vcc, s[24:25], v[140:141]
	s_lshl_b64 s[24:25], s[22:23], 19
	s_add_u32 s24, s10, s24
	s_addc_u32 s25, s11, s25
	s_and_b64 s[26:27], vcc, exec
	s_cselect_b32 s23, s25, s3
	s_cselect_b32 s54, s24, s2
	s_ashr_i32 s21, s20, 31
	s_lshl_b64 s[26:27], s[20:21], 19
	v_readlane_b32 s30, v253, 53
	v_readlane_b32 s31, v253, 54
	s_add_u32 s26, s30, s26
	s_addc_u32 s27, s31, s27
	s_and_b64 s[30:31], vcc, exec
	s_cselect_b32 s21, s27, s29
	s_cselect_b32 s55, s26, s28
	s_add_u32 s2, s2, 0x40080
	s_addc_u32 s3, s3, 0
	s_add_u32 s56, s28, 0x100
	v_lshl_add_u32 v240, s0, 8, v150
	v_ashrrev_i32_e32 v241, 31, v240
	v_lshl_add_u64 v[240:241], v[240:241], 2, s[18:19]
	global_load_dword v242, v[240:241], off
	global_load_dword v243, v[240:241], off offset:64
	global_load_dword v244, v[240:241], off offset:128
	global_load_dword v245, v[240:241], off offset:192
	global_load_dword v246, v[240:241], off offset:512
	global_load_dword v247, v[240:241], off offset:576
	global_load_dword v248, v[240:241], off offset:640
	global_load_dword v249, v[240:241], off offset:704
	v_mov_b32_e32 v0, 0
	s_addc_u32 s57, s29, 0
	s_mov_b32 s58, -2
	v_mov_b32_e32 v1, v0
	v_mov_b64_e32 v[2:3], v[0:1]
	v_mov_b64_e32 v[4:5], v[0:1]
	v_mov_b64_e32 v[6:7], v[0:1]
	v_mov_b64_e32 v[8:9], v[0:1]
	v_mov_b64_e32 v[10:11], v[0:1]
	v_mov_b64_e32 v[12:13], v[0:1]
	v_mov_b64_e32 v[14:15], v[0:1]
	v_mov_b64_e32 v[16:17], v[0:1]
	v_mov_b64_e32 v[18:19], v[0:1]
	v_mov_b64_e32 v[20:21], v[0:1]
	v_mov_b64_e32 v[22:23], v[0:1]
	v_mov_b64_e32 v[24:25], v[0:1]
	v_mov_b64_e32 v[26:27], v[0:1]
	v_mov_b64_e32 v[28:29], v[0:1]
	v_mov_b64_e32 v[30:31], v[0:1]
	v_mov_b64_e32 v[32:33], v[0:1]
	v_mov_b64_e32 v[34:35], v[0:1]
	v_mov_b64_e32 v[36:37], v[0:1]
	v_mov_b64_e32 v[38:39], v[0:1]
	v_mov_b64_e32 v[40:41], v[0:1]
	v_mov_b64_e32 v[42:43], v[0:1]
	v_mov_b64_e32 v[44:45], v[0:1]
	v_mov_b64_e32 v[46:47], v[0:1]
	v_mov_b64_e32 v[48:49], v[0:1]
	v_mov_b64_e32 v[50:51], v[0:1]
	v_mov_b64_e32 v[52:53], v[0:1]
	v_mov_b64_e32 v[54:55], v[0:1]
	v_mov_b64_e32 v[56:57], v[0:1]
	v_mov_b64_e32 v[58:59], v[0:1]
	v_mov_b64_e32 v[60:61], v[0:1]
	v_mov_b64_e32 v[62:63], v[0:1]
	v_mov_b64_e32 v[64:65], v[0:1]
	v_mov_b64_e32 v[66:67], v[0:1]
	v_mov_b64_e32 v[68:69], v[0:1]
	v_mov_b64_e32 v[70:71], v[0:1]
	v_mov_b64_e32 v[72:73], v[0:1]
	v_mov_b64_e32 v[74:75], v[0:1]
	v_mov_b64_e32 v[76:77], v[0:1]
	v_mov_b64_e32 v[78:79], v[0:1]
	v_mov_b64_e32 v[80:81], v[0:1]
	v_mov_b64_e32 v[82:83], v[0:1]
	v_mov_b64_e32 v[84:85], v[0:1]
	v_mov_b64_e32 v[86:87], v[0:1]
	v_mov_b64_e32 v[88:89], v[0:1]
	v_mov_b64_e32 v[90:91], v[0:1]
	v_mov_b64_e32 v[92:93], v[0:1]
	v_mov_b64_e32 v[94:95], v[0:1]
	v_mov_b64_e32 v[96:97], v[0:1]
	v_mov_b64_e32 v[98:99], v[0:1]
	v_mov_b64_e32 v[100:101], v[0:1]
	v_mov_b64_e32 v[102:103], v[0:1]
	v_mov_b64_e32 v[104:105], v[0:1]
	v_mov_b64_e32 v[106:107], v[0:1]
	v_mov_b64_e32 v[108:109], v[0:1]
	v_mov_b64_e32 v[110:111], v[0:1]
	v_mov_b64_e32 v[112:113], v[0:1]
	v_mov_b64_e32 v[114:115], v[0:1]
	v_mov_b64_e32 v[116:117], v[0:1]
	v_mov_b64_e32 v[118:119], v[0:1]
	v_mov_b64_e32 v[120:121], v[0:1]
	v_mov_b64_e32 v[122:123], v[0:1]
	v_mov_b64_e32 v[124:125], v[0:1]
	v_mov_b64_e32 v[126:127], v[0:1]
.LBB0_946:
	ds_read_b128 v[144:147], v153
	ds_read_b128 v[158:161], v153 offset:1024
	ds_read_b128 v[162:165], v153 offset:2048
	ds_read_b128 v[166:169], v153 offset:3072
	s_add_u32 s28, s2, 0xfffc0080
	s_addc_u32 s29, s3, -1
	s_cmp_eq_u32 s58, 12
	s_cselect_b32 s31, s23, s29
	s_cselect_b32 s30, s54, s28
	s_cselect_b32 s29, s21, s57
	s_cselect_b32 s28, s55, s56
	v_lshl_add_u64 v[148:149], s[2:3], 0, v[136:137]
	s_add_i32 m0, s37, 0xc000
	ds_read_b128 v[170:173], v154
	ds_read_b128 v[176:179], v154 offset:1024
	ds_read_b128 v[180:183], v154 offset:2048
	ds_read_b128 v[184:187], v154 offset:3072
	ds_read_b128 v[188:191], v154 offset:4096
	ds_read_b128 v[192:195], v154 offset:5120
	ds_read_b128 v[196:199], v154 offset:6144
	ds_read_b128 v[200:203], v154 offset:7168
	global_load_lds_dwordx4 v[148:149], off
	s_add_i32 m0, s37, 0xe000
	v_lshl_add_u64 v[148:149], s[2:3], 0, v[138:139]
	global_load_lds_dwordx4 v[148:149], off
	s_waitcnt lgkmcnt(8)
	s_setprio 1
	s_barrier
	s_waitcnt lgkmcnt(0)
	v_mfma_f32_16x16x32_bf16 v[124:127], v[144:147], v[170:173], v[124:127]
	v_mfma_f32_16x16x32_bf16 v[120:123], v[162:165], v[170:173], v[120:123]
	v_mfma_f32_16x16x32_bf16 v[116:119], v[144:147], v[180:183], v[116:119]
	v_mfma_f32_16x16x32_bf16 v[112:115], v[162:165], v[180:183], v[112:115]
	v_mfma_f32_16x16x32_bf16 v[104:107], v[144:147], v[188:191], v[104:107]
	v_mfma_f32_16x16x32_bf16 v[96:99], v[162:165], v[188:191], v[96:99]
	v_mfma_f32_16x16x32_bf16 v[76:79], v[144:147], v[196:199], v[76:79]
	v_mfma_f32_16x16x32_bf16 v[72:75], v[162:165], v[196:199], v[72:75]
	v_mfma_f32_16x16x32_bf16 v[124:127], v[158:161], v[176:179], v[124:127]
	v_mfma_f32_16x16x32_bf16 v[120:123], v[166:169], v[176:179], v[120:123]
	v_mfma_f32_16x16x32_bf16 v[116:119], v[158:161], v[184:187], v[116:119]
	v_mfma_f32_16x16x32_bf16 v[112:115], v[166:169], v[184:187], v[112:115]
	v_mfma_f32_16x16x32_bf16 v[104:107], v[158:161], v[192:195], v[104:107]
	v_mfma_f32_16x16x32_bf16 v[96:99], v[166:169], v[192:195], v[96:99]
	v_mfma_f32_16x16x32_bf16 v[76:79], v[158:161], v[200:203], v[76:79]
	v_mfma_f32_16x16x32_bf16 v[72:75], v[166:169], v[200:203], v[72:75]
	s_barrier
	s_setprio 0
	s_add_i32 s59, s50, s34
	v_lshl_add_u64 v[148:149], s[28:29], 0, v[132:133]
	s_mov_b32 m0, s59
	ds_read_b128 v[204:207], v155
	ds_read_b128 v[212:215], v155 offset:1024
	ds_read_b128 v[216:219], v155 offset:2048
	ds_read_b128 v[220:223], v155 offset:3072
	global_load_lds_dwordx4 v[148:149], off
	s_add_i32 m0, s59, 0x2000
	v_lshl_add_u64 v[208:209], s[28:29], 0, v[128:129]
	global_load_lds_dwordx4 v[208:209], off
	s_setprio 1
	s_barrier
	s_waitcnt lgkmcnt(0)
	v_mfma_f32_16x16x32_bf16 v[108:111], v[204:207], v[170:173], v[108:111]
	v_mfma_f32_16x16x32_bf16 v[100:103], v[216:219], v[170:173], v[100:103]
	v_mfma_f32_16x16x32_bf16 v[92:95], v[204:207], v[180:183], v[92:95]
	v_mfma_f32_16x16x32_bf16 v[88:91], v[216:219], v[180:183], v[88:91]
	v_mfma_f32_16x16x32_bf16 v[84:87], v[204:207], v[188:191], v[84:87]
	v_mfma_f32_16x16x32_bf16 v[80:83], v[216:219], v[188:191], v[80:83]
	v_mfma_f32_16x16x32_bf16 v[68:71], v[204:207], v[196:199], v[68:71]
	v_mfma_f32_16x16x32_bf16 v[64:67], v[216:219], v[196:199], v[64:67]
	v_mfma_f32_16x16x32_bf16 v[108:111], v[212:215], v[176:179], v[108:111]
	v_mfma_f32_16x16x32_bf16 v[100:103], v[220:223], v[176:179], v[100:103]
	v_mfma_f32_16x16x32_bf16 v[92:95], v[212:215], v[184:187], v[92:95]
	v_mfma_f32_16x16x32_bf16 v[88:91], v[220:223], v[184:187], v[88:91]
	v_mfma_f32_16x16x32_bf16 v[84:87], v[212:215], v[192:195], v[84:87]
	v_mfma_f32_16x16x32_bf16 v[80:83], v[220:223], v[192:195], v[80:83]
	v_mfma_f32_16x16x32_bf16 v[68:71], v[212:215], v[200:203], v[68:71]
	v_mfma_f32_16x16x32_bf16 v[64:67], v[220:223], v[200:203], v[64:67]
	s_barrier
	s_setprio 0
	s_mov_b32 m0, s37
	v_lshl_add_u64 v[224:225], s[30:31], 0, v[134:135]
	ds_read_b128 v[170:173], v154 offset:16384
	ds_read_b128 v[176:179], v154 offset:17408
	ds_read_b128 v[180:183], v154 offset:18432
	ds_read_b128 v[184:187], v154 offset:19456
	ds_read_b128 v[188:191], v154 offset:20480
	ds_read_b128 v[192:195], v154 offset:21504
	ds_read_b128 v[196:199], v154 offset:22528
	ds_read_b128 v[200:203], v154 offset:23552
	global_load_lds_dwordx4 v[224:225], off
	s_mov_b32 m0, s38
	v_lshl_add_u64 v[226:227], s[30:31], 0, v[130:131]
	global_load_lds_dwordx4 v[226:227], off
	s_setprio 1
	s_barrier
	s_waitcnt lgkmcnt(0)
	v_mfma_f32_16x16x32_bf16 v[60:63], v[144:147], v[170:173], v[60:63]
	v_mfma_f32_16x16x32_bf16 v[56:59], v[162:165], v[170:173], v[56:59]
	v_mfma_f32_16x16x32_bf16 v[44:47], v[144:147], v[180:183], v[44:47]
	v_mfma_f32_16x16x32_bf16 v[40:43], v[162:165], v[180:183], v[40:43]
	v_mfma_f32_16x16x32_bf16 v[28:31], v[144:147], v[188:191], v[28:31]
	v_mfma_f32_16x16x32_bf16 v[24:27], v[162:165], v[188:191], v[24:27]
	v_mfma_f32_16x16x32_bf16 v[12:15], v[144:147], v[196:199], v[12:15]
	v_mfma_f32_16x16x32_bf16 v[8:11], v[162:165], v[196:199], v[8:11]
	v_mfma_f32_16x16x32_bf16 v[60:63], v[158:161], v[176:179], v[60:63]
	v_mfma_f32_16x16x32_bf16 v[56:59], v[166:169], v[176:179], v[56:59]
	v_mfma_f32_16x16x32_bf16 v[44:47], v[158:161], v[184:187], v[44:47]
	v_mfma_f32_16x16x32_bf16 v[40:43], v[166:169], v[184:187], v[40:43]
	v_mfma_f32_16x16x32_bf16 v[28:31], v[158:161], v[192:195], v[28:31]
	v_mfma_f32_16x16x32_bf16 v[24:27], v[166:169], v[192:195], v[24:27]
	v_mfma_f32_16x16x32_bf16 v[12:15], v[158:161], v[200:203], v[12:15]
	v_mfma_f32_16x16x32_bf16 v[8:11], v[166:169], v[200:203], v[8:11]
	s_barrier
	s_setprio 0
	s_add_u32 s60, s28, 0x40000
	s_addc_u32 s61, s29, 0
	s_add_i32 s59, s51, s34
	s_mov_b32 m0, s59
	v_lshl_add_u64 v[144:145], s[60:61], 0, v[132:133]
	global_load_lds_dwordx4 v[144:145], off
	s_add_i32 m0, s59, 0x2000
	v_lshl_add_u64 v[144:145], s[60:61], 0, v[128:129]
	global_load_lds_dwordx4 v[144:145], off
	s_waitcnt vmcnt(6)
	s_setprio 1
	s_barrier
	v_mfma_f32_16x16x32_bf16 v[52:55], v[204:207], v[170:173], v[52:55]
	v_mfma_f32_16x16x32_bf16 v[48:51], v[216:219], v[170:173], v[48:51]
	v_mfma_f32_16x16x32_bf16 v[36:39], v[204:207], v[180:183], v[36:39]
	v_mfma_f32_16x16x32_bf16 v[32:35], v[216:219], v[180:183], v[32:35]
	v_mfma_f32_16x16x32_bf16 v[20:23], v[204:207], v[188:191], v[20:23]
	v_mfma_f32_16x16x32_bf16 v[16:19], v[216:219], v[188:191], v[16:19]
	v_mfma_f32_16x16x32_bf16 v[4:7], v[204:207], v[196:199], v[4:7]
	v_mfma_f32_16x16x32_bf16 v[0:3], v[216:219], v[196:199], v[0:3]
	v_mfma_f32_16x16x32_bf16 v[52:55], v[212:215], v[176:179], v[52:55]
	v_mfma_f32_16x16x32_bf16 v[48:51], v[220:223], v[176:179], v[48:51]
	v_mfma_f32_16x16x32_bf16 v[36:39], v[212:215], v[184:187], v[36:39]
	v_mfma_f32_16x16x32_bf16 v[32:35], v[220:223], v[184:187], v[32:35]
	v_mfma_f32_16x16x32_bf16 v[20:23], v[212:215], v[192:195], v[20:23]
	v_mfma_f32_16x16x32_bf16 v[16:19], v[220:223], v[192:195], v[16:19]
	v_mfma_f32_16x16x32_bf16 v[4:7], v[212:215], v[200:203], v[4:7]
	v_mfma_f32_16x16x32_bf16 v[0:3], v[220:223], v[200:203], v[0:3]
	s_barrier
	s_setprio 0
	s_add_i32 s59, 0, 0x18000
	v_add_u32_e32 v157, s59, v151
	ds_read_b128 v[144:147], v157
	ds_read_b128 v[158:161], v157 offset:1024
	ds_read_b128 v[162:165], v157 offset:2048
	ds_read_b128 v[166:169], v157 offset:3072
	s_add_u32 s30, s30, 0x40000
	s_addc_u32 s31, s31, 0
	s_mov_b32 m0, s39
	v_lshl_add_u64 v[204:205], s[30:31], 0, v[134:135]
	ds_read_b128 v[170:173], v154 offset:32768
	ds_read_b128 v[176:179], v154 offset:33792
	ds_read_b128 v[180:183], v154 offset:34816
	ds_read_b128 v[184:187], v154 offset:35840
	ds_read_b128 v[188:191], v154 offset:36864
	ds_read_b128 v[192:195], v154 offset:37888
	ds_read_b128 v[196:199], v154 offset:38912
	ds_read_b128 v[200:203], v154 offset:39936
	global_load_lds_dwordx4 v[204:205], off
	s_mov_b32 m0, s40
	v_lshl_add_u64 v[204:205], s[30:31], 0, v[130:131]
	global_load_lds_dwordx4 v[204:205], off
	s_waitcnt lgkmcnt(8)
	s_setprio 1
	s_barrier
	s_waitcnt lgkmcnt(0)
	v_mfma_f32_16x16x32_bf16 v[124:127], v[144:147], v[170:173], v[124:127]
	v_mfma_f32_16x16x32_bf16 v[120:123], v[162:165], v[170:173], v[120:123]
	v_mfma_f32_16x16x32_bf16 v[116:119], v[144:147], v[180:183], v[116:119]
	v_mfma_f32_16x16x32_bf16 v[112:115], v[162:165], v[180:183], v[112:115]
	v_mfma_f32_16x16x32_bf16 v[104:107], v[144:147], v[188:191], v[104:107]
	v_mfma_f32_16x16x32_bf16 v[96:99], v[162:165], v[188:191], v[96:99]
	v_mfma_f32_16x16x32_bf16 v[76:79], v[144:147], v[196:199], v[76:79]
	v_mfma_f32_16x16x32_bf16 v[72:75], v[162:165], v[196:199], v[72:75]
	v_mfma_f32_16x16x32_bf16 v[124:127], v[158:161], v[176:179], v[124:127]
	v_mfma_f32_16x16x32_bf16 v[120:123], v[166:169], v[176:179], v[120:123]
	v_mfma_f32_16x16x32_bf16 v[116:119], v[158:161], v[184:187], v[116:119]
	v_mfma_f32_16x16x32_bf16 v[112:115], v[166:169], v[184:187], v[112:115]
	v_mfma_f32_16x16x32_bf16 v[104:107], v[158:161], v[192:195], v[104:107]
	v_mfma_f32_16x16x32_bf16 v[96:99], v[166:169], v[192:195], v[96:99]
	v_mfma_f32_16x16x32_bf16 v[76:79], v[158:161], v[200:203], v[76:79]
	v_mfma_f32_16x16x32_bf16 v[72:75], v[166:169], v[200:203], v[72:75]
	s_barrier
	s_setprio 0
	s_add_i32 s30, 0, 0x1c000
	s_add_i32 s31, s59, s34
	v_add_u32_e32 v157, s30, v151
	v_lshl_add_u64 v[148:149], v[148:149], 0, s[8:9]
	s_mov_b32 m0, s31
	ds_read_b128 v[204:207], v157
	ds_read_b128 v[212:215], v157 offset:1024
	ds_read_b128 v[216:219], v157 offset:2048
	ds_read_b128 v[220:223], v157 offset:3072
	global_load_lds_dwordx4 v[148:149], off
	s_add_i32 m0, s31, 0x2000
	v_lshl_add_u64 v[148:149], v[208:209], 0, s[8:9]
	global_load_lds_dwordx4 v[148:149], off
	s_setprio 1
	s_barrier
	s_waitcnt lgkmcnt(0)
	v_mfma_f32_16x16x32_bf16 v[108:111], v[204:207], v[170:173], v[108:111]
	v_mfma_f32_16x16x32_bf16 v[100:103], v[216:219], v[170:173], v[100:103]
	v_mfma_f32_16x16x32_bf16 v[92:95], v[204:207], v[180:183], v[92:95]
	v_mfma_f32_16x16x32_bf16 v[88:91], v[216:219], v[180:183], v[88:91]
	v_mfma_f32_16x16x32_bf16 v[84:87], v[204:207], v[188:191], v[84:87]
	v_mfma_f32_16x16x32_bf16 v[80:83], v[216:219], v[188:191], v[80:83]
	v_mfma_f32_16x16x32_bf16 v[68:71], v[204:207], v[196:199], v[68:71]
	v_mfma_f32_16x16x32_bf16 v[64:67], v[216:219], v[196:199], v[64:67]
	v_mfma_f32_16x16x32_bf16 v[108:111], v[212:215], v[176:179], v[108:111]
	v_mfma_f32_16x16x32_bf16 v[100:103], v[220:223], v[176:179], v[100:103]
	v_mfma_f32_16x16x32_bf16 v[92:95], v[212:215], v[184:187], v[92:95]
	v_mfma_f32_16x16x32_bf16 v[88:91], v[220:223], v[184:187], v[88:91]
	v_mfma_f32_16x16x32_bf16 v[84:87], v[212:215], v[192:195], v[84:87]
	v_mfma_f32_16x16x32_bf16 v[80:83], v[220:223], v[192:195], v[80:83]
	v_mfma_f32_16x16x32_bf16 v[68:71], v[212:215], v[200:203], v[68:71]
	v_mfma_f32_16x16x32_bf16 v[64:67], v[220:223], v[200:203], v[64:67]
	s_barrier
	s_setprio 0
	s_mov_b32 m0, s42
	v_lshl_add_u64 v[148:149], v[224:225], 0, s[8:9]
	ds_read_b128 v[170:173], v154 offset:49152
	ds_read_b128 v[176:179], v154 offset:50176
	ds_read_b128 v[180:183], v154 offset:51200
	ds_read_b128 v[184:187], v154 offset:52224
	ds_read_b128 v[188:191], v154 offset:53248
	ds_read_b128 v[192:195], v154 offset:54272
	ds_read_b128 v[196:199], v154 offset:55296
	ds_read_b128 v[200:203], v154 offset:56320
	global_load_lds_dwordx4 v[148:149], off
	s_mov_b32 m0, s43
	v_lshl_add_u64 v[148:149], v[226:227], 0, s[8:9]
	global_load_lds_dwordx4 v[148:149], off
	s_setprio 1
	s_barrier
	s_waitcnt lgkmcnt(0)
	v_mfma_f32_16x16x32_bf16 v[60:63], v[144:147], v[170:173], v[60:63]
	v_mfma_f32_16x16x32_bf16 v[56:59], v[162:165], v[170:173], v[56:59]
	v_mfma_f32_16x16x32_bf16 v[44:47], v[144:147], v[180:183], v[44:47]
	v_mfma_f32_16x16x32_bf16 v[40:43], v[162:165], v[180:183], v[40:43]
	v_mfma_f32_16x16x32_bf16 v[28:31], v[144:147], v[188:191], v[28:31]
	v_mfma_f32_16x16x32_bf16 v[24:27], v[162:165], v[188:191], v[24:27]
	v_mfma_f32_16x16x32_bf16 v[12:15], v[144:147], v[196:199], v[12:15]
	v_mfma_f32_16x16x32_bf16 v[8:11], v[162:165], v[196:199], v[8:11]
	v_mfma_f32_16x16x32_bf16 v[60:63], v[158:161], v[176:179], v[60:63]
	v_mfma_f32_16x16x32_bf16 v[56:59], v[166:169], v[176:179], v[56:59]
	v_mfma_f32_16x16x32_bf16 v[44:47], v[158:161], v[184:187], v[44:47]
	v_mfma_f32_16x16x32_bf16 v[40:43], v[166:169], v[184:187], v[40:43]
	v_mfma_f32_16x16x32_bf16 v[28:31], v[158:161], v[192:195], v[28:31]
	v_mfma_f32_16x16x32_bf16 v[24:27], v[166:169], v[192:195], v[24:27]
	v_mfma_f32_16x16x32_bf16 v[12:15], v[158:161], v[200:203], v[12:15]
	v_mfma_f32_16x16x32_bf16 v[8:11], v[166:169], v[200:203], v[8:11]
	s_barrier
	s_setprio 0
	s_add_u32 s28, s28, 0x40080
	s_addc_u32 s29, s29, 0
	s_add_i32 s30, s30, s34
	s_mov_b32 m0, s30
	v_lshl_add_u64 v[144:145], s[28:29], 0, v[132:133]
	global_load_lds_dwordx4 v[144:145], off
	s_add_i32 m0, s30, 0x2000
	v_lshl_add_u64 v[144:145], s[28:29], 0, v[128:129]
	global_load_lds_dwordx4 v[144:145], off
	s_waitcnt vmcnt(6)
	s_setprio 1
	s_barrier
	v_mfma_f32_16x16x32_bf16 v[52:55], v[204:207], v[170:173], v[52:55]
	v_mfma_f32_16x16x32_bf16 v[48:51], v[216:219], v[170:173], v[48:51]
	v_mfma_f32_16x16x32_bf16 v[36:39], v[204:207], v[180:183], v[36:39]
	v_mfma_f32_16x16x32_bf16 v[32:35], v[216:219], v[180:183], v[32:35]
	v_mfma_f32_16x16x32_bf16 v[20:23], v[204:207], v[188:191], v[20:23]
	v_mfma_f32_16x16x32_bf16 v[16:19], v[216:219], v[188:191], v[16:19]
	v_mfma_f32_16x16x32_bf16 v[4:7], v[204:207], v[196:199], v[4:7]
	v_mfma_f32_16x16x32_bf16 v[0:3], v[216:219], v[196:199], v[0:3]
	v_mfma_f32_16x16x32_bf16 v[52:55], v[212:215], v[176:179], v[52:55]
	v_mfma_f32_16x16x32_bf16 v[48:51], v[220:223], v[176:179], v[48:51]
	v_mfma_f32_16x16x32_bf16 v[36:39], v[212:215], v[184:187], v[36:39]
	v_mfma_f32_16x16x32_bf16 v[32:35], v[220:223], v[184:187], v[32:35]
	v_mfma_f32_16x16x32_bf16 v[20:23], v[212:215], v[192:195], v[20:23]
	v_mfma_f32_16x16x32_bf16 v[16:19], v[220:223], v[192:195], v[16:19]
	v_mfma_f32_16x16x32_bf16 v[4:7], v[212:215], v[200:203], v[4:7]
	v_mfma_f32_16x16x32_bf16 v[0:3], v[220:223], v[200:203], v[0:3]
	s_barrier
	s_setprio 0
	s_add_i32 s58, s58, 2
	s_add_u32 s2, s2, 0x100
	s_addc_u32 s3, s3, 0
	s_add_u32 s56, s56, 0x100
	s_addc_u32 s57, s57, 0
	s_cmp_gt_u32 s58, 13
	s_cbranch_scc0 .LBB0_946
	v_lshl_add_u32 v144, s0, 8, v150
	v_ashrrev_i32_e32 v145, 31, v144
	v_mov_b32_e32 v145, v242
	v_mov_b32_e32 v157, v243
	v_mov_b32_e32 v164, v244
	v_mov_b32_e32 v165, v245
	v_mov_b32_e32 v166, v246
	v_mov_b32_e32 v167, v247
	v_mov_b32_e32 v168, v248
	v_mov_b32_e32 v169, v249
	v_mov_b64_e32 v[146:147], s[92:93]
	v_or_b32_e32 v160, 16, v144
	v_or_b32_e32 v162, 32, v144
	v_lshl_or_b32 v148, s1, 8, v152
	v_mad_i64_i32 v[158:159], s[0:1], v144, s52, v[146:147]
	v_mad_i64_i32 v[160:161], s[0:1], v160, s52, v[146:147]
	v_mad_i64_i32 v[162:163], s[0:1], v162, s52, v[146:147]
	v_ashrrev_i32_e32 v149, 31, v148
	v_lshlrev_b64 v[148:149], 1, v[148:149]
	v_lshl_add_u64 v[158:159], v[158:159], 0, v[148:149]
	v_lshl_add_u64 v[160:161], v[160:161], 0, v[148:149]
	v_lshl_add_u64 v[162:163], v[162:163], 0, v[148:149]
	v_add_u32_e32 v170, 0x80, v144
	s_mov_b64 s[28:29], s[26:27]
	v_fmamk_f32 v145, v145, 0x3a800000, v156
	v_fmamk_f32 v157, v157, 0x3a800000, v156
	v_fmamk_f32 v164, v164, 0x3a800000, v156
	v_fmamk_f32 v171, v165, 0x3a800000, v156
	v_fmamk_f32 v172, v166, 0x3a800000, v156
	v_mul_f32_e32 v165, 0x4b800000, v145
	v_mul_f32_e32 v166, 0x4b800000, v157
	v_cmp_gt_f32_e32 vcc, s53, v145
	v_cmp_gt_f32_e64 s[0:1], s53, v157
	v_fmamk_f32 v173, v167, 0x3a800000, v156
	v_mul_f32_e32 v167, 0x4b800000, v164
	v_cndmask_b32_e32 v145, v145, v165, vcc
	v_cndmask_b32_e64 v157, v157, v166, s[0:1]
	v_cmp_gt_f32_e64 s[2:3], s53, v164
	v_rsq_f32_e32 v145, v145
	v_rsq_f32_e32 v157, v157
	v_cndmask_b32_e64 v164, v164, v167, s[2:3]
	v_rsq_f32_e32 v165, v164
	v_mul_f32_e32 v164, 0x45800000, v145
	v_mul_f32_e32 v166, 0x45800000, v157
	v_cndmask_b32_e32 v164, v145, v164, vcc
	v_mul_f32_e32 v167, 0x45800000, v165
	v_cndmask_b32_e64 v166, v157, v166, s[0:1]
	v_fmamk_f32 v175, v168, 0x3a800000, v156
	v_cndmask_b32_e64 v168, v165, v167, s[2:3]
	v_pk_mul_f32 v[126:127], v[126:127], v[164:165] op_sel_hi:[1,0]
	v_pk_mul_f32 v[124:125], v[124:125], v[164:165] op_sel_hi:[1,0]
	v_pk_mul_f32 v[122:123], v[122:123], v[164:165] op_sel_hi:[1,0]
	v_pk_mul_f32 v[120:121], v[120:121], v[164:165] op_sel_hi:[1,0]
	v_pk_mul_f32 v[110:111], v[110:111], v[164:165] op_sel_hi:[1,0]
	v_pk_mul_f32 v[108:109], v[108:109], v[164:165] op_sel_hi:[1,0]
	v_pk_mul_f32 v[102:103], v[102:103], v[164:165] op_sel_hi:[1,0]
	v_pk_mul_f32 v[100:101], v[100:101], v[164:165] op_sel_hi:[1,0]
	v_pk_mul_f32 v[118:119], v[118:119], v[166:167] op_sel_hi:[1,0]
	v_pk_mul_f32 v[116:117], v[116:117], v[166:167] op_sel_hi:[1,0]
	v_pk_mul_f32 v[114:115], v[114:115], v[166:167] op_sel_hi:[1,0]
	v_pk_mul_f32 v[112:113], v[112:113], v[166:167] op_sel_hi:[1,0]
	v_pk_mul_f32 v[94:95], v[94:95], v[166:167] op_sel_hi:[1,0]
	v_pk_mul_f32 v[92:93], v[92:93], v[166:167] op_sel_hi:[1,0]
	v_pk_mul_f32 v[164:165], v[90:91], v[166:167] op_sel_hi:[1,0]
	v_pk_mul_f32 v[166:167], v[88:89], v[166:167] op_sel_hi:[1,0]
	v_cvt_pk_bf16_f32 v88, v124, v125
	v_cvt_pk_bf16_f32 v89, v126, v127
	v_cvt_pk_bf16_f32 v90, v120, v121
	v_cvt_pk_bf16_f32 v91, v122, v123
	global_store_dwordx4 v[158:159], v[88:91], off nt
	v_fmamk_f32 v169, v169, 0x3a800000, v156
	v_pk_mul_f32 v[106:107], v[106:107], v[168:169] op_sel_hi:[1,0]
	v_cvt_pk_bf16_f32 v88, v108, v109
	v_cvt_pk_bf16_f32 v89, v110, v111
	v_cvt_pk_bf16_f32 v90, v100, v101
	v_cvt_pk_bf16_f32 v91, v102, v103
	global_store_dwordx4 v[158:159], v[88:91], off offset:256 nt
	v_pk_mul_f32 v[104:105], v[104:105], v[168:169] op_sel_hi:[1,0]
	v_pk_mul_f32 v[98:99], v[98:99], v[168:169] op_sel_hi:[1,0]
	v_cvt_pk_bf16_f32 v88, v116, v117
	v_cvt_pk_bf16_f32 v89, v118, v119
	v_cvt_pk_bf16_f32 v90, v112, v113
	v_cvt_pk_bf16_f32 v91, v114, v115
	global_store_dwordx4 v[160:161], v[88:91], off nt
	v_pk_mul_f32 v[96:97], v[96:97], v[168:169] op_sel_hi:[1,0]
	v_pk_mul_f32 v[86:87], v[86:87], v[168:169] op_sel_hi:[1,0]
	v_cvt_pk_bf16_f32 v88, v92, v93
	v_cvt_pk_bf16_f32 v89, v94, v95
	v_cvt_pk_bf16_f32 v90, v166, v167
	v_cvt_pk_bf16_f32 v91, v164, v165
	global_store_dwordx4 v[160:161], v[88:91], off offset:256 nt
	v_pk_mul_f32 v[84:85], v[84:85], v[168:169] op_sel_hi:[1,0]
	v_cmp_gt_f32_e32 vcc, s53, v171
	v_cvt_pk_bf16_f32 v88, v104, v105
	v_cvt_pk_bf16_f32 v89, v106, v107
	v_cvt_pk_bf16_f32 v90, v96, v97
	v_cvt_pk_bf16_f32 v91, v98, v99
	global_store_dwordx4 v[162:163], v[88:91], off nt
	s_mov_b64 s[2:3], s[24:25]
	s_nop 0
	v_pk_mul_f32 v[88:89], v[82:83], v[168:169] op_sel_hi:[1,0]
	v_pk_mul_f32 v[82:83], v[80:81], v[168:169] op_sel_hi:[1,0]
	v_cvt_pk_bf16_f32 v80, v84, v85
	v_cvt_pk_bf16_f32 v81, v86, v87
	s_nop 0
	v_cvt_pk_bf16_f32 v82, v82, v83
	v_cvt_pk_bf16_f32 v83, v88, v89
	global_store_dwordx4 v[162:163], v[80:83], off offset:256 nt
	s_nop 1
	v_mul_f32_e32 v81, 0x4b800000, v171
	v_cndmask_b32_e32 v81, v171, v81, vcc
	v_rsq_f32_e32 v82, v81
	v_or_b32_e32 v80, 48, v144
	v_mad_i64_i32 v[80:81], s[0:1], v80, s52, v[146:147]
	v_mul_f32_e32 v83, 0x45800000, v82
	v_cndmask_b32_e32 v82, v82, v83, vcc
	v_lshl_add_u64 v[80:81], v[80:81], 0, v[148:149]
	v_pk_mul_f32 v[78:79], v[78:79], v[82:83] op_sel_hi:[1,0]
	v_pk_mul_f32 v[76:77], v[76:77], v[82:83] op_sel_hi:[1,0]
	v_pk_mul_f32 v[84:85], v[74:75], v[82:83] op_sel_hi:[1,0]
	v_pk_mul_f32 v[74:75], v[72:73], v[82:83] op_sel_hi:[1,0]
	v_cvt_pk_bf16_f32 v72, v76, v77
	v_cvt_pk_bf16_f32 v73, v78, v79
	v_pk_mul_f32 v[68:69], v[68:69], v[82:83] op_sel_hi:[1,0]
	v_cvt_pk_bf16_f32 v74, v74, v75
	v_cvt_pk_bf16_f32 v75, v84, v85
	global_store_dwordx4 v[80:81], v[72:75], off nt
	v_pk_mul_f32 v[70:71], v[70:71], v[82:83] op_sel_hi:[1,0]
	v_cmp_gt_f32_e32 vcc, s53, v172
	v_pk_mul_f32 v[72:73], v[66:67], v[82:83] op_sel_hi:[1,0]
	v_pk_mul_f32 v[66:67], v[64:65], v[82:83] op_sel_hi:[1,0]
	v_cvt_pk_bf16_f32 v64, v68, v69
	v_cvt_pk_bf16_f32 v65, v70, v71
	s_nop 0
	v_cvt_pk_bf16_f32 v66, v66, v67
	v_cvt_pk_bf16_f32 v67, v72, v73
	global_store_dwordx4 v[80:81], v[64:67], off offset:256 nt
	s_nop 1
	v_mul_f32_e32 v64, 0x4b800000, v172
	v_cndmask_b32_e32 v64, v172, v64, vcc
	v_rsq_f32_e32 v66, v64
	v_mad_i64_i32 v[64:65], s[0:1], v170, s52, v[146:147]
	v_lshl_add_u64 v[64:65], v[64:65], 0, v[148:149]
	v_mul_f32_e32 v67, 0x45800000, v66
	v_cndmask_b32_e32 v66, v66, v67, vcc
	v_pk_mul_f32 v[62:63], v[62:63], v[66:67] op_sel_hi:[1,0]
	v_pk_mul_f32 v[60:61], v[60:61], v[66:67] op_sel_hi:[1,0]
	v_pk_mul_f32 v[68:69], v[58:59], v[66:67] op_sel_hi:[1,0]
	v_pk_mul_f32 v[58:59], v[56:57], v[66:67] op_sel_hi:[1,0]
	v_cvt_pk_bf16_f32 v56, v60, v61
	v_cvt_pk_bf16_f32 v57, v62, v63
	v_pk_mul_f32 v[54:55], v[54:55], v[66:67] op_sel_hi:[1,0]
	v_cvt_pk_bf16_f32 v58, v58, v59
	v_cvt_pk_bf16_f32 v59, v68, v69
	global_store_dwordx4 v[64:65], v[56:59], off nt
	v_pk_mul_f32 v[52:53], v[52:53], v[66:67] op_sel_hi:[1,0]
	v_cmp_gt_f32_e32 vcc, s53, v173
	v_pk_mul_f32 v[56:57], v[50:51], v[66:67] op_sel_hi:[1,0]
	v_pk_mul_f32 v[50:51], v[48:49], v[66:67] op_sel_hi:[1,0]
	v_cvt_pk_bf16_f32 v48, v52, v53
	v_cvt_pk_bf16_f32 v49, v54, v55
	s_nop 0
	v_cvt_pk_bf16_f32 v50, v50, v51
	v_cvt_pk_bf16_f32 v51, v56, v57
	global_store_dwordx4 v[64:65], v[48:51], off offset:256 nt
	s_nop 1
	v_mul_f32_e32 v49, 0x4b800000, v173
	v_cndmask_b32_e32 v49, v173, v49, vcc
	v_rsq_f32_e32 v50, v49
	v_add_u32_e32 v48, 0x90, v144
	v_mad_i64_i32 v[48:49], s[0:1], v48, s52, v[146:147]
	v_mul_f32_e32 v51, 0x45800000, v50
	v_cndmask_b32_e32 v50, v50, v51, vcc
	v_lshl_add_u64 v[48:49], v[48:49], 0, v[148:149]
	v_pk_mul_f32 v[46:47], v[46:47], v[50:51] op_sel_hi:[1,0]
	v_pk_mul_f32 v[44:45], v[44:45], v[50:51] op_sel_hi:[1,0]
	v_pk_mul_f32 v[52:53], v[42:43], v[50:51] op_sel_hi:[1,0]
	v_pk_mul_f32 v[42:43], v[40:41], v[50:51] op_sel_hi:[1,0]
	v_cvt_pk_bf16_f32 v40, v44, v45
	v_cvt_pk_bf16_f32 v41, v46, v47
	v_pk_mul_f32 v[38:39], v[38:39], v[50:51] op_sel_hi:[1,0]
	v_cvt_pk_bf16_f32 v42, v42, v43
	v_cvt_pk_bf16_f32 v43, v52, v53
	global_store_dwordx4 v[48:49], v[40:43], off nt
	v_pk_mul_f32 v[36:37], v[36:37], v[50:51] op_sel_hi:[1,0]
	v_cmp_gt_f32_e32 vcc, s53, v175
	v_pk_mul_f32 v[40:41], v[34:35], v[50:51] op_sel_hi:[1,0]
	v_pk_mul_f32 v[34:35], v[32:33], v[50:51] op_sel_hi:[1,0]
	v_cvt_pk_bf16_f32 v32, v36, v37
	v_cvt_pk_bf16_f32 v33, v38, v39
	s_nop 0
	v_cvt_pk_bf16_f32 v34, v34, v35
	v_cvt_pk_bf16_f32 v35, v40, v41
	global_store_dwordx4 v[48:49], v[32:35], off offset:256 nt
	s_nop 1
	v_mul_f32_e32 v33, 0x4b800000, v175
	v_cndmask_b32_e32 v33, v175, v33, vcc
	v_rsq_f32_e32 v34, v33
	v_add_u32_e32 v32, 0xa0, v144
	v_mad_i64_i32 v[32:33], s[0:1], v32, s52, v[146:147]
	v_mul_f32_e32 v35, 0x45800000, v34
	v_cndmask_b32_e32 v34, v34, v35, vcc
	v_lshl_add_u64 v[32:33], v[32:33], 0, v[148:149]
	v_pk_mul_f32 v[30:31], v[30:31], v[34:35] op_sel_hi:[1,0]
	v_pk_mul_f32 v[28:29], v[28:29], v[34:35] op_sel_hi:[1,0]
	v_pk_mul_f32 v[36:37], v[26:27], v[34:35] op_sel_hi:[1,0]
	v_pk_mul_f32 v[26:27], v[24:25], v[34:35] op_sel_hi:[1,0]
	v_cvt_pk_bf16_f32 v24, v28, v29
	v_cvt_pk_bf16_f32 v25, v30, v31
	v_pk_mul_f32 v[22:23], v[22:23], v[34:35] op_sel_hi:[1,0]
	v_cvt_pk_bf16_f32 v26, v26, v27
	v_cvt_pk_bf16_f32 v27, v36, v37
	global_store_dwordx4 v[32:33], v[24:27], off nt
	v_pk_mul_f32 v[20:21], v[20:21], v[34:35] op_sel_hi:[1,0]
	v_cmp_gt_f32_e32 vcc, s53, v169
	v_pk_mul_f32 v[24:25], v[18:19], v[34:35] op_sel_hi:[1,0]
	v_pk_mul_f32 v[18:19], v[16:17], v[34:35] op_sel_hi:[1,0]
	v_cvt_pk_bf16_f32 v16, v20, v21
	v_cvt_pk_bf16_f32 v17, v22, v23
	s_nop 0
	v_cvt_pk_bf16_f32 v18, v18, v19
	v_cvt_pk_bf16_f32 v19, v24, v25
	global_store_dwordx4 v[32:33], v[16:19], off offset:256 nt
	s_nop 1
	v_mul_f32_e32 v17, 0x4b800000, v169
	v_cndmask_b32_e32 v17, v169, v17, vcc
	v_rsq_f32_e32 v18, v17
	v_add_u32_e32 v16, 0xb0, v144
	v_mad_i64_i32 v[16:17], s[0:1], v16, s52, v[146:147]
	v_mul_f32_e32 v19, 0x45800000, v18
	v_cndmask_b32_e32 v18, v18, v19, vcc
	v_lshl_add_u64 v[16:17], v[16:17], 0, v[148:149]
	v_pk_mul_f32 v[14:15], v[14:15], v[18:19] op_sel_hi:[1,0]
	v_pk_mul_f32 v[12:13], v[12:13], v[18:19] op_sel_hi:[1,0]
	v_pk_mul_f32 v[20:21], v[10:11], v[18:19] op_sel_hi:[1,0]
	v_pk_mul_f32 v[10:11], v[8:9], v[18:19] op_sel_hi:[1,0]
	v_cvt_pk_bf16_f32 v8, v12, v13
	v_cvt_pk_bf16_f32 v9, v14, v15
	s_and_b64 vcc, exec, s[6:7]
	v_cvt_pk_bf16_f32 v10, v10, v11
	v_cvt_pk_bf16_f32 v11, v20, v21
	global_store_dwordx4 v[16:17], v[8:11], off nt
	s_mov_b32 s1, s20
	s_mov_b32 s0, s22
	v_pk_mul_f32 v[8:9], v[2:3], v[18:19] op_sel_hi:[1,0]
	v_pk_mul_f32 v[2:3], v[0:1], v[18:19] op_sel_hi:[1,0]
	v_pk_mul_f32 v[6:7], v[6:7], v[18:19] op_sel_hi:[1,0]
	v_pk_mul_f32 v[4:5], v[4:5], v[18:19] op_sel_hi:[1,0]
	s_nop 0
	v_cvt_pk_bf16_f32 v0, v4, v5
	v_cvt_pk_bf16_f32 v1, v6, v7
	v_cvt_pk_bf16_f32 v2, v2, v3
	v_cvt_pk_bf16_f32 v3, v8, v9
	global_store_dwordx4 v[16:17], v[0:3], off offset:256 nt
	s_cbranch_vccz .LBB0_943
	s_waitcnt vmcnt(0)
	s_cmpk_gt_u32 s33, 0xff
	s_cbranch_scc1 .LBB0_950
	s_barrier

.LBB0_1079:
	s_ashr_i32 s29, s28, 31
	v_cmp_lt_i64_e32 vcc, s[30:31], v[140:141]
	s_lshl_b64 s[30:31], s[28:29], 19
	s_add_u32 s30, s10, s30
	s_addc_u32 s31, s11, s31
	s_and_b64 s[34:35], vcc, exec
	s_cselect_b32 s29, s31, s3
	s_cselect_b32 s63, s30, s2
	s_ashr_i32 s27, s26, 31
	s_lshl_b64 s[34:35], s[26:27], 19
	s_add_u32 s34, s41, s34
	s_addc_u32 s35, s42, s35
	s_and_b64 s[38:39], vcc, exec
	s_cselect_b32 s27, s35, s37
	s_cselect_b32 s64, s34, s36
	s_add_u32 s2, s2, 0x40080
	s_addc_u32 s3, s3, 0
	s_add_u32 s65, s36, 0x100
	v_lshl_add_u32 v240, s0, 8, v148
	v_ashrrev_i32_e32 v241, 31, v240
	v_lshl_add_u64 v[240:241], v[240:241], 2, s[18:19]
	global_load_dword v242, v[240:241], off
	global_load_dword v243, v[240:241], off offset:64
	global_load_dword v244, v[240:241], off offset:128
	global_load_dword v245, v[240:241], off offset:192
	global_load_dword v246, v[240:241], off offset:512
	global_load_dword v247, v[240:241], off offset:576
	global_load_dword v248, v[240:241], off offset:640
	global_load_dword v249, v[240:241], off offset:704
	v_mov_b32_e32 v0, 0
	s_addc_u32 s66, s37, 0
	s_mov_b32 s67, -2
	v_mov_b32_e32 v1, v0
	v_mov_b64_e32 v[2:3], v[0:1]
	v_mov_b64_e32 v[4:5], v[0:1]
	v_mov_b64_e32 v[6:7], v[0:1]
	v_mov_b64_e32 v[8:9], v[0:1]
	v_mov_b64_e32 v[10:11], v[0:1]
	v_mov_b64_e32 v[12:13], v[0:1]
	v_mov_b64_e32 v[14:15], v[0:1]
	v_mov_b64_e32 v[16:17], v[0:1]
	v_mov_b64_e32 v[18:19], v[0:1]
	v_mov_b64_e32 v[20:21], v[0:1]
	v_mov_b64_e32 v[22:23], v[0:1]
	v_mov_b64_e32 v[24:25], v[0:1]
	v_mov_b64_e32 v[26:27], v[0:1]
	v_mov_b64_e32 v[28:29], v[0:1]
	v_mov_b64_e32 v[30:31], v[0:1]
	v_mov_b64_e32 v[32:33], v[0:1]
	v_mov_b64_e32 v[34:35], v[0:1]
	v_mov_b64_e32 v[36:37], v[0:1]
	v_mov_b64_e32 v[38:39], v[0:1]
	v_mov_b64_e32 v[40:41], v[0:1]
	v_mov_b64_e32 v[42:43], v[0:1]
	v_mov_b64_e32 v[44:45], v[0:1]
	v_mov_b64_e32 v[46:47], v[0:1]
	v_mov_b64_e32 v[48:49], v[0:1]
	v_mov_b64_e32 v[50:51], v[0:1]
	v_mov_b64_e32 v[52:53], v[0:1]
	v_mov_b64_e32 v[54:55], v[0:1]
	v_mov_b64_e32 v[56:57], v[0:1]
	v_mov_b64_e32 v[58:59], v[0:1]
	v_mov_b64_e32 v[60:61], v[0:1]
	v_mov_b64_e32 v[62:63], v[0:1]
	v_mov_b64_e32 v[64:65], v[0:1]
	v_mov_b64_e32 v[66:67], v[0:1]
	v_mov_b64_e32 v[68:69], v[0:1]
	v_mov_b64_e32 v[70:71], v[0:1]
	v_mov_b64_e32 v[72:73], v[0:1]
	v_mov_b64_e32 v[74:75], v[0:1]
	v_mov_b64_e32 v[76:77], v[0:1]
	v_mov_b64_e32 v[78:79], v[0:1]
	v_mov_b64_e32 v[80:81], v[0:1]
	v_mov_b64_e32 v[82:83], v[0:1]
	v_mov_b64_e32 v[84:85], v[0:1]
	v_mov_b64_e32 v[86:87], v[0:1]
	v_mov_b64_e32 v[88:89], v[0:1]
	v_mov_b64_e32 v[90:91], v[0:1]
	v_mov_b64_e32 v[92:93], v[0:1]
	v_mov_b64_e32 v[94:95], v[0:1]
	v_mov_b64_e32 v[96:97], v[0:1]
	v_mov_b64_e32 v[98:99], v[0:1]
	v_mov_b64_e32 v[100:101], v[0:1]
	v_mov_b64_e32 v[102:103], v[0:1]
	v_mov_b64_e32 v[104:105], v[0:1]
	v_mov_b64_e32 v[106:107], v[0:1]
	v_mov_b64_e32 v[108:109], v[0:1]
	v_mov_b64_e32 v[110:111], v[0:1]
	v_mov_b64_e32 v[112:113], v[0:1]
	v_mov_b64_e32 v[114:115], v[0:1]
	v_mov_b64_e32 v[116:117], v[0:1]
	v_mov_b64_e32 v[118:119], v[0:1]
	v_mov_b64_e32 v[120:121], v[0:1]
	v_mov_b64_e32 v[122:123], v[0:1]
	v_mov_b64_e32 v[124:125], v[0:1]
	v_mov_b64_e32 v[126:127], v[0:1]
.LBB0_1080:
	ds_read_b128 v[144:147], v151
	ds_read_b128 v[156:159], v151 offset:1024
	ds_read_b128 v[160:163], v151 offset:2048
	ds_read_b128 v[164:167], v151 offset:3072
	s_add_u32 s36, s2, 0xfffc0080
	s_addc_u32 s37, s3, -1
	s_cmp_eq_u32 s67, 12
	s_cselect_b32 s39, s29, s37
	s_cselect_b32 s38, s63, s36
	s_cselect_b32 s37, s27, s66
	s_cselect_b32 s36, s64, s65
	v_lshl_add_u64 v[172:173], s[2:3], 0, v[136:137]
	s_add_i32 m0, s48, 0xc000
	ds_read_b128 v[168:171], v152
	ds_read_b128 v[176:179], v152 offset:1024
	ds_read_b128 v[180:183], v152 offset:2048
	ds_read_b128 v[184:187], v152 offset:3072
	ds_read_b128 v[188:191], v152 offset:4096
	ds_read_b128 v[192:195], v152 offset:5120
	ds_read_b128 v[196:199], v152 offset:6144
	ds_read_b128 v[200:203], v152 offset:7168
	global_load_lds_dwordx4 v[172:173], off
	s_add_i32 m0, s48, 0xe000
	v_lshl_add_u64 v[172:173], s[2:3], 0, v[138:139]
	global_load_lds_dwordx4 v[172:173], off
	s_waitcnt lgkmcnt(8)
	s_setprio 1
	s_barrier
	s_waitcnt lgkmcnt(0)
	v_mfma_f32_16x16x32_bf16 v[124:127], v[144:147], v[168:171], v[124:127]
	v_mfma_f32_16x16x32_bf16 v[120:123], v[160:163], v[168:171], v[120:123]
	v_mfma_f32_16x16x32_bf16 v[116:119], v[144:147], v[180:183], v[116:119]
	v_mfma_f32_16x16x32_bf16 v[112:115], v[160:163], v[180:183], v[112:115]
	v_mfma_f32_16x16x32_bf16 v[104:107], v[144:147], v[188:191], v[104:107]
	v_mfma_f32_16x16x32_bf16 v[96:99], v[160:163], v[188:191], v[96:99]
	v_mfma_f32_16x16x32_bf16 v[76:79], v[144:147], v[196:199], v[76:79]
	v_mfma_f32_16x16x32_bf16 v[72:75], v[160:163], v[196:199], v[72:75]
	v_mfma_f32_16x16x32_bf16 v[124:127], v[156:159], v[176:179], v[124:127]
	v_mfma_f32_16x16x32_bf16 v[120:123], v[164:167], v[176:179], v[120:123]
	v_mfma_f32_16x16x32_bf16 v[116:119], v[156:159], v[184:187], v[116:119]
	v_mfma_f32_16x16x32_bf16 v[112:115], v[164:167], v[184:187], v[112:115]
	v_mfma_f32_16x16x32_bf16 v[104:107], v[156:159], v[192:195], v[104:107]
	v_mfma_f32_16x16x32_bf16 v[96:99], v[164:167], v[192:195], v[96:99]
	v_mfma_f32_16x16x32_bf16 v[76:79], v[156:159], v[200:203], v[76:79]
	v_mfma_f32_16x16x32_bf16 v[72:75], v[164:167], v[200:203], v[72:75]
	s_barrier
	s_setprio 0
	s_add_i32 s68, s56, s43
	v_lshl_add_u64 v[172:173], s[36:37], 0, v[130:131]
	s_mov_b32 m0, s68
	ds_read_b128 v[204:207], v153
	ds_read_b128 v[212:215], v153 offset:1024
	ds_read_b128 v[216:219], v153 offset:2048
	ds_read_b128 v[220:223], v153 offset:3072
	global_load_lds_dwordx4 v[172:173], off
	s_add_i32 m0, s68, 0x2000
	v_lshl_add_u64 v[208:209], s[36:37], 0, v[134:135]
	global_load_lds_dwordx4 v[208:209], off
	s_setprio 1
	s_barrier
	s_waitcnt lgkmcnt(0)
	v_mfma_f32_16x16x32_bf16 v[108:111], v[204:207], v[168:171], v[108:111]
	v_mfma_f32_16x16x32_bf16 v[100:103], v[216:219], v[168:171], v[100:103]
	v_mfma_f32_16x16x32_bf16 v[92:95], v[204:207], v[180:183], v[92:95]
	v_mfma_f32_16x16x32_bf16 v[88:91], v[216:219], v[180:183], v[88:91]
	v_mfma_f32_16x16x32_bf16 v[84:87], v[204:207], v[188:191], v[84:87]
	v_mfma_f32_16x16x32_bf16 v[80:83], v[216:219], v[188:191], v[80:83]
	v_mfma_f32_16x16x32_bf16 v[68:71], v[204:207], v[196:199], v[68:71]
	v_mfma_f32_16x16x32_bf16 v[64:67], v[216:219], v[196:199], v[64:67]
	v_mfma_f32_16x16x32_bf16 v[108:111], v[212:215], v[176:179], v[108:111]
	v_mfma_f32_16x16x32_bf16 v[100:103], v[220:223], v[176:179], v[100:103]
	v_mfma_f32_16x16x32_bf16 v[92:95], v[212:215], v[184:187], v[92:95]
	v_mfma_f32_16x16x32_bf16 v[88:91], v[220:223], v[184:187], v[88:91]
	v_mfma_f32_16x16x32_bf16 v[84:87], v[212:215], v[192:195], v[84:87]
	v_mfma_f32_16x16x32_bf16 v[80:83], v[220:223], v[192:195], v[80:83]
	v_mfma_f32_16x16x32_bf16 v[68:71], v[212:215], v[200:203], v[68:71]
	v_mfma_f32_16x16x32_bf16 v[64:67], v[220:223], v[200:203], v[64:67]
	s_barrier
	s_setprio 0
	s_mov_b32 m0, s48
	v_lshl_add_u64 v[224:225], s[38:39], 0, v[128:129]
	ds_read_b128 v[168:171], v152 offset:16384
	ds_read_b128 v[176:179], v152 offset:17408
	ds_read_b128 v[180:183], v152 offset:18432
	ds_read_b128 v[184:187], v152 offset:19456
	ds_read_b128 v[188:191], v152 offset:20480
	ds_read_b128 v[192:195], v152 offset:21504
	ds_read_b128 v[196:199], v152 offset:22528
	ds_read_b128 v[200:203], v152 offset:23552
	global_load_lds_dwordx4 v[224:225], off
	s_mov_b32 m0, s49
	v_lshl_add_u64 v[226:227], s[38:39], 0, v[132:133]
	global_load_lds_dwordx4 v[226:227], off
	s_setprio 1
	s_barrier
	s_waitcnt lgkmcnt(0)
	v_mfma_f32_16x16x32_bf16 v[60:63], v[144:147], v[168:171], v[60:63]
	v_mfma_f32_16x16x32_bf16 v[56:59], v[160:163], v[168:171], v[56:59]
	v_mfma_f32_16x16x32_bf16 v[44:47], v[144:147], v[180:183], v[44:47]
	v_mfma_f32_16x16x32_bf16 v[40:43], v[160:163], v[180:183], v[40:43]
	v_mfma_f32_16x16x32_bf16 v[28:31], v[144:147], v[188:191], v[28:31]
	v_mfma_f32_16x16x32_bf16 v[24:27], v[160:163], v[188:191], v[24:27]
	v_mfma_f32_16x16x32_bf16 v[12:15], v[144:147], v[196:199], v[12:15]
	v_mfma_f32_16x16x32_bf16 v[8:11], v[160:163], v[196:199], v[8:11]
	v_mfma_f32_16x16x32_bf16 v[60:63], v[156:159], v[176:179], v[60:63]
	v_mfma_f32_16x16x32_bf16 v[56:59], v[164:167], v[176:179], v[56:59]
	v_mfma_f32_16x16x32_bf16 v[44:47], v[156:159], v[184:187], v[44:47]
	v_mfma_f32_16x16x32_bf16 v[40:43], v[164:167], v[184:187], v[40:43]
	v_mfma_f32_16x16x32_bf16 v[28:31], v[156:159], v[192:195], v[28:31]
	v_mfma_f32_16x16x32_bf16 v[24:27], v[164:167], v[192:195], v[24:27]
	v_mfma_f32_16x16x32_bf16 v[12:15], v[156:159], v[200:203], v[12:15]
	v_mfma_f32_16x16x32_bf16 v[8:11], v[164:167], v[200:203], v[8:11]
	s_barrier
	s_setprio 0
	s_add_u32 s68, s36, 0x40000
	s_addc_u32 s69, s37, 0
	s_add_i32 s70, s57, s43
	s_mov_b32 m0, s70
	v_lshl_add_u64 v[144:145], s[68:69], 0, v[130:131]
	global_load_lds_dwordx4 v[144:145], off
	s_add_i32 m0, s70, 0x2000
	v_lshl_add_u64 v[144:145], s[68:69], 0, v[134:135]
	global_load_lds_dwordx4 v[144:145], off
	s_waitcnt vmcnt(6)
	s_setprio 1
	s_barrier
	v_mfma_f32_16x16x32_bf16 v[52:55], v[204:207], v[168:171], v[52:55]
	v_mfma_f32_16x16x32_bf16 v[48:51], v[216:219], v[168:171], v[48:51]
	v_mfma_f32_16x16x32_bf16 v[36:39], v[204:207], v[180:183], v[36:39]
	v_mfma_f32_16x16x32_bf16 v[32:35], v[216:219], v[180:183], v[32:35]
	v_mfma_f32_16x16x32_bf16 v[20:23], v[204:207], v[188:191], v[20:23]
	v_mfma_f32_16x16x32_bf16 v[16:19], v[216:219], v[188:191], v[16:19]
	v_mfma_f32_16x16x32_bf16 v[4:7], v[204:207], v[196:199], v[4:7]
	v_mfma_f32_16x16x32_bf16 v[0:3], v[216:219], v[196:199], v[0:3]
	v_mfma_f32_16x16x32_bf16 v[52:55], v[212:215], v[176:179], v[52:55]
	v_mfma_f32_16x16x32_bf16 v[48:51], v[220:223], v[176:179], v[48:51]
	v_mfma_f32_16x16x32_bf16 v[36:39], v[212:215], v[184:187], v[36:39]
	v_mfma_f32_16x16x32_bf16 v[32:35], v[220:223], v[184:187], v[32:35]
	v_mfma_f32_16x16x32_bf16 v[20:23], v[212:215], v[192:195], v[20:23]
	v_mfma_f32_16x16x32_bf16 v[16:19], v[220:223], v[192:195], v[16:19]
	v_mfma_f32_16x16x32_bf16 v[4:7], v[212:215], v[200:203], v[4:7]
	v_mfma_f32_16x16x32_bf16 v[0:3], v[220:223], v[200:203], v[0:3]
	s_barrier
	s_setprio 0
	s_add_i32 s68, 0, 0x18000
	v_add_u32_e32 v155, s68, v149
	ds_read_b128 v[144:147], v155
	ds_read_b128 v[156:159], v155 offset:1024
	ds_read_b128 v[160:163], v155 offset:2048
	ds_read_b128 v[164:167], v155 offset:3072
	s_add_u32 s38, s38, 0x40000
	s_addc_u32 s39, s39, 0
	s_mov_b32 m0, s50
	v_lshl_add_u64 v[204:205], s[38:39], 0, v[128:129]
	ds_read_b128 v[168:171], v152 offset:32768
	ds_read_b128 v[176:179], v152 offset:33792
	ds_read_b128 v[180:183], v152 offset:34816
	ds_read_b128 v[184:187], v152 offset:35840
	ds_read_b128 v[188:191], v152 offset:36864
	ds_read_b128 v[192:195], v152 offset:37888
	ds_read_b128 v[196:199], v152 offset:38912
	ds_read_b128 v[200:203], v152 offset:39936
	global_load_lds_dwordx4 v[204:205], off
	s_mov_b32 m0, s51
	v_lshl_add_u64 v[204:205], s[38:39], 0, v[132:133]
	global_load_lds_dwordx4 v[204:205], off
	s_waitcnt lgkmcnt(8)
	s_setprio 1
	s_barrier
	s_waitcnt lgkmcnt(0)
	v_mfma_f32_16x16x32_bf16 v[124:127], v[144:147], v[168:171], v[124:127]
	v_mfma_f32_16x16x32_bf16 v[120:123], v[160:163], v[168:171], v[120:123]
	v_mfma_f32_16x16x32_bf16 v[116:119], v[144:147], v[180:183], v[116:119]
	v_mfma_f32_16x16x32_bf16 v[112:115], v[160:163], v[180:183], v[112:115]
	v_mfma_f32_16x16x32_bf16 v[104:107], v[144:147], v[188:191], v[104:107]
	v_mfma_f32_16x16x32_bf16 v[96:99], v[160:163], v[188:191], v[96:99]
	v_mfma_f32_16x16x32_bf16 v[76:79], v[144:147], v[196:199], v[76:79]
	v_mfma_f32_16x16x32_bf16 v[72:75], v[160:163], v[196:199], v[72:75]
	v_mfma_f32_16x16x32_bf16 v[124:127], v[156:159], v[176:179], v[124:127]
	v_mfma_f32_16x16x32_bf16 v[120:123], v[164:167], v[176:179], v[120:123]
	v_mfma_f32_16x16x32_bf16 v[116:119], v[156:159], v[184:187], v[116:119]
	v_mfma_f32_16x16x32_bf16 v[112:115], v[164:167], v[184:187], v[112:115]
	v_mfma_f32_16x16x32_bf16 v[104:107], v[156:159], v[192:195], v[104:107]
	v_mfma_f32_16x16x32_bf16 v[96:99], v[164:167], v[192:195], v[96:99]
	v_mfma_f32_16x16x32_bf16 v[76:79], v[156:159], v[200:203], v[76:79]
	v_mfma_f32_16x16x32_bf16 v[72:75], v[164:167], v[200:203], v[72:75]
	s_barrier
	s_setprio 0
	s_add_i32 s38, 0, 0x1c000
	s_add_i32 s39, s68, s43
	v_add_u32_e32 v155, s38, v149
	v_lshl_add_u64 v[172:173], v[172:173], 0, s[8:9]
	s_mov_b32 m0, s39
	ds_read_b128 v[204:207], v155
	ds_read_b128 v[212:215], v155 offset:1024
	ds_read_b128 v[216:219], v155 offset:2048
	ds_read_b128 v[220:223], v155 offset:3072
	global_load_lds_dwordx4 v[172:173], off
	s_add_i32 m0, s39, 0x2000
	v_lshl_add_u64 v[172:173], v[208:209], 0, s[8:9]
	global_load_lds_dwordx4 v[172:173], off
	s_setprio 1
	s_barrier
	s_waitcnt lgkmcnt(0)
	v_mfma_f32_16x16x32_bf16 v[108:111], v[204:207], v[168:171], v[108:111]
	v_mfma_f32_16x16x32_bf16 v[100:103], v[216:219], v[168:171], v[100:103]
	v_mfma_f32_16x16x32_bf16 v[92:95], v[204:207], v[180:183], v[92:95]
	v_mfma_f32_16x16x32_bf16 v[88:91], v[216:219], v[180:183], v[88:91]
	v_mfma_f32_16x16x32_bf16 v[84:87], v[204:207], v[188:191], v[84:87]
	v_mfma_f32_16x16x32_bf16 v[80:83], v[216:219], v[188:191], v[80:83]
	v_mfma_f32_16x16x32_bf16 v[68:71], v[204:207], v[196:199], v[68:71]
	v_mfma_f32_16x16x32_bf16 v[64:67], v[216:219], v[196:199], v[64:67]
	v_mfma_f32_16x16x32_bf16 v[108:111], v[212:215], v[176:179], v[108:111]
	v_mfma_f32_16x16x32_bf16 v[100:103], v[220:223], v[176:179], v[100:103]
	v_mfma_f32_16x16x32_bf16 v[92:95], v[212:215], v[184:187], v[92:95]
	v_mfma_f32_16x16x32_bf16 v[88:91], v[220:223], v[184:187], v[88:91]
	v_mfma_f32_16x16x32_bf16 v[84:87], v[212:215], v[192:195], v[84:87]
	v_mfma_f32_16x16x32_bf16 v[80:83], v[220:223], v[192:195], v[80:83]
	v_mfma_f32_16x16x32_bf16 v[68:71], v[212:215], v[200:203], v[68:71]
	v_mfma_f32_16x16x32_bf16 v[64:67], v[220:223], v[200:203], v[64:67]
	s_barrier
	s_setprio 0
	s_mov_b32 m0, s53
	v_lshl_add_u64 v[172:173], v[224:225], 0, s[8:9]
	ds_read_b128 v[168:171], v152 offset:49152
	ds_read_b128 v[176:179], v152 offset:50176
	ds_read_b128 v[180:183], v152 offset:51200
	ds_read_b128 v[184:187], v152 offset:52224
	ds_read_b128 v[188:191], v152 offset:53248
	ds_read_b128 v[192:195], v152 offset:54272
	ds_read_b128 v[196:199], v152 offset:55296
	ds_read_b128 v[200:203], v152 offset:56320
	global_load_lds_dwordx4 v[172:173], off
	s_mov_b32 m0, s54
	v_lshl_add_u64 v[172:173], v[226:227], 0, s[8:9]
	global_load_lds_dwordx4 v[172:173], off
	s_setprio 1
	s_barrier
	s_waitcnt lgkmcnt(0)
	v_mfma_f32_16x16x32_bf16 v[60:63], v[144:147], v[168:171], v[60:63]
	v_mfma_f32_16x16x32_bf16 v[56:59], v[160:163], v[168:171], v[56:59]
	v_mfma_f32_16x16x32_bf16 v[44:47], v[144:147], v[180:183], v[44:47]
	v_mfma_f32_16x16x32_bf16 v[40:43], v[160:163], v[180:183], v[40:43]
	v_mfma_f32_16x16x32_bf16 v[28:31], v[144:147], v[188:191], v[28:31]
	v_mfma_f32_16x16x32_bf16 v[24:27], v[160:163], v[188:191], v[24:27]
	v_mfma_f32_16x16x32_bf16 v[12:15], v[144:147], v[196:199], v[12:15]
	v_mfma_f32_16x16x32_bf16 v[8:11], v[160:163], v[196:199], v[8:11]
	v_mfma_f32_16x16x32_bf16 v[60:63], v[156:159], v[176:179], v[60:63]
	v_mfma_f32_16x16x32_bf16 v[56:59], v[164:167], v[176:179], v[56:59]
	v_mfma_f32_16x16x32_bf16 v[44:47], v[156:159], v[184:187], v[44:47]
	v_mfma_f32_16x16x32_bf16 v[40:43], v[164:167], v[184:187], v[40:43]
	v_mfma_f32_16x16x32_bf16 v[28:31], v[156:159], v[192:195], v[28:31]
	v_mfma_f32_16x16x32_bf16 v[24:27], v[164:167], v[192:195], v[24:27]
	v_mfma_f32_16x16x32_bf16 v[12:15], v[156:159], v[200:203], v[12:15]
	v_mfma_f32_16x16x32_bf16 v[8:11], v[164:167], v[200:203], v[8:11]
	s_barrier
	s_setprio 0
	s_add_u32 s36, s36, 0x40080
	s_addc_u32 s37, s37, 0
	s_add_i32 s38, s38, s43
	s_mov_b32 m0, s38
	v_lshl_add_u64 v[144:145], s[36:37], 0, v[130:131]
	global_load_lds_dwordx4 v[144:145], off
	s_add_i32 m0, s38, 0x2000
	v_lshl_add_u64 v[144:145], s[36:37], 0, v[134:135]
	global_load_lds_dwordx4 v[144:145], off
	s_waitcnt vmcnt(6)
	s_setprio 1
	s_barrier
	v_mfma_f32_16x16x32_bf16 v[52:55], v[204:207], v[168:171], v[52:55]
	v_mfma_f32_16x16x32_bf16 v[48:51], v[216:219], v[168:171], v[48:51]
	v_mfma_f32_16x16x32_bf16 v[36:39], v[204:207], v[180:183], v[36:39]
	v_mfma_f32_16x16x32_bf16 v[32:35], v[216:219], v[180:183], v[32:35]
	v_mfma_f32_16x16x32_bf16 v[20:23], v[204:207], v[188:191], v[20:23]
	v_mfma_f32_16x16x32_bf16 v[16:19], v[216:219], v[188:191], v[16:19]
	v_mfma_f32_16x16x32_bf16 v[4:7], v[204:207], v[196:199], v[4:7]
	v_mfma_f32_16x16x32_bf16 v[0:3], v[216:219], v[196:199], v[0:3]
	v_mfma_f32_16x16x32_bf16 v[52:55], v[212:215], v[176:179], v[52:55]
	v_mfma_f32_16x16x32_bf16 v[48:51], v[220:223], v[176:179], v[48:51]
	v_mfma_f32_16x16x32_bf16 v[36:39], v[212:215], v[184:187], v[36:39]
	v_mfma_f32_16x16x32_bf16 v[32:35], v[220:223], v[184:187], v[32:35]
	v_mfma_f32_16x16x32_bf16 v[20:23], v[212:215], v[192:195], v[20:23]
	v_mfma_f32_16x16x32_bf16 v[16:19], v[220:223], v[192:195], v[16:19]
	v_mfma_f32_16x16x32_bf16 v[4:7], v[212:215], v[200:203], v[4:7]
	v_mfma_f32_16x16x32_bf16 v[0:3], v[220:223], v[200:203], v[0:3]
	s_barrier
	s_setprio 0
	s_add_i32 s67, s67, 2
	s_add_u32 s2, s2, 0x100
	s_addc_u32 s3, s3, 0
	s_add_u32 s65, s65, 0x100
	s_addc_u32 s66, s66, 0
	s_cmp_gt_u32 s67, 13
	s_cbranch_scc0 .LBB0_1080
	v_lshl_add_u32 v146, s0, 8, v148
	v_ashrrev_i32_e32 v147, 31, v146
	v_mov_b32_e32 v155, v242
	v_mov_b32_e32 v164, v243
	v_mov_b32_e32 v165, v244
	v_mov_b32_e32 v166, v245
	v_mov_b32_e32 v167, v246
	v_mov_b32_e32 v168, v247
	v_mov_b32_e32 v169, v248
	v_mov_b32_e32 v170, v249
	v_lshl_or_b32 v144, s1, 8, v150
	v_ashrrev_i32_e32 v145, 31, v144
	v_lshlrev_b64 v[160:161], 10, v[146:147]
	v_lshlrev_b64 v[162:163], 1, v[144:145]
	v_lshl_add_u64 v[144:145], s[92:93], 0, v[160:161]
	v_or_b32_e32 v156, 16, v146
	v_ashrrev_i32_e32 v157, 31, v156
	v_or_b32_e32 v158, 32, v146
	v_lshlrev_b64 v[156:157], 10, v[156:157]
	v_lshl_add_u64 v[144:145], v[144:145], 0, v[162:163]
	v_ashrrev_i32_e32 v159, 31, v158
	v_lshl_add_u64 v[156:157], s[92:93], 0, v[156:157]
	v_lshlrev_b64 v[158:159], 10, v[158:159]
	v_lshl_add_u64 v[156:157], v[156:157], 0, v[162:163]
	v_lshl_add_u64 v[158:159], s[92:93], 0, v[158:159]
	v_lshl_add_u64 v[158:159], v[158:159], 0, v[162:163]
	s_mov_b64 s[36:37], s[34:35]
	v_fmamk_f32 v147, v155, 0x3a800000, v154
	v_fmamk_f32 v155, v164, 0x3a800000, v154
	v_fmamk_f32 v160, v165, 0x3a800000, v154
	v_mul_f32_e32 v161, 0x4b800000, v147
	v_mul_f32_e32 v164, 0x4b800000, v155
	v_cmp_gt_f32_e32 vcc, s58, v147
	v_cmp_gt_f32_e64 s[0:1], s58, v155
	v_mul_f32_e32 v165, 0x4b800000, v160
	v_cndmask_b32_e32 v147, v147, v161, vcc
	v_cndmask_b32_e64 v155, v155, v164, s[0:1]
	v_cmp_gt_f32_e64 s[2:3], s58, v160
	v_rsq_f32_e32 v147, v147
	v_rsq_f32_e32 v155, v155
	v_cndmask_b32_e64 v160, v160, v165, s[2:3]
	v_rsq_f32_e32 v160, v160
	v_mul_f32_e32 v161, 0x45800000, v147
	v_mul_f32_e32 v164, 0x45800000, v155
	v_cndmask_b32_e32 v147, v147, v161, vcc
	v_mul_f32_e32 v165, 0x45800000, v160
	v_cndmask_b32_e64 v155, v155, v164, s[0:1]
	v_cndmask_b32_e64 v161, v160, v165, s[2:3]
	v_mul_f32_e32 v160, 0x3e0293ee, v147
	v_mul_f32_e32 v164, 0x3e0293ee, v155
	v_fmamk_f32 v171, v166, 0x3a800000, v154
	v_mul_f32_e32 v166, 0x3e0293ee, v161
	v_pk_mul_f32 v[126:127], v[126:127], v[160:161] op_sel_hi:[1,0]
	v_pk_mul_f32 v[124:125], v[124:125], v[160:161] op_sel_hi:[1,0]
	v_pk_mul_f32 v[122:123], v[122:123], v[160:161] op_sel_hi:[1,0]
	v_pk_mul_f32 v[120:121], v[120:121], v[160:161] op_sel_hi:[1,0]
	v_pk_mul_f32 v[110:111], v[110:111], v[160:161] op_sel_hi:[1,0]
	v_pk_mul_f32 v[108:109], v[108:109], v[160:161] op_sel_hi:[1,0]
	v_pk_mul_f32 v[102:103], v[102:103], v[160:161] op_sel_hi:[1,0]
	v_pk_mul_f32 v[100:101], v[100:101], v[160:161] op_sel_hi:[1,0]
	v_pk_mul_f32 v[118:119], v[118:119], v[164:165] op_sel_hi:[1,0]
	v_pk_mul_f32 v[116:117], v[116:117], v[164:165] op_sel_hi:[1,0]
	v_pk_mul_f32 v[114:115], v[114:115], v[164:165] op_sel_hi:[1,0]
	v_pk_mul_f32 v[112:113], v[112:113], v[164:165] op_sel_hi:[1,0]
	v_pk_mul_f32 v[94:95], v[94:95], v[164:165] op_sel_hi:[1,0]
	v_pk_mul_f32 v[92:93], v[92:93], v[164:165] op_sel_hi:[1,0]
	v_pk_mul_f32 v[160:161], v[90:91], v[164:165] op_sel_hi:[1,0]
	v_pk_mul_f32 v[164:165], v[88:89], v[164:165] op_sel_hi:[1,0]
	v_cvt_pk_bf16_f32 v88, v124, v125
	v_cvt_pk_bf16_f32 v89, v126, v127
	v_cvt_pk_bf16_f32 v90, v120, v121
	v_cvt_pk_bf16_f32 v91, v122, v123
	global_store_dwordx4 v[144:145], v[88:91], off
	v_fmamk_f32 v167, v167, 0x3a800000, v154
	v_pk_mul_f32 v[106:107], v[106:107], v[166:167] op_sel_hi:[1,0]
	v_cvt_pk_bf16_f32 v88, v108, v109
	v_cvt_pk_bf16_f32 v89, v110, v111
	v_cvt_pk_bf16_f32 v90, v100, v101
	v_cvt_pk_bf16_f32 v91, v102, v103
	global_store_dwordx4 v[144:145], v[88:91], off offset:256
	v_pk_mul_f32 v[104:105], v[104:105], v[166:167] op_sel_hi:[1,0]
	v_pk_mul_f32 v[98:99], v[98:99], v[166:167] op_sel_hi:[1,0]
	v_cvt_pk_bf16_f32 v88, v116, v117
	v_cvt_pk_bf16_f32 v89, v118, v119
	v_cvt_pk_bf16_f32 v90, v112, v113
	v_cvt_pk_bf16_f32 v91, v114, v115
	global_store_dwordx4 v[156:157], v[88:91], off
	v_pk_mul_f32 v[96:97], v[96:97], v[166:167] op_sel_hi:[1,0]
	v_pk_mul_f32 v[86:87], v[86:87], v[166:167] op_sel_hi:[1,0]
	v_cvt_pk_bf16_f32 v88, v92, v93
	v_cvt_pk_bf16_f32 v89, v94, v95
	v_cvt_pk_bf16_f32 v90, v164, v165
	v_cvt_pk_bf16_f32 v91, v160, v161
	global_store_dwordx4 v[156:157], v[88:91], off offset:256
	v_pk_mul_f32 v[84:85], v[84:85], v[166:167] op_sel_hi:[1,0]
	v_cmp_gt_f32_e32 vcc, s58, v171
	v_cvt_pk_bf16_f32 v88, v104, v105
	v_cvt_pk_bf16_f32 v89, v106, v107
	v_cvt_pk_bf16_f32 v90, v96, v97
	v_cvt_pk_bf16_f32 v91, v98, v99
	global_store_dwordx4 v[158:159], v[88:91], off
	v_fmamk_f32 v168, v168, 0x3a800000, v154
	v_fmamk_f32 v169, v169, 0x3a800000, v154
	v_pk_mul_f32 v[88:89], v[82:83], v[166:167] op_sel_hi:[1,0]
	v_pk_mul_f32 v[82:83], v[80:81], v[166:167] op_sel_hi:[1,0]
	v_cvt_pk_bf16_f32 v80, v84, v85
	v_cvt_pk_bf16_f32 v81, v86, v87
	v_fmamk_f32 v170, v170, 0x3a800000, v154
	v_cvt_pk_bf16_f32 v82, v82, v83
	v_cvt_pk_bf16_f32 v83, v88, v89
	global_store_dwordx4 v[158:159], v[80:83], off offset:256
	s_mov_b32 s1, s26
	s_mov_b32 s0, s28
	v_mul_f32_e32 v82, 0x4b800000, v171
	v_cndmask_b32_e32 v82, v171, v82, vcc
	v_rsq_f32_e32 v82, v82
	v_or_b32_e32 v80, 48, v146
	v_ashrrev_i32_e32 v81, 31, v80
	v_lshlrev_b64 v[80:81], 10, v[80:81]
	v_mul_f32_e32 v83, 0x45800000, v82
	v_cndmask_b32_e32 v82, v82, v83, vcc
	v_lshl_add_u64 v[80:81], s[92:93], 0, v[80:81]
	v_mul_f32_e32 v82, 0x3e0293ee, v82
	v_lshl_add_u64 v[80:81], v[80:81], 0, v[162:163]
	v_pk_mul_f32 v[78:79], v[78:79], v[82:83] op_sel_hi:[1,0]
	v_pk_mul_f32 v[76:77], v[76:77], v[82:83] op_sel_hi:[1,0]
	v_pk_mul_f32 v[84:85], v[74:75], v[82:83] op_sel_hi:[1,0]
	v_pk_mul_f32 v[74:75], v[72:73], v[82:83] op_sel_hi:[1,0]
	v_cvt_pk_bf16_f32 v72, v76, v77
	v_cvt_pk_bf16_f32 v73, v78, v79
	v_pk_mul_f32 v[70:71], v[70:71], v[82:83] op_sel_hi:[1,0]
	v_cvt_pk_bf16_f32 v74, v74, v75
	v_cvt_pk_bf16_f32 v75, v84, v85
	global_store_dwordx4 v[80:81], v[72:75], off
	v_pk_mul_f32 v[68:69], v[68:69], v[82:83] op_sel_hi:[1,0]
	v_cmp_gt_f32_e32 vcc, s58, v167
	v_pk_mul_f32 v[72:73], v[66:67], v[82:83] op_sel_hi:[1,0]
	v_pk_mul_f32 v[66:67], v[64:65], v[82:83] op_sel_hi:[1,0]
	v_cvt_pk_bf16_f32 v64, v68, v69
	v_cvt_pk_bf16_f32 v65, v70, v71
	s_mov_b64 s[2:3], s[30:31]
	v_cvt_pk_bf16_f32 v66, v66, v67
	v_mul_f32_e32 v67, 0x4b800000, v167
	v_cndmask_b32_e32 v67, v167, v67, vcc
	v_rsq_f32_e32 v68, v67
	v_cvt_pk_bf16_f32 v67, v72, v73
	global_store_dwordx4 v[80:81], v[64:67], off offset:256
	s_nop 1
	v_mul_f32_e32 v66, 0x45800000, v68
	v_cndmask_b32_e32 v66, v68, v66, vcc
	v_mul_f32_e32 v66, 0x3e0293ee, v66
	v_pk_mul_f32 v[60:61], v[60:61], v[66:67] op_sel_hi:[1,0]
	v_pk_mul_f32 v[68:69], v[58:59], v[66:67] op_sel_hi:[1,0]
	v_pk_mul_f32 v[58:59], v[56:57], v[66:67] op_sel_hi:[1,0]
	v_cvt_pk_bf16_f32 v56, v60, v61
	v_add_co_u32_e32 v60, vcc, s59, v144
	v_pk_mul_f32 v[62:63], v[62:63], v[66:67] op_sel_hi:[1,0]
	s_nop 0
	v_addc_co_u32_e32 v61, vcc, 0, v145, vcc
	v_cvt_pk_bf16_f32 v57, v62, v63
	v_cvt_pk_bf16_f32 v58, v58, v59
	v_cvt_pk_bf16_f32 v59, v68, v69
	global_store_dwordx4 v[60:61], v[56:59], off
	v_pk_mul_f32 v[54:55], v[54:55], v[66:67] op_sel_hi:[1,0]
	v_pk_mul_f32 v[52:53], v[52:53], v[66:67] op_sel_hi:[1,0]
	v_pk_mul_f32 v[56:57], v[50:51], v[66:67] op_sel_hi:[1,0]
	v_pk_mul_f32 v[50:51], v[48:49], v[66:67] op_sel_hi:[1,0]
	v_cvt_pk_bf16_f32 v48, v52, v53
	v_cvt_pk_bf16_f32 v49, v54, v55
	v_cmp_gt_f32_e32 vcc, s58, v168
	v_cvt_pk_bf16_f32 v50, v50, v51
	v_mul_f32_e32 v51, 0x4b800000, v168
	v_lshl_add_u64 v[64:65], v[144:145], 0, s[14:15]
	v_cndmask_b32_e32 v51, v168, v51, vcc
	v_rsq_f32_e32 v52, v51
	v_cvt_pk_bf16_f32 v51, v56, v57
	global_store_dwordx4 v[64:65], v[48:51], off offset:256
	s_nop 1
	v_mul_f32_e32 v50, 0x45800000, v52
	v_cndmask_b32_e32 v50, v52, v50, vcc
	v_mul_f32_e32 v50, 0x3e0293ee, v50
	v_pk_mul_f32 v[44:45], v[44:45], v[50:51] op_sel_hi:[1,0]
	v_pk_mul_f32 v[52:53], v[42:43], v[50:51] op_sel_hi:[1,0]
	v_pk_mul_f32 v[42:43], v[40:41], v[50:51] op_sel_hi:[1,0]
	v_cvt_pk_bf16_f32 v40, v44, v45
	v_add_co_u32_e32 v44, vcc, s60, v144
	v_pk_mul_f32 v[46:47], v[46:47], v[50:51] op_sel_hi:[1,0]
	s_nop 0
	v_addc_co_u32_e32 v45, vcc, 0, v145, vcc
	v_cvt_pk_bf16_f32 v41, v46, v47
	v_cvt_pk_bf16_f32 v42, v42, v43
	v_cvt_pk_bf16_f32 v43, v52, v53
	global_store_dwordx4 v[44:45], v[40:43], off
	v_pk_mul_f32 v[38:39], v[38:39], v[50:51] op_sel_hi:[1,0]
	v_pk_mul_f32 v[36:37], v[36:37], v[50:51] op_sel_hi:[1,0]
	v_pk_mul_f32 v[40:41], v[34:35], v[50:51] op_sel_hi:[1,0]
	v_pk_mul_f32 v[34:35], v[32:33], v[50:51] op_sel_hi:[1,0]
	v_cvt_pk_bf16_f32 v32, v36, v37
	v_cvt_pk_bf16_f32 v33, v38, v39
	v_cmp_gt_f32_e32 vcc, s58, v169
	v_cvt_pk_bf16_f32 v34, v34, v35
	v_mul_f32_e32 v35, 0x4b800000, v169
	v_lshl_add_u64 v[48:49], v[144:145], 0, s[20:21]
	v_cndmask_b32_e32 v35, v169, v35, vcc
	v_rsq_f32_e32 v36, v35
	v_cvt_pk_bf16_f32 v35, v40, v41
	global_store_dwordx4 v[48:49], v[32:35], off offset:256
	s_nop 1
	v_mul_f32_e32 v34, 0x45800000, v36
	v_cndmask_b32_e32 v34, v36, v34, vcc
	v_mul_f32_e32 v34, 0x3e0293ee, v34
	v_pk_mul_f32 v[28:29], v[28:29], v[34:35] op_sel_hi:[1,0]
	v_pk_mul_f32 v[36:37], v[26:27], v[34:35] op_sel_hi:[1,0]
	v_pk_mul_f32 v[26:27], v[24:25], v[34:35] op_sel_hi:[1,0]
	v_cvt_pk_bf16_f32 v24, v28, v29
	v_add_co_u32_e32 v28, vcc, s61, v144
	v_pk_mul_f32 v[30:31], v[30:31], v[34:35] op_sel_hi:[1,0]
	s_nop 0
	v_addc_co_u32_e32 v29, vcc, 0, v145, vcc
	v_cvt_pk_bf16_f32 v25, v30, v31
	v_cvt_pk_bf16_f32 v26, v26, v27
	v_cvt_pk_bf16_f32 v27, v36, v37
	global_store_dwordx4 v[28:29], v[24:27], off
	v_pk_mul_f32 v[22:23], v[22:23], v[34:35] op_sel_hi:[1,0]
	v_pk_mul_f32 v[20:21], v[20:21], v[34:35] op_sel_hi:[1,0]
	v_pk_mul_f32 v[24:25], v[18:19], v[34:35] op_sel_hi:[1,0]
	v_pk_mul_f32 v[18:19], v[16:17], v[34:35] op_sel_hi:[1,0]
	v_cvt_pk_bf16_f32 v16, v20, v21
	v_cvt_pk_bf16_f32 v17, v22, v23
	v_cmp_gt_f32_e32 vcc, s58, v170
	v_cvt_pk_bf16_f32 v18, v18, v19
	v_mul_f32_e32 v19, 0x4b800000, v170
	v_lshl_add_u64 v[32:33], v[144:145], 0, s[22:23]
	v_cndmask_b32_e32 v19, v170, v19, vcc
	v_rsq_f32_e32 v20, v19
	v_cvt_pk_bf16_f32 v19, v24, v25
	global_store_dwordx4 v[32:33], v[16:19], off offset:256
	s_nop 1
	v_mul_f32_e32 v18, 0x45800000, v20
	v_cndmask_b32_e32 v18, v20, v18, vcc
	v_mul_f32_e32 v18, 0x3e0293ee, v18
	v_pk_mul_f32 v[12:13], v[12:13], v[18:19] op_sel_hi:[1,0]
	v_pk_mul_f32 v[20:21], v[10:11], v[18:19] op_sel_hi:[1,0]
	v_pk_mul_f32 v[10:11], v[8:9], v[18:19] op_sel_hi:[1,0]
	v_cvt_pk_bf16_f32 v8, v12, v13
	v_add_co_u32_e32 v12, vcc, s62, v144
	v_pk_mul_f32 v[14:15], v[14:15], v[18:19] op_sel_hi:[1,0]
	s_nop 0
	v_addc_co_u32_e32 v13, vcc, 0, v145, vcc
	v_cvt_pk_bf16_f32 v9, v14, v15
	v_lshl_add_u64 v[16:17], v[144:145], 0, s[24:25]
	v_cvt_pk_bf16_f32 v10, v10, v11
	v_cvt_pk_bf16_f32 v11, v20, v21
	global_store_dwordx4 v[12:13], v[8:11], off
	s_and_b64 vcc, exec, s[6:7]
	v_pk_mul_f32 v[6:7], v[6:7], v[18:19] op_sel_hi:[1,0]
	v_pk_mul_f32 v[8:9], v[2:3], v[18:19] op_sel_hi:[1,0]
	v_pk_mul_f32 v[2:3], v[0:1], v[18:19] op_sel_hi:[1,0]
	v_pk_mul_f32 v[4:5], v[4:5], v[18:19] op_sel_hi:[1,0]
	s_nop 0
	v_cvt_pk_bf16_f32 v0, v4, v5
	v_cvt_pk_bf16_f32 v1, v6, v7
	v_cvt_pk_bf16_f32 v2, v2, v3
	v_cvt_pk_bf16_f32 v3, v8, v9
	global_store_dwordx4 v[16:17], v[0:3], off offset:256
	s_cbranch_vccz .LBB0_1073
	s_waitcnt vmcnt(0)
	s_cmpk_gt_u32 s33, 0xff
	s_cbranch_scc1 .LBB0_1084
	s_barrier

.LBB0_1217:
	s_ashr_i32 s23, s22, 31
	v_cmp_lt_i64_e32 vcc, s[24:25], v[140:141]
	s_lshl_b64 s[24:25], s[22:23], 19
	s_add_u32 s24, s90, s24
	s_addc_u32 s25, s91, s25
	s_and_b64 s[26:27], vcc, exec
	s_cselect_b32 s23, s25, s29
	s_cselect_b32 s59, s24, s28
	s_ashr_i32 s21, s20, 31
	s_lshl_b64 s[26:27], s[20:21], 19
	s_add_u32 s26, s37, s26
	s_addc_u32 s27, s38, s27
	s_and_b64 s[34:35], vcc, exec
	s_cselect_b32 s21, s27, s31
	s_cselect_b32 s60, s26, s30
	s_add_u32 s28, s28, 0x40080
	s_addc_u32 s29, s29, 0
	s_add_u32 s61, s30, 0x100
	v_lshl_add_u32 v240, s0, 8, v148
	v_ashrrev_i32_e32 v241, 31, v240
	v_lshl_add_u64 v[240:241], v[240:241], 2, s[8:9]
	global_load_dword v242, v[240:241], off
	global_load_dword v243, v[240:241], off offset:64
	global_load_dword v244, v[240:241], off offset:128
	global_load_dword v245, v[240:241], off offset:192
	global_load_dword v246, v[240:241], off offset:512
	global_load_dword v247, v[240:241], off offset:576
	global_load_dword v248, v[240:241], off offset:640
	global_load_dword v249, v[240:241], off offset:704
	v_mov_b32_e32 v0, 0
	s_addc_u32 s62, s31, 0
	s_mov_b32 s63, -2
	v_mov_b32_e32 v1, v0
	v_mov_b64_e32 v[2:3], v[0:1]
	v_mov_b64_e32 v[4:5], v[0:1]
	v_mov_b64_e32 v[6:7], v[0:1]
	v_mov_b64_e32 v[8:9], v[0:1]
	v_mov_b64_e32 v[10:11], v[0:1]
	v_mov_b64_e32 v[12:13], v[0:1]
	v_mov_b64_e32 v[14:15], v[0:1]
	v_mov_b64_e32 v[16:17], v[0:1]
	v_mov_b64_e32 v[18:19], v[0:1]
	v_mov_b64_e32 v[20:21], v[0:1]
	v_mov_b64_e32 v[22:23], v[0:1]
	v_mov_b64_e32 v[24:25], v[0:1]
	v_mov_b64_e32 v[26:27], v[0:1]
	v_mov_b64_e32 v[28:29], v[0:1]
	v_mov_b64_e32 v[30:31], v[0:1]
	v_mov_b64_e32 v[32:33], v[0:1]
	v_mov_b64_e32 v[34:35], v[0:1]
	v_mov_b64_e32 v[36:37], v[0:1]
	v_mov_b64_e32 v[38:39], v[0:1]
	v_mov_b64_e32 v[40:41], v[0:1]
	v_mov_b64_e32 v[42:43], v[0:1]
	v_mov_b64_e32 v[44:45], v[0:1]
	v_mov_b64_e32 v[46:47], v[0:1]
	v_mov_b64_e32 v[48:49], v[0:1]
	v_mov_b64_e32 v[50:51], v[0:1]
	v_mov_b64_e32 v[52:53], v[0:1]
	v_mov_b64_e32 v[54:55], v[0:1]
	v_mov_b64_e32 v[56:57], v[0:1]
	v_mov_b64_e32 v[58:59], v[0:1]
	v_mov_b64_e32 v[60:61], v[0:1]
	v_mov_b64_e32 v[62:63], v[0:1]
	v_mov_b64_e32 v[64:65], v[0:1]
	v_mov_b64_e32 v[66:67], v[0:1]
	v_mov_b64_e32 v[68:69], v[0:1]
	v_mov_b64_e32 v[70:71], v[0:1]
	v_mov_b64_e32 v[72:73], v[0:1]
	v_mov_b64_e32 v[74:75], v[0:1]
	v_mov_b64_e32 v[76:77], v[0:1]
	v_mov_b64_e32 v[78:79], v[0:1]
	v_mov_b64_e32 v[80:81], v[0:1]
	v_mov_b64_e32 v[82:83], v[0:1]
	v_mov_b64_e32 v[84:85], v[0:1]
	v_mov_b64_e32 v[86:87], v[0:1]
	v_mov_b64_e32 v[88:89], v[0:1]
	v_mov_b64_e32 v[90:91], v[0:1]
	v_mov_b64_e32 v[92:93], v[0:1]
	v_mov_b64_e32 v[94:95], v[0:1]
	v_mov_b64_e32 v[96:97], v[0:1]
	v_mov_b64_e32 v[98:99], v[0:1]
	v_mov_b64_e32 v[100:101], v[0:1]
	v_mov_b64_e32 v[102:103], v[0:1]
	v_mov_b64_e32 v[104:105], v[0:1]
	v_mov_b64_e32 v[106:107], v[0:1]
	v_mov_b64_e32 v[108:109], v[0:1]
	v_mov_b64_e32 v[110:111], v[0:1]
	v_mov_b64_e32 v[112:113], v[0:1]
	v_mov_b64_e32 v[114:115], v[0:1]
	v_mov_b64_e32 v[116:117], v[0:1]
	v_mov_b64_e32 v[118:119], v[0:1]
	v_mov_b64_e32 v[120:121], v[0:1]
	v_mov_b64_e32 v[122:123], v[0:1]
	v_mov_b64_e32 v[124:125], v[0:1]
	v_mov_b64_e32 v[126:127], v[0:1]
.LBB0_1218:
	ds_read_b128 v[144:147], v151
	ds_read_b128 v[156:159], v151 offset:1024
	ds_read_b128 v[160:163], v151 offset:2048
	ds_read_b128 v[164:167], v151 offset:3072
	s_add_u32 s30, s28, 0xfffc0080
	s_addc_u32 s31, s29, -1
	s_cmp_eq_u32 s63, 12
	s_cselect_b32 s35, s23, s31
	s_cselect_b32 s34, s59, s30
	s_cselect_b32 s31, s21, s62
	s_cselect_b32 s30, s60, s61
	v_lshl_add_u64 v[172:173], s[28:29], 0, v[136:137]
	s_add_i32 m0, s40, 0xc000
	ds_read_b128 v[168:171], v152
	ds_read_b128 v[176:179], v152 offset:1024
	ds_read_b128 v[180:183], v152 offset:2048
	ds_read_b128 v[184:187], v152 offset:3072
	ds_read_b128 v[188:191], v152 offset:4096
	ds_read_b128 v[192:195], v152 offset:5120
	ds_read_b128 v[196:199], v152 offset:6144
	ds_read_b128 v[200:203], v152 offset:7168
	global_load_lds_dwordx4 v[172:173], off
	s_add_i32 m0, s40, 0xe000
	v_lshl_add_u64 v[172:173], s[28:29], 0, v[138:139]
	global_load_lds_dwordx4 v[172:173], off
	s_waitcnt lgkmcnt(8)
	s_setprio 1
	s_barrier
	s_waitcnt lgkmcnt(0)
	v_mfma_f32_16x16x32_bf16 v[124:127], v[144:147], v[168:171], v[124:127]
	v_mfma_f32_16x16x32_bf16 v[120:123], v[160:163], v[168:171], v[120:123]
	v_mfma_f32_16x16x32_bf16 v[116:119], v[144:147], v[180:183], v[116:119]
	v_mfma_f32_16x16x32_bf16 v[112:115], v[160:163], v[180:183], v[112:115]
	v_mfma_f32_16x16x32_bf16 v[92:95], v[144:147], v[188:191], v[92:95]
	v_mfma_f32_16x16x32_bf16 v[88:91], v[160:163], v[188:191], v[88:91]
	v_mfma_f32_16x16x32_bf16 v[76:79], v[144:147], v[196:199], v[76:79]
	v_mfma_f32_16x16x32_bf16 v[72:75], v[160:163], v[196:199], v[72:75]
	v_mfma_f32_16x16x32_bf16 v[124:127], v[156:159], v[176:179], v[124:127]
	v_mfma_f32_16x16x32_bf16 v[120:123], v[164:167], v[176:179], v[120:123]
	v_mfma_f32_16x16x32_bf16 v[116:119], v[156:159], v[184:187], v[116:119]
	v_mfma_f32_16x16x32_bf16 v[112:115], v[164:167], v[184:187], v[112:115]
	v_mfma_f32_16x16x32_bf16 v[92:95], v[156:159], v[192:195], v[92:95]
	v_mfma_f32_16x16x32_bf16 v[88:91], v[164:167], v[192:195], v[88:91]
	v_mfma_f32_16x16x32_bf16 v[76:79], v[156:159], v[200:203], v[76:79]
	v_mfma_f32_16x16x32_bf16 v[72:75], v[164:167], v[200:203], v[72:75]
	s_barrier
	s_setprio 0
	s_add_i32 s64, s52, s39
	v_lshl_add_u64 v[172:173], s[30:31], 0, v[130:131]
	s_mov_b32 m0, s64
	ds_read_b128 v[204:207], v153
	ds_read_b128 v[212:215], v153 offset:1024
	ds_read_b128 v[216:219], v153 offset:2048
	ds_read_b128 v[220:223], v153 offset:3072
	global_load_lds_dwordx4 v[172:173], off
	s_add_i32 m0, s64, 0x2000
	v_lshl_add_u64 v[208:209], s[30:31], 0, v[134:135]
	global_load_lds_dwordx4 v[208:209], off
	s_setprio 1
	s_barrier
	s_waitcnt lgkmcnt(0)
	v_mfma_f32_16x16x32_bf16 v[108:111], v[204:207], v[168:171], v[108:111]
	v_mfma_f32_16x16x32_bf16 v[104:107], v[216:219], v[168:171], v[104:107]
	v_mfma_f32_16x16x32_bf16 v[100:103], v[204:207], v[180:183], v[100:103]
	v_mfma_f32_16x16x32_bf16 v[96:99], v[216:219], v[180:183], v[96:99]
	v_mfma_f32_16x16x32_bf16 v[84:87], v[204:207], v[188:191], v[84:87]
	v_mfma_f32_16x16x32_bf16 v[80:83], v[216:219], v[188:191], v[80:83]
	v_mfma_f32_16x16x32_bf16 v[68:71], v[204:207], v[196:199], v[68:71]
	v_mfma_f32_16x16x32_bf16 v[64:67], v[216:219], v[196:199], v[64:67]
	v_mfma_f32_16x16x32_bf16 v[108:111], v[212:215], v[176:179], v[108:111]
	v_mfma_f32_16x16x32_bf16 v[104:107], v[220:223], v[176:179], v[104:107]
	v_mfma_f32_16x16x32_bf16 v[100:103], v[212:215], v[184:187], v[100:103]
	v_mfma_f32_16x16x32_bf16 v[96:99], v[220:223], v[184:187], v[96:99]
	v_mfma_f32_16x16x32_bf16 v[84:87], v[212:215], v[192:195], v[84:87]
	v_mfma_f32_16x16x32_bf16 v[80:83], v[220:223], v[192:195], v[80:83]
	v_mfma_f32_16x16x32_bf16 v[68:71], v[212:215], v[200:203], v[68:71]
	v_mfma_f32_16x16x32_bf16 v[64:67], v[220:223], v[200:203], v[64:67]
	s_barrier
	s_setprio 0
	s_mov_b32 m0, s40
	v_lshl_add_u64 v[224:225], s[34:35], 0, v[128:129]
	ds_read_b128 v[168:171], v152 offset:16384
	ds_read_b128 v[176:179], v152 offset:17408
	ds_read_b128 v[180:183], v152 offset:18432
	ds_read_b128 v[184:187], v152 offset:19456
	ds_read_b128 v[188:191], v152 offset:20480
	ds_read_b128 v[192:195], v152 offset:21504
	ds_read_b128 v[196:199], v152 offset:22528
	ds_read_b128 v[200:203], v152 offset:23552
	global_load_lds_dwordx4 v[224:225], off
	s_mov_b32 m0, s41
	v_lshl_add_u64 v[226:227], s[34:35], 0, v[132:133]
	global_load_lds_dwordx4 v[226:227], off
	s_setprio 1
	s_barrier
	s_waitcnt lgkmcnt(0)
	v_mfma_f32_16x16x32_bf16 v[60:63], v[144:147], v[168:171], v[60:63]
	v_mfma_f32_16x16x32_bf16 v[56:59], v[160:163], v[168:171], v[56:59]
	v_mfma_f32_16x16x32_bf16 v[44:47], v[144:147], v[180:183], v[44:47]
	v_mfma_f32_16x16x32_bf16 v[40:43], v[160:163], v[180:183], v[40:43]
	v_mfma_f32_16x16x32_bf16 v[28:31], v[144:147], v[188:191], v[28:31]
	v_mfma_f32_16x16x32_bf16 v[24:27], v[160:163], v[188:191], v[24:27]
	v_mfma_f32_16x16x32_bf16 v[12:15], v[144:147], v[196:199], v[12:15]
	v_mfma_f32_16x16x32_bf16 v[8:11], v[160:163], v[196:199], v[8:11]
	v_mfma_f32_16x16x32_bf16 v[60:63], v[156:159], v[176:179], v[60:63]
	v_mfma_f32_16x16x32_bf16 v[56:59], v[164:167], v[176:179], v[56:59]
	v_mfma_f32_16x16x32_bf16 v[44:47], v[156:159], v[184:187], v[44:47]
	v_mfma_f32_16x16x32_bf16 v[40:43], v[164:167], v[184:187], v[40:43]
	v_mfma_f32_16x16x32_bf16 v[28:31], v[156:159], v[192:195], v[28:31]
	v_mfma_f32_16x16x32_bf16 v[24:27], v[164:167], v[192:195], v[24:27]
	v_mfma_f32_16x16x32_bf16 v[12:15], v[156:159], v[200:203], v[12:15]
	v_mfma_f32_16x16x32_bf16 v[8:11], v[164:167], v[200:203], v[8:11]
	s_barrier
	s_setprio 0
	s_add_u32 s64, s30, 0x40000
	s_addc_u32 s65, s31, 0
	s_add_i32 s66, s53, s39
	s_mov_b32 m0, s66
	v_lshl_add_u64 v[144:145], s[64:65], 0, v[130:131]
	global_load_lds_dwordx4 v[144:145], off
	s_add_i32 m0, s66, 0x2000
	v_lshl_add_u64 v[144:145], s[64:65], 0, v[134:135]
	global_load_lds_dwordx4 v[144:145], off
	s_waitcnt vmcnt(6)
	s_setprio 1
	s_barrier
	v_mfma_f32_16x16x32_bf16 v[52:55], v[204:207], v[168:171], v[52:55]
	v_mfma_f32_16x16x32_bf16 v[48:51], v[216:219], v[168:171], v[48:51]
	v_mfma_f32_16x16x32_bf16 v[36:39], v[204:207], v[180:183], v[36:39]
	v_mfma_f32_16x16x32_bf16 v[32:35], v[216:219], v[180:183], v[32:35]
	v_mfma_f32_16x16x32_bf16 v[20:23], v[204:207], v[188:191], v[20:23]
	v_mfma_f32_16x16x32_bf16 v[16:19], v[216:219], v[188:191], v[16:19]
	v_mfma_f32_16x16x32_bf16 v[4:7], v[204:207], v[196:199], v[4:7]
	v_mfma_f32_16x16x32_bf16 v[0:3], v[216:219], v[196:199], v[0:3]
	v_mfma_f32_16x16x32_bf16 v[52:55], v[212:215], v[176:179], v[52:55]
	v_mfma_f32_16x16x32_bf16 v[48:51], v[220:223], v[176:179], v[48:51]
	v_mfma_f32_16x16x32_bf16 v[36:39], v[212:215], v[184:187], v[36:39]
	v_mfma_f32_16x16x32_bf16 v[32:35], v[220:223], v[184:187], v[32:35]
	v_mfma_f32_16x16x32_bf16 v[20:23], v[212:215], v[192:195], v[20:23]
	v_mfma_f32_16x16x32_bf16 v[16:19], v[220:223], v[192:195], v[16:19]
	v_mfma_f32_16x16x32_bf16 v[4:7], v[212:215], v[200:203], v[4:7]
	v_mfma_f32_16x16x32_bf16 v[0:3], v[220:223], v[200:203], v[0:3]
	s_barrier
	s_setprio 0
	s_add_i32 s64, 0, 0x18000
	v_add_u32_e32 v155, s64, v149
	ds_read_b128 v[144:147], v155
	ds_read_b128 v[156:159], v155 offset:1024
	ds_read_b128 v[160:163], v155 offset:2048
	ds_read_b128 v[164:167], v155 offset:3072
	s_add_u32 s34, s34, 0x40000
	s_addc_u32 s35, s35, 0
	s_mov_b32 m0, s42
	v_lshl_add_u64 v[204:205], s[34:35], 0, v[128:129]
	ds_read_b128 v[168:171], v152 offset:32768
	ds_read_b128 v[176:179], v152 offset:33792
	ds_read_b128 v[180:183], v152 offset:34816
	ds_read_b128 v[184:187], v152 offset:35840
	ds_read_b128 v[188:191], v152 offset:36864
	ds_read_b128 v[192:195], v152 offset:37888
	ds_read_b128 v[196:199], v152 offset:38912
	ds_read_b128 v[200:203], v152 offset:39936
	global_load_lds_dwordx4 v[204:205], off
	s_mov_b32 m0, s43
	v_lshl_add_u64 v[204:205], s[34:35], 0, v[132:133]
	global_load_lds_dwordx4 v[204:205], off
	s_waitcnt lgkmcnt(8)
	s_setprio 1
	s_barrier
	s_waitcnt lgkmcnt(0)
	v_mfma_f32_16x16x32_bf16 v[124:127], v[144:147], v[168:171], v[124:127]
	v_mfma_f32_16x16x32_bf16 v[120:123], v[160:163], v[168:171], v[120:123]
	v_mfma_f32_16x16x32_bf16 v[116:119], v[144:147], v[180:183], v[116:119]
	v_mfma_f32_16x16x32_bf16 v[112:115], v[160:163], v[180:183], v[112:115]
	v_mfma_f32_16x16x32_bf16 v[92:95], v[144:147], v[188:191], v[92:95]
	v_mfma_f32_16x16x32_bf16 v[88:91], v[160:163], v[188:191], v[88:91]
	v_mfma_f32_16x16x32_bf16 v[76:79], v[144:147], v[196:199], v[76:79]
	v_mfma_f32_16x16x32_bf16 v[72:75], v[160:163], v[196:199], v[72:75]
	v_mfma_f32_16x16x32_bf16 v[124:127], v[156:159], v[176:179], v[124:127]
	v_mfma_f32_16x16x32_bf16 v[120:123], v[164:167], v[176:179], v[120:123]
	v_mfma_f32_16x16x32_bf16 v[116:119], v[156:159], v[184:187], v[116:119]
	v_mfma_f32_16x16x32_bf16 v[112:115], v[164:167], v[184:187], v[112:115]
	v_mfma_f32_16x16x32_bf16 v[92:95], v[156:159], v[192:195], v[92:95]
	v_mfma_f32_16x16x32_bf16 v[88:91], v[164:167], v[192:195], v[88:91]
	v_mfma_f32_16x16x32_bf16 v[76:79], v[156:159], v[200:203], v[76:79]
	v_mfma_f32_16x16x32_bf16 v[72:75], v[164:167], v[200:203], v[72:75]
	s_barrier
	s_setprio 0
	s_add_i32 s34, 0, 0x1c000
	s_add_i32 s35, s64, s39
	v_add_u32_e32 v155, s34, v149
	v_lshl_add_u64 v[172:173], v[172:173], 0, s[6:7]
	s_mov_b32 m0, s35
	ds_read_b128 v[204:207], v155
	ds_read_b128 v[212:215], v155 offset:1024
	ds_read_b128 v[216:219], v155 offset:2048
	ds_read_b128 v[220:223], v155 offset:3072
	global_load_lds_dwordx4 v[172:173], off
	s_add_i32 m0, s35, 0x2000
	v_lshl_add_u64 v[172:173], v[208:209], 0, s[6:7]
	global_load_lds_dwordx4 v[172:173], off
	s_setprio 1
	s_barrier
	s_waitcnt lgkmcnt(0)
	v_mfma_f32_16x16x32_bf16 v[108:111], v[204:207], v[168:171], v[108:111]
	v_mfma_f32_16x16x32_bf16 v[104:107], v[216:219], v[168:171], v[104:107]
	v_mfma_f32_16x16x32_bf16 v[100:103], v[204:207], v[180:183], v[100:103]
	v_mfma_f32_16x16x32_bf16 v[96:99], v[216:219], v[180:183], v[96:99]
	v_mfma_f32_16x16x32_bf16 v[84:87], v[204:207], v[188:191], v[84:87]
	v_mfma_f32_16x16x32_bf16 v[80:83], v[216:219], v[188:191], v[80:83]
	v_mfma_f32_16x16x32_bf16 v[68:71], v[204:207], v[196:199], v[68:71]
	v_mfma_f32_16x16x32_bf16 v[64:67], v[216:219], v[196:199], v[64:67]
	v_mfma_f32_16x16x32_bf16 v[108:111], v[212:215], v[176:179], v[108:111]
	v_mfma_f32_16x16x32_bf16 v[104:107], v[220:223], v[176:179], v[104:107]
	v_mfma_f32_16x16x32_bf16 v[100:103], v[212:215], v[184:187], v[100:103]
	v_mfma_f32_16x16x32_bf16 v[96:99], v[220:223], v[184:187], v[96:99]
	v_mfma_f32_16x16x32_bf16 v[84:87], v[212:215], v[192:195], v[84:87]
	v_mfma_f32_16x16x32_bf16 v[80:83], v[220:223], v[192:195], v[80:83]
	v_mfma_f32_16x16x32_bf16 v[68:71], v[212:215], v[200:203], v[68:71]
	v_mfma_f32_16x16x32_bf16 v[64:67], v[220:223], v[200:203], v[64:67]
	s_barrier
	s_setprio 0
	s_mov_b32 m0, s49
	v_lshl_add_u64 v[172:173], v[224:225], 0, s[6:7]
	ds_read_b128 v[168:171], v152 offset:49152
	ds_read_b128 v[176:179], v152 offset:50176
	ds_read_b128 v[180:183], v152 offset:51200
	ds_read_b128 v[184:187], v152 offset:52224
	ds_read_b128 v[188:191], v152 offset:53248
	ds_read_b128 v[192:195], v152 offset:54272
	ds_read_b128 v[196:199], v152 offset:55296
	ds_read_b128 v[200:203], v152 offset:56320
	global_load_lds_dwordx4 v[172:173], off
	s_mov_b32 m0, s50
	v_lshl_add_u64 v[172:173], v[226:227], 0, s[6:7]
	global_load_lds_dwordx4 v[172:173], off
	s_setprio 1
	s_barrier
	s_waitcnt lgkmcnt(0)
	v_mfma_f32_16x16x32_bf16 v[60:63], v[144:147], v[168:171], v[60:63]
	v_mfma_f32_16x16x32_bf16 v[56:59], v[160:163], v[168:171], v[56:59]
	v_mfma_f32_16x16x32_bf16 v[44:47], v[144:147], v[180:183], v[44:47]
	v_mfma_f32_16x16x32_bf16 v[40:43], v[160:163], v[180:183], v[40:43]
	v_mfma_f32_16x16x32_bf16 v[28:31], v[144:147], v[188:191], v[28:31]
	v_mfma_f32_16x16x32_bf16 v[24:27], v[160:163], v[188:191], v[24:27]
	v_mfma_f32_16x16x32_bf16 v[12:15], v[144:147], v[196:199], v[12:15]
	v_mfma_f32_16x16x32_bf16 v[8:11], v[160:163], v[196:199], v[8:11]
	v_mfma_f32_16x16x32_bf16 v[60:63], v[156:159], v[176:179], v[60:63]
	v_mfma_f32_16x16x32_bf16 v[56:59], v[164:167], v[176:179], v[56:59]
	v_mfma_f32_16x16x32_bf16 v[44:47], v[156:159], v[184:187], v[44:47]
	v_mfma_f32_16x16x32_bf16 v[40:43], v[164:167], v[184:187], v[40:43]
	v_mfma_f32_16x16x32_bf16 v[28:31], v[156:159], v[192:195], v[28:31]
	v_mfma_f32_16x16x32_bf16 v[24:27], v[164:167], v[192:195], v[24:27]
	v_mfma_f32_16x16x32_bf16 v[12:15], v[156:159], v[200:203], v[12:15]
	v_mfma_f32_16x16x32_bf16 v[8:11], v[164:167], v[200:203], v[8:11]
	s_barrier
	s_setprio 0
	s_add_u32 s30, s30, 0x40080
	s_addc_u32 s31, s31, 0
	s_add_i32 s34, s34, s39
	s_mov_b32 m0, s34
	v_lshl_add_u64 v[144:145], s[30:31], 0, v[130:131]
	global_load_lds_dwordx4 v[144:145], off
	s_add_i32 m0, s34, 0x2000
	v_lshl_add_u64 v[144:145], s[30:31], 0, v[134:135]
	global_load_lds_dwordx4 v[144:145], off
	s_waitcnt vmcnt(6)
	s_setprio 1
	s_barrier
	v_mfma_f32_16x16x32_bf16 v[52:55], v[204:207], v[168:171], v[52:55]
	v_mfma_f32_16x16x32_bf16 v[48:51], v[216:219], v[168:171], v[48:51]
	v_mfma_f32_16x16x32_bf16 v[36:39], v[204:207], v[180:183], v[36:39]
	v_mfma_f32_16x16x32_bf16 v[32:35], v[216:219], v[180:183], v[32:35]
	v_mfma_f32_16x16x32_bf16 v[20:23], v[204:207], v[188:191], v[20:23]
	v_mfma_f32_16x16x32_bf16 v[16:19], v[216:219], v[188:191], v[16:19]
	v_mfma_f32_16x16x32_bf16 v[4:7], v[204:207], v[196:199], v[4:7]
	v_mfma_f32_16x16x32_bf16 v[0:3], v[216:219], v[196:199], v[0:3]
	v_mfma_f32_16x16x32_bf16 v[52:55], v[212:215], v[176:179], v[52:55]
	v_mfma_f32_16x16x32_bf16 v[48:51], v[220:223], v[176:179], v[48:51]
	v_mfma_f32_16x16x32_bf16 v[36:39], v[212:215], v[184:187], v[36:39]
	v_mfma_f32_16x16x32_bf16 v[32:35], v[220:223], v[184:187], v[32:35]
	v_mfma_f32_16x16x32_bf16 v[20:23], v[212:215], v[192:195], v[20:23]
	v_mfma_f32_16x16x32_bf16 v[16:19], v[220:223], v[192:195], v[16:19]
	v_mfma_f32_16x16x32_bf16 v[4:7], v[212:215], v[200:203], v[4:7]
	v_mfma_f32_16x16x32_bf16 v[0:3], v[220:223], v[200:203], v[0:3]
	s_barrier
	s_setprio 0
	s_add_i32 s63, s63, 2
	s_add_u32 s28, s28, 0x100
	s_addc_u32 s29, s29, 0
	s_add_u32 s61, s61, 0x100
	s_addc_u32 s62, s62, 0
	s_cmp_gt_u32 s63, 13
	s_cbranch_scc0 .LBB0_1218
	v_lshl_add_u32 v146, s0, 8, v148
	v_ashrrev_i32_e32 v147, 31, v146
	v_mov_b32_e32 v155, v242
	v_mov_b32_e32 v162, v243
	v_mov_b32_e32 v163, v244
	v_mov_b32_e32 v164, v245
	v_mov_b32_e32 v165, v246
	v_mov_b32_e32 v166, v247
	v_mov_b32_e32 v167, v248
	v_mov_b32_e32 v168, v249
	v_lshl_or_b32 v144, s1, 8, v150
	v_ashrrev_i32_e32 v145, 31, v144
	v_lshlrev_b64 v[158:159], 13, v[146:147]
	v_lshlrev_b64 v[160:161], 1, v[144:145]
	v_lshl_add_u64 v[144:145], s[92:93], 0, v[158:159]
	v_lshl_add_u64 v[144:145], v[144:145], 0, v[160:161]
	v_or_b32_e32 v156, 16, v146
	v_ashrrev_i32_e32 v157, 31, v156
	v_lshlrev_b64 v[156:157], 13, v[156:157]
	v_lshl_add_u64 v[156:157], s[92:93], 0, v[156:157]
	v_lshl_add_u64 v[156:157], v[156:157], 0, v[160:161]
	s_mov_b64 s[30:31], s[26:27]
	s_mov_b64 s[28:29], s[24:25]
	v_fmamk_f32 v147, v155, 0x3a800000, v154
	v_mul_f32_e32 v158, 0x4b800000, v147
	v_cmp_gt_f32_e32 vcc, s54, v147
	v_fmamk_f32 v155, v162, 0x3a800000, v154
	v_mul_f32_e32 v162, 0x4b800000, v155
	v_cndmask_b32_e32 v147, v147, v158, vcc
	v_rsq_f32_e32 v158, v147
	v_cmp_gt_f32_e64 s[0:1], s54, v155
	v_fmamk_f32 v159, v163, 0x3a800000, v154
	v_fmamk_f32 v163, v164, 0x3a800000, v154
	v_cndmask_b32_e64 v155, v155, v162, s[0:1]
	v_rsq_f32_e32 v155, v155
	v_mul_f32_e32 v162, 0x45800000, v158
	v_cndmask_b32_e32 v158, v158, v162, vcc
	v_pk_mul_f32 v[124:125], v[124:125], v[158:159] op_sel_hi:[1,0]
	v_pk_mul_f32 v[104:105], v[104:105], v[158:159] op_sel_hi:[1,0]
	v_fmamk_f32 v164, v165, 0x3a800000, v154
	v_fmamk_f32 v165, v166, 0x3a800000, v154
	v_fmamk_f32 v166, v167, 0x3a800000, v154
	v_mul_f32_e32 v167, 0x45800000, v155
	v_pk_mul_f32 v[126:127], v[126:127], v[158:159] op_sel_hi:[1,0]
	v_pk_mul_f32 v[122:123], v[122:123], v[158:159] op_sel_hi:[1,0]
	v_pk_mul_f32 v[120:121], v[120:121], v[158:159] op_sel_hi:[1,0]
	v_pk_mul_f32 v[108:109], v[108:109], v[158:159] op_sel_hi:[1,0]
	v_pk_mul_f32 v[106:107], v[106:107], v[158:159] op_sel_hi:[1,0]
	v_max_f32_e32 v124, 0, v124
	v_max_f32_e32 v125, 0, v125
	v_max_f32_e32 v104, 0, v104
	v_cndmask_b32_e64 v162, v155, v167, s[0:1]
	v_pk_mul_f32 v[110:111], v[110:111], v[158:159] op_sel_hi:[1,0]
	v_max_f32_e32 v120, 0, v120
	v_max_f32_e32 v121, 0, v121
	v_max_f32_e32 v126, 0, v126
	v_max_f32_e32 v122, 0, v122
	v_max_f32_e32 v127, 0, v127
	v_max_f32_e32 v123, 0, v123
	v_max_f32_e32 v108, 0, v108
	v_max_f32_e32 v109, 0, v109
	v_max_f32_e32 v105, 0, v105
	v_max_f32_e32 v106, 0, v106
	v_max_f32_e32 v107, 0, v107
	v_mul_f32_e32 v124, v124, v124
	v_mul_f32_e32 v125, v125, v125
	v_mul_f32_e32 v155, v104, v104
	v_cvt_pk_bf16_f32 v104, v124, v125
	v_fmamk_f32 v147, v168, 0x3a800000, v154
	v_pk_mul_f32 v[112:113], v[112:113], v[162:163] op_sel_hi:[1,0]
	v_max_f32_e32 v110, 0, v110
	v_max_f32_e32 v111, 0, v111
	v_mul_f32_e32 v120, v120, v120
	v_mul_f32_e32 v121, v121, v121
	v_mul_f32_e32 v126, v126, v126
	v_mul_f32_e32 v122, v122, v122
	v_mul_f32_e32 v127, v127, v127
	v_mul_f32_e32 v123, v123, v123
	v_mul_f32_e32 v108, v108, v108
	v_mul_f32_e32 v109, v109, v109
	v_mul_f32_e32 v158, v105, v105
	v_mul_f32_e32 v167, v106, v106
	v_mul_f32_e32 v168, v107, v107
	v_cvt_pk_bf16_f32 v105, v126, v127
	v_cvt_pk_bf16_f32 v106, v120, v121
	v_cvt_pk_bf16_f32 v107, v122, v123
	global_store_dwordx4 v[144:145], v[104:107], off nt
	v_pk_mul_f32 v[116:117], v[116:117], v[162:163] op_sel_hi:[1,0]
	v_mul_f32_e32 v110, v110, v110
	v_cvt_pk_bf16_f32 v104, v108, v109
	v_mul_f32_e32 v111, v111, v111
	v_cvt_pk_bf16_f32 v105, v110, v111
	v_cvt_pk_bf16_f32 v106, v155, v158
	v_cvt_pk_bf16_f32 v107, v167, v168
	global_store_dwordx4 v[144:145], v[104:107], off offset:256 nt
	v_pk_mul_f32 v[118:119], v[118:119], v[162:163] op_sel_hi:[1,0]
	v_pk_mul_f32 v[114:115], v[114:115], v[162:163] op_sel_hi:[1,0]
	v_max_f32_e32 v104, 0, v112
	v_mul_f32_e32 v106, v104, v104
	v_max_f32_e32 v104, 0, v117
	v_max_f32_e32 v116, 0, v116
	v_max_f32_e32 v107, 0, v113
	v_mul_f32_e32 v104, v104, v104
	v_pk_mul_f32 v[98:99], v[98:99], v[162:163] op_sel_hi:[1,0]
	v_pk_mul_f32 v[96:97], v[96:97], v[162:163] op_sel_hi:[1,0]
	v_mul_f32_e32 v105, v116, v116
	v_mul_f32_e32 v107, v107, v107
	v_max_f32_e32 v108, 0, v118
	v_max_f32_e32 v109, 0, v114
	v_max_f32_e32 v110, 0, v119
	v_max_f32_e32 v111, 0, v115
	v_cvt_pk_bf16_f32 v104, v105, v104
	v_pk_mul_f32 v[102:103], v[102:103], v[162:163] op_sel_hi:[1,0]
	v_pk_mul_f32 v[100:101], v[100:101], v[162:163] op_sel_hi:[1,0]
	v_max_f32_e32 v96, 0, v96
	v_max_f32_e32 v97, 0, v97
	v_max_f32_e32 v98, 0, v98
	v_mul_f32_e32 v108, v108, v108
	v_mul_f32_e32 v109, v109, v109
	v_mul_f32_e32 v110, v110, v110
	v_mul_f32_e32 v111, v111, v111
	v_cvt_pk_bf16_f32 v105, v108, v110
	v_cvt_pk_bf16_f32 v106, v106, v107
	v_cvt_pk_bf16_f32 v107, v109, v111
	global_store_dwordx4 v[156:157], v[104:107], off nt
	v_max_f32_e32 v100, 0, v100
	v_max_f32_e32 v99, 0, v99
	v_mul_f32_e32 v104, v96, v96
	v_max_f32_e32 v96, 0, v101
	v_mul_f32_e32 v101, v97, v97
	v_max_f32_e32 v97, 0, v102
	v_mul_f32_e32 v102, v98, v98
	v_max_f32_e32 v98, 0, v103
	v_mul_f32_e32 v96, v96, v96
	v_mul_f32_e32 v97, v97, v97
	v_mul_f32_e32 v98, v98, v98
	v_mul_f32_e32 v100, v100, v100
	v_mul_f32_e32 v99, v99, v99
	v_cvt_pk_bf16_f32 v96, v100, v96
	v_cvt_pk_bf16_f32 v97, v97, v98
	v_cvt_pk_bf16_f32 v98, v104, v101
	v_cvt_pk_bf16_f32 v99, v102, v99
	global_store_dwordx4 v[156:157], v[96:99], off offset:256 nt
	v_cmp_gt_f32_e32 vcc, s54, v159
	s_mov_b32 s1, s20
	v_mul_f32_e32 v98, 0x4b800000, v159
	v_cndmask_b32_e32 v98, v159, v98, vcc
	v_rsq_f32_e32 v98, v98
	v_or_b32_e32 v96, 32, v146
	v_ashrrev_i32_e32 v97, 31, v96
	v_lshlrev_b64 v[96:97], 13, v[96:97]
	v_mul_f32_e32 v99, 0x45800000, v98
	v_cndmask_b32_e32 v98, v98, v99, vcc
	v_pk_mul_f32 v[88:89], v[88:89], v[98:99] op_sel_hi:[1,0]
	v_pk_mul_f32 v[92:93], v[92:93], v[98:99] op_sel_hi:[1,0]
	v_pk_mul_f32 v[90:91], v[90:91], v[98:99] op_sel_hi:[1,0]
	v_max_f32_e32 v88, 0, v88
	v_pk_mul_f32 v[94:95], v[94:95], v[98:99] op_sel_hi:[1,0]
	v_mul_f32_e32 v99, v88, v88
	v_max_f32_e32 v88, 0, v93
	v_max_f32_e32 v89, 0, v89
	v_max_f32_e32 v90, 0, v90
	v_lshl_add_u64 v[96:97], s[92:93], 0, v[96:97]
	v_max_f32_e32 v92, 0, v92
	v_mul_f32_e32 v88, v88, v88
	v_mul_f32_e32 v93, v89, v89
	v_max_f32_e32 v89, 0, v94
	v_mul_f32_e32 v94, v90, v90
	v_max_f32_e32 v90, 0, v95
	v_max_f32_e32 v91, 0, v91
	v_pk_mul_f32 v[82:83], v[82:83], v[98:99] op_sel_hi:[1,0]
	v_pk_mul_f32 v[80:81], v[80:81], v[98:99] op_sel_hi:[1,0]
	v_lshl_add_u64 v[96:97], v[96:97], 0, v[160:161]
	v_mul_f32_e32 v92, v92, v92
	v_mul_f32_e32 v89, v89, v89
	v_mul_f32_e32 v90, v90, v90
	v_mul_f32_e32 v91, v91, v91
	v_cvt_pk_bf16_f32 v88, v92, v88
	v_pk_mul_f32 v[86:87], v[86:87], v[98:99] op_sel_hi:[1,0]
	v_pk_mul_f32 v[84:85], v[84:85], v[98:99] op_sel_hi:[1,0]
	v_max_f32_e32 v80, 0, v80
	v_max_f32_e32 v81, 0, v81
	v_max_f32_e32 v82, 0, v82
	v_cvt_pk_bf16_f32 v89, v89, v90
	v_cvt_pk_bf16_f32 v90, v99, v93
	v_cvt_pk_bf16_f32 v91, v94, v91
	global_store_dwordx4 v[96:97], v[88:91], off nt
	v_max_f32_e32 v84, 0, v84
	v_max_f32_e32 v83, 0, v83
	v_mul_f32_e32 v88, v80, v80
	v_max_f32_e32 v80, 0, v85
	v_mul_f32_e32 v85, v81, v81
	v_max_f32_e32 v81, 0, v86
	v_mul_f32_e32 v86, v82, v82
	v_max_f32_e32 v82, 0, v87
	v_mul_f32_e32 v80, v80, v80
	v_mul_f32_e32 v81, v81, v81
	v_mul_f32_e32 v82, v82, v82
	v_mul_f32_e32 v84, v84, v84
	v_mul_f32_e32 v83, v83, v83
	v_cvt_pk_bf16_f32 v80, v84, v80
	v_cvt_pk_bf16_f32 v81, v81, v82
	v_cvt_pk_bf16_f32 v82, v88, v85
	v_cvt_pk_bf16_f32 v83, v86, v83
	global_store_dwordx4 v[96:97], v[80:83], off offset:256 nt
	v_cmp_gt_f32_e32 vcc, s54, v163
	s_mov_b32 s0, s22
	v_mul_f32_e32 v82, 0x4b800000, v163
	v_cndmask_b32_e32 v82, v163, v82, vcc
	v_rsq_f32_e32 v82, v82
	v_or_b32_e32 v80, 48, v146
	v_ashrrev_i32_e32 v81, 31, v80
	v_lshlrev_b64 v[80:81], 13, v[80:81]
	v_mul_f32_e32 v83, 0x45800000, v82
	v_cndmask_b32_e32 v82, v82, v83, vcc
	v_pk_mul_f32 v[72:73], v[72:73], v[82:83] op_sel_hi:[1,0]
	v_pk_mul_f32 v[76:77], v[76:77], v[82:83] op_sel_hi:[1,0]
	v_pk_mul_f32 v[74:75], v[74:75], v[82:83] op_sel_hi:[1,0]
	v_max_f32_e32 v72, 0, v72
	v_pk_mul_f32 v[78:79], v[78:79], v[82:83] op_sel_hi:[1,0]
	v_mul_f32_e32 v83, v72, v72
	v_max_f32_e32 v72, 0, v77
	v_max_f32_e32 v73, 0, v73
	v_max_f32_e32 v74, 0, v74
	v_lshl_add_u64 v[80:81], s[92:93], 0, v[80:81]
	v_max_f32_e32 v76, 0, v76
	v_mul_f32_e32 v72, v72, v72
	v_mul_f32_e32 v77, v73, v73
	v_max_f32_e32 v73, 0, v78
	v_mul_f32_e32 v78, v74, v74
	v_max_f32_e32 v74, 0, v79
	v_max_f32_e32 v75, 0, v75
	v_pk_mul_f32 v[64:65], v[64:65], v[82:83] op_sel_hi:[1,0]
	v_lshl_add_u64 v[80:81], v[80:81], 0, v[160:161]
	v_mul_f32_e32 v76, v76, v76
	v_mul_f32_e32 v73, v73, v73
	v_mul_f32_e32 v74, v74, v74
	v_mul_f32_e32 v75, v75, v75
	v_cvt_pk_bf16_f32 v72, v76, v72
	v_pk_mul_f32 v[68:69], v[68:69], v[82:83] op_sel_hi:[1,0]
	v_max_f32_e32 v64, 0, v64
	v_cvt_pk_bf16_f32 v73, v73, v74
	v_cvt_pk_bf16_f32 v74, v83, v77
	v_cvt_pk_bf16_f32 v75, v78, v75
	global_store_dwordx4 v[80:81], v[72:75], off nt
	v_max_f32_e32 v68, 0, v68
	v_mul_f32_e32 v68, v68, v68
	v_mul_f32_e32 v72, v64, v64
	v_max_f32_e32 v64, 0, v69
	v_mul_f32_e32 v64, v64, v64
	v_cvt_pk_bf16_f32 v64, v68, v64
	v_mul_f32_e32 v68, 0x4b800000, v164
	v_cmp_gt_f32_e32 vcc, s54, v164
	v_pk_mul_f32 v[66:67], v[66:67], v[82:83] op_sel_hi:[1,0]
	v_pk_mul_f32 v[70:71], v[70:71], v[82:83] op_sel_hi:[1,0]
	v_cndmask_b32_e32 v68, v164, v68, vcc
	v_max_f32_e32 v65, 0, v65
	v_max_f32_e32 v66, 0, v66
	v_rsq_f32_e32 v68, v68
	v_mul_f32_e32 v69, v65, v65
	v_max_f32_e32 v65, 0, v70
	v_mul_f32_e32 v70, v66, v66
	v_max_f32_e32 v66, 0, v71
	v_mul_f32_e32 v65, v65, v65
	v_max_f32_e32 v67, 0, v67
	v_mul_f32_e32 v66, v66, v66
	v_mul_f32_e32 v67, v67, v67
	v_cvt_pk_bf16_f32 v65, v65, v66
	v_cvt_pk_bf16_f32 v66, v72, v69
	v_cvt_pk_bf16_f32 v67, v70, v67
	global_store_dwordx4 v[80:81], v[64:67], off offset:256 nt
	s_nop 1
	v_mul_f32_e32 v66, 0x45800000, v68
	v_cndmask_b32_e32 v66, v68, v66, vcc
	v_pk_mul_f32 v[56:57], v[56:57], v[66:67] op_sel_hi:[1,0]
	v_pk_mul_f32 v[60:61], v[60:61], v[66:67] op_sel_hi:[1,0]
	v_pk_mul_f32 v[58:59], v[58:59], v[66:67] op_sel_hi:[1,0]
	v_max_f32_e32 v56, 0, v56
	v_pk_mul_f32 v[62:63], v[62:63], v[66:67] op_sel_hi:[1,0]
	v_max_f32_e32 v60, 0, v60
	v_mul_f32_e32 v67, v56, v56
	v_max_f32_e32 v56, 0, v61
	v_max_f32_e32 v57, 0, v57
	v_max_f32_e32 v58, 0, v58
	v_mul_f32_e32 v60, v60, v60
	v_mul_f32_e32 v56, v56, v56
	v_mul_f32_e32 v61, v57, v57
	v_max_f32_e32 v57, 0, v62
	v_mul_f32_e32 v62, v58, v58
	v_max_f32_e32 v58, 0, v63
	v_mul_f32_e32 v57, v57, v57
	v_max_f32_e32 v59, 0, v59
	v_mul_f32_e32 v58, v58, v58
	v_cvt_pk_bf16_f32 v56, v60, v56
	v_add_co_u32_e32 v60, vcc, s55, v144
	v_pk_mul_f32 v[48:49], v[48:49], v[66:67] op_sel_hi:[1,0]
	v_mul_f32_e32 v59, v59, v59
	v_cvt_pk_bf16_f32 v57, v57, v58
	v_cvt_pk_bf16_f32 v58, v67, v61
	v_addc_co_u32_e32 v61, vcc, 0, v145, vcc
	v_pk_mul_f32 v[52:53], v[52:53], v[66:67] op_sel_hi:[1,0]
	v_max_f32_e32 v48, 0, v48
	v_cvt_pk_bf16_f32 v59, v62, v59
	global_store_dwordx4 v[60:61], v[56:59], off nt
	v_max_f32_e32 v52, 0, v52
	v_mul_f32_e32 v52, v52, v52
	v_mul_f32_e32 v56, v48, v48
	v_max_f32_e32 v48, 0, v53
	v_mul_f32_e32 v48, v48, v48
	v_cvt_pk_bf16_f32 v48, v52, v48
	v_mul_f32_e32 v52, 0x4b800000, v165
	v_cmp_gt_f32_e32 vcc, s54, v165
	v_pk_mul_f32 v[50:51], v[50:51], v[66:67] op_sel_hi:[1,0]
	v_pk_mul_f32 v[54:55], v[54:55], v[66:67] op_sel_hi:[1,0]
	v_cndmask_b32_e32 v52, v165, v52, vcc
	v_max_f32_e32 v49, 0, v49
	v_max_f32_e32 v50, 0, v50
	v_rsq_f32_e32 v52, v52
	v_mul_f32_e32 v53, v49, v49
	v_max_f32_e32 v49, 0, v54
	v_mul_f32_e32 v54, v50, v50
	v_max_f32_e32 v50, 0, v55
	v_mul_f32_e32 v49, v49, v49
	v_max_f32_e32 v51, 0, v51
	v_mul_f32_e32 v50, v50, v50
	v_lshl_add_u64 v[64:65], v[144:145], 0, s[12:13]
	v_mul_f32_e32 v51, v51, v51
	v_cvt_pk_bf16_f32 v49, v49, v50
	v_cvt_pk_bf16_f32 v50, v56, v53
	v_cvt_pk_bf16_f32 v51, v54, v51
	global_store_dwordx4 v[64:65], v[48:51], off offset:256 nt
	s_nop 1
	v_mul_f32_e32 v50, 0x45800000, v52
	v_cndmask_b32_e32 v50, v52, v50, vcc
	v_pk_mul_f32 v[40:41], v[40:41], v[50:51] op_sel_hi:[1,0]
	v_pk_mul_f32 v[44:45], v[44:45], v[50:51] op_sel_hi:[1,0]
	v_pk_mul_f32 v[42:43], v[42:43], v[50:51] op_sel_hi:[1,0]
	v_max_f32_e32 v40, 0, v40
	v_pk_mul_f32 v[46:47], v[46:47], v[50:51] op_sel_hi:[1,0]
	v_max_f32_e32 v44, 0, v44
	v_mul_f32_e32 v51, v40, v40
	v_max_f32_e32 v40, 0, v45
	v_max_f32_e32 v41, 0, v41
	v_max_f32_e32 v42, 0, v42
	v_mul_f32_e32 v44, v44, v44
	v_mul_f32_e32 v40, v40, v40
	v_mul_f32_e32 v45, v41, v41
	v_max_f32_e32 v41, 0, v46
	v_mul_f32_e32 v46, v42, v42
	v_max_f32_e32 v42, 0, v47
	v_mul_f32_e32 v41, v41, v41
	v_max_f32_e32 v43, 0, v43
	v_mul_f32_e32 v42, v42, v42
	v_cvt_pk_bf16_f32 v40, v44, v40
	v_add_co_u32_e32 v44, vcc, s56, v144
	v_pk_mul_f32 v[32:33], v[32:33], v[50:51] op_sel_hi:[1,0]
	v_mul_f32_e32 v43, v43, v43
	v_cvt_pk_bf16_f32 v41, v41, v42
	v_cvt_pk_bf16_f32 v42, v51, v45
	v_addc_co_u32_e32 v45, vcc, 0, v145, vcc
	v_pk_mul_f32 v[36:37], v[36:37], v[50:51] op_sel_hi:[1,0]
	v_max_f32_e32 v32, 0, v32
	v_cvt_pk_bf16_f32 v43, v46, v43
	global_store_dwordx4 v[44:45], v[40:43], off nt
	v_max_f32_e32 v36, 0, v36
	v_mul_f32_e32 v36, v36, v36
	v_mul_f32_e32 v40, v32, v32
	v_max_f32_e32 v32, 0, v37
	v_mul_f32_e32 v32, v32, v32
	v_cvt_pk_bf16_f32 v32, v36, v32
	v_mul_f32_e32 v36, 0x4b800000, v166
	v_cmp_gt_f32_e32 vcc, s54, v166
	v_pk_mul_f32 v[34:35], v[34:35], v[50:51] op_sel_hi:[1,0]
	v_pk_mul_f32 v[38:39], v[38:39], v[50:51] op_sel_hi:[1,0]
	v_cndmask_b32_e32 v36, v166, v36, vcc
	v_max_f32_e32 v33, 0, v33
	v_max_f32_e32 v34, 0, v34
	v_rsq_f32_e32 v36, v36
	v_mul_f32_e32 v37, v33, v33
	v_max_f32_e32 v33, 0, v38
	v_mul_f32_e32 v38, v34, v34
	v_max_f32_e32 v34, 0, v39
	v_mul_f32_e32 v33, v33, v33
	v_max_f32_e32 v35, 0, v35
	v_mul_f32_e32 v34, v34, v34
	v_lshl_add_u64 v[48:49], v[144:145], 0, s[14:15]
	v_mul_f32_e32 v35, v35, v35
	v_cvt_pk_bf16_f32 v33, v33, v34
	v_cvt_pk_bf16_f32 v34, v40, v37
	v_cvt_pk_bf16_f32 v35, v38, v35
	global_store_dwordx4 v[48:49], v[32:35], off offset:256 nt
	s_nop 1
	v_mul_f32_e32 v34, 0x45800000, v36
	v_cndmask_b32_e32 v34, v36, v34, vcc
	v_pk_mul_f32 v[24:25], v[24:25], v[34:35] op_sel_hi:[1,0]
	v_pk_mul_f32 v[28:29], v[28:29], v[34:35] op_sel_hi:[1,0]
	v_pk_mul_f32 v[26:27], v[26:27], v[34:35] op_sel_hi:[1,0]
	v_max_f32_e32 v24, 0, v24
	v_pk_mul_f32 v[30:31], v[30:31], v[34:35] op_sel_hi:[1,0]
	v_max_f32_e32 v28, 0, v28
	v_mul_f32_e32 v35, v24, v24
	v_max_f32_e32 v24, 0, v29
	v_max_f32_e32 v25, 0, v25
	v_max_f32_e32 v26, 0, v26
	v_mul_f32_e32 v28, v28, v28
	v_mul_f32_e32 v24, v24, v24
	v_mul_f32_e32 v29, v25, v25
	v_max_f32_e32 v25, 0, v30
	v_mul_f32_e32 v30, v26, v26
	v_max_f32_e32 v26, 0, v31
	v_mul_f32_e32 v25, v25, v25
	v_max_f32_e32 v27, 0, v27
	v_mul_f32_e32 v26, v26, v26
	v_cvt_pk_bf16_f32 v24, v28, v24
	v_add_co_u32_e32 v28, vcc, s57, v144
	v_pk_mul_f32 v[16:17], v[16:17], v[34:35] op_sel_hi:[1,0]
	v_mul_f32_e32 v27, v27, v27
	v_cvt_pk_bf16_f32 v25, v25, v26
	v_cvt_pk_bf16_f32 v26, v35, v29
	v_addc_co_u32_e32 v29, vcc, 0, v145, vcc
	v_pk_mul_f32 v[20:21], v[20:21], v[34:35] op_sel_hi:[1,0]
	v_max_f32_e32 v16, 0, v16
	v_cvt_pk_bf16_f32 v27, v30, v27
	global_store_dwordx4 v[28:29], v[24:27], off nt
	v_max_f32_e32 v20, 0, v20
	v_mul_f32_e32 v20, v20, v20
	v_mul_f32_e32 v24, v16, v16
	v_max_f32_e32 v16, 0, v21
	v_mul_f32_e32 v16, v16, v16
	v_cvt_pk_bf16_f32 v16, v20, v16
	v_mul_f32_e32 v20, 0x4b800000, v147
	v_cmp_gt_f32_e32 vcc, s54, v147
	v_pk_mul_f32 v[18:19], v[18:19], v[34:35] op_sel_hi:[1,0]
	v_pk_mul_f32 v[22:23], v[22:23], v[34:35] op_sel_hi:[1,0]
	v_cndmask_b32_e32 v20, v147, v20, vcc
	v_max_f32_e32 v17, 0, v17
	v_max_f32_e32 v18, 0, v18
	v_rsq_f32_e32 v20, v20
	v_mul_f32_e32 v21, v17, v17
	v_max_f32_e32 v17, 0, v22
	v_mul_f32_e32 v22, v18, v18
	v_max_f32_e32 v18, 0, v23
	v_mul_f32_e32 v17, v17, v17
	v_max_f32_e32 v19, 0, v19
	v_mul_f32_e32 v18, v18, v18
	v_lshl_add_u64 v[32:33], v[144:145], 0, s[16:17]
	v_mul_f32_e32 v19, v19, v19
	v_cvt_pk_bf16_f32 v17, v17, v18
	v_cvt_pk_bf16_f32 v18, v24, v21
	v_cvt_pk_bf16_f32 v19, v22, v19
	global_store_dwordx4 v[32:33], v[16:19], off offset:256 nt
	s_nop 1
	v_mul_f32_e32 v18, 0x45800000, v20
	v_cndmask_b32_e32 v18, v20, v18, vcc
	v_pk_mul_f32 v[8:9], v[8:9], v[18:19] op_sel_hi:[1,0]
	v_pk_mul_f32 v[12:13], v[12:13], v[18:19] op_sel_hi:[1,0]
	v_pk_mul_f32 v[10:11], v[10:11], v[18:19] op_sel_hi:[1,0]
	v_max_f32_e32 v8, 0, v8
	v_pk_mul_f32 v[14:15], v[14:15], v[18:19] op_sel_hi:[1,0]
	v_max_f32_e32 v12, 0, v12
	v_mul_f32_e32 v19, v8, v8
	v_max_f32_e32 v8, 0, v13
	v_max_f32_e32 v9, 0, v9
	v_max_f32_e32 v10, 0, v10
	v_mul_f32_e32 v12, v12, v12
	v_mul_f32_e32 v8, v8, v8
	v_mul_f32_e32 v13, v9, v9
	v_max_f32_e32 v9, 0, v14
	v_mul_f32_e32 v14, v10, v10
	v_max_f32_e32 v10, 0, v15
	v_mul_f32_e32 v9, v9, v9
	v_max_f32_e32 v11, 0, v11
	v_mul_f32_e32 v10, v10, v10
	v_cvt_pk_bf16_f32 v8, v12, v8
	v_add_co_u32_e32 v12, vcc, s58, v144
	v_pk_mul_f32 v[2:3], v[2:3], v[18:19] op_sel_hi:[1,0]
	v_pk_mul_f32 v[0:1], v[0:1], v[18:19] op_sel_hi:[1,0]
	v_mul_f32_e32 v11, v11, v11
	v_cvt_pk_bf16_f32 v9, v9, v10
	v_cvt_pk_bf16_f32 v10, v19, v13
	v_addc_co_u32_e32 v13, vcc, 0, v145, vcc
	v_pk_mul_f32 v[6:7], v[6:7], v[18:19] op_sel_hi:[1,0]
	v_pk_mul_f32 v[4:5], v[4:5], v[18:19] op_sel_hi:[1,0]
	v_max_f32_e32 v0, 0, v0
	v_max_f32_e32 v1, 0, v1
	v_max_f32_e32 v2, 0, v2
	v_cvt_pk_bf16_f32 v11, v14, v11
	global_store_dwordx4 v[12:13], v[8:11], off nt
	v_max_f32_e32 v3, 0, v3
	v_lshl_add_u64 v[16:17], v[144:145], 0, s[18:19]
	v_mul_f32_e32 v8, v0, v0
	v_max_f32_e32 v0, 0, v5
	v_mul_f32_e32 v5, v1, v1
	v_max_f32_e32 v1, 0, v6
	v_mul_f32_e32 v6, v2, v2
	v_max_f32_e32 v2, 0, v7
	v_max_f32_e32 v4, 0, v4
	v_mul_f32_e32 v0, v0, v0
	v_mul_f32_e32 v1, v1, v1
	v_mul_f32_e32 v2, v2, v2
	v_mul_f32_e32 v3, v3, v3
	s_and_b64 vcc, exec, s[2:3]
	v_mul_f32_e32 v4, v4, v4
	v_cvt_pk_bf16_f32 v0, v4, v0
	v_cvt_pk_bf16_f32 v1, v1, v2
	v_cvt_pk_bf16_f32 v2, v8, v5
	v_cvt_pk_bf16_f32 v3, v6, v3
	global_store_dwordx4 v[16:17], v[0:3], off offset:256 nt
	s_cbranch_vccz .LBB0_1211
	s_waitcnt vmcnt(0)
	s_cmpk_gt_u32 s33, 0xff
	s_cbranch_scc1 .LBB0_1222
	s_barrier
